# GEMM K-loop loaders: m0 written ahead of the LDS-DMA address VALU so that VALU supplies the m0->DMA wait state; 90 s_nop 0 removed; on top of v058
# baseline (speedup 1.0000x reference)
.LBB0_311:
	v_add_u32_e32 v164, 0x10000, v143
	v_add_u32_e32 v180, 0x14000, v143
	ds_read_b128 v[138:141], v164
	ds_read_b128 v[156:159], v164 offset:1024
	ds_read_b128 v[160:163], v164 offset:2048
	ds_read_b128 v[164:167], v164 offset:3072
	ds_read_b128 v[168:171], v180
	ds_read_b128 v[172:175], v180 offset:1024
	ds_read_b128 v[176:179], v180 offset:2048
	ds_read_b128 v[204:207], v180 offset:3072
	ds_read_b128 v[208:211], v155
	ds_read_b128 v[212:215], v155 offset:1024
	ds_read_b128 v[216:219], v155 offset:2048
	ds_read_b128 v[220:223], v155 offset:3072
	ds_read_b128 v[224:227], v155 offset:4096
	ds_read_b128 v[228:231], v155 offset:5120
	ds_read_b128 v[232:235], v155 offset:6144
	ds_read_b128 v[236:239], v155 offset:7168
	s_add_u32 s4, s62, 0xfffc0080
	s_addc_u32 s5, s63, -1
	s_add_i32 s84, 0, 0x10000
	s_cmp_eq_u32 s82, 12
	s_cselect_b32 s65, s33, s5
	s_cselect_b32 s64, s36, s4
	s_cselect_b32 s35, s53, s79
	s_cselect_b32 s34, s55, s75
	s_add_i32 s4, 0, 0x14000
	s_add_i32 m0, s68, 0xc000
	v_lshl_add_u64 v[180:181], s[62:63], 0, v[134:135]
	global_load_lds_dwordx4 v[180:181], off
	s_add_i32 m0, s68, 0xe000
	v_lshl_add_u64 v[180:181], s[62:63], 0, v[136:137]
	global_load_lds_dwordx4 v[180:181], off
	s_waitcnt vmcnt(8)
	s_waitcnt lgkmcnt(0)
	s_barrier
	v_mfma_f32_16x16x32_bf16 v[124:127], v[138:141], v[208:211], v[124:127]
	v_mfma_f32_16x16x32_bf16 v[120:123], v[160:163], v[208:211], v[120:123]
	v_mfma_f32_16x16x32_bf16 v[108:111], v[138:141], v[216:219], v[108:111]
	v_mfma_f32_16x16x32_bf16 v[104:107], v[160:163], v[216:219], v[104:107]
	v_mfma_f32_16x16x32_bf16 v[92:95], v[138:141], v[224:227], v[92:95]
	v_mfma_f32_16x16x32_bf16 v[88:91], v[160:163], v[224:227], v[88:91]
	v_mfma_f32_16x16x32_bf16 v[76:79], v[138:141], v[232:235], v[76:79]
	v_mfma_f32_16x16x32_bf16 v[72:75], v[160:163], v[232:235], v[72:75]
	v_mfma_f32_16x16x32_bf16 v[124:127], v[156:159], v[212:215], v[124:127]
	v_mfma_f32_16x16x32_bf16 v[120:123], v[164:167], v[212:215], v[120:123]
	v_mfma_f32_16x16x32_bf16 v[108:111], v[156:159], v[220:223], v[108:111]
	v_mfma_f32_16x16x32_bf16 v[104:107], v[164:167], v[220:223], v[104:107]
	v_mfma_f32_16x16x32_bf16 v[92:95], v[156:159], v[228:231], v[92:95]
	v_mfma_f32_16x16x32_bf16 v[88:91], v[164:167], v[228:231], v[88:91]
	v_mfma_f32_16x16x32_bf16 v[76:79], v[156:159], v[236:239], v[76:79]
	v_mfma_f32_16x16x32_bf16 v[72:75], v[164:167], v[236:239], v[72:75]
	v_mfma_f32_16x16x32_bf16 v[116:119], v[168:171], v[208:211], v[116:119]
	v_mfma_f32_16x16x32_bf16 v[112:115], v[176:179], v[208:211], v[112:115]
	v_mfma_f32_16x16x32_bf16 v[100:103], v[168:171], v[216:219], v[100:103]
	v_mfma_f32_16x16x32_bf16 v[96:99], v[176:179], v[216:219], v[96:99]
	v_mfma_f32_16x16x32_bf16 v[84:87], v[168:171], v[224:227], v[84:87]
	v_mfma_f32_16x16x32_bf16 v[80:83], v[176:179], v[224:227], v[80:83]
	v_mfma_f32_16x16x32_bf16 v[68:71], v[168:171], v[232:235], v[68:71]
	v_mfma_f32_16x16x32_bf16 v[64:67], v[176:179], v[232:235], v[64:67]
	v_mfma_f32_16x16x32_bf16 v[116:119], v[172:175], v[212:215], v[116:119]
	v_mfma_f32_16x16x32_bf16 v[112:115], v[204:207], v[212:215], v[112:115]
	v_mfma_f32_16x16x32_bf16 v[100:103], v[172:175], v[220:223], v[100:103]
	v_mfma_f32_16x16x32_bf16 v[96:99], v[204:207], v[220:223], v[96:99]
	v_mfma_f32_16x16x32_bf16 v[84:87], v[172:175], v[228:231], v[84:87]
	v_mfma_f32_16x16x32_bf16 v[80:83], v[204:207], v[228:231], v[80:83]
	v_mfma_f32_16x16x32_bf16 v[68:71], v[172:175], v[236:239], v[68:71]
	v_mfma_f32_16x16x32_bf16 v[64:67], v[204:207], v[236:239], v[64:67]
	s_barrier
	s_add_i32 s5, s84, s28
	v_lshl_add_u64 v[180:181], s[34:35], 0, v[144:145]
	s_mov_b32 m0, s5
	ds_read_b128 v[208:211], v155 offset:16384
	ds_read_b128 v[212:215], v155 offset:17408
	ds_read_b128 v[216:219], v155 offset:18432
	ds_read_b128 v[220:223], v155 offset:19456
	ds_read_b128 v[224:227], v155 offset:20480
	ds_read_b128 v[228:231], v155 offset:21504
	ds_read_b128 v[232:235], v155 offset:22528
	ds_read_b128 v[236:239], v155 offset:23552
	global_load_lds_dwordx4 v[180:181], off
	s_add_i32 m0, s5, 0x2000
	s_add_u32 s88, s34, 0x40000
	v_lshl_add_u64 v[240:241], s[34:35], 0, v[128:129]
	s_addc_u32 s89, s35, 0
	s_add_i32 s4, s4, s28
	global_load_lds_dwordx4 v[240:241], off
	v_lshl_add_u64 v[242:243], s[88:89], 0, v[144:145]
	s_mov_b32 m0, s4
	v_lshl_add_u64 v[244:245], s[64:65], 0, v[130:131]
	global_load_lds_dwordx4 v[242:243], off
	s_add_i32 m0, s4, 0x2000
	v_lshl_add_u64 v[242:243], s[88:89], 0, v[128:129]
	global_load_lds_dwordx4 v[242:243], off
	s_mov_b32 m0, s68
	v_lshl_add_u64 v[242:243], s[64:65], 0, v[132:133]
	global_load_lds_dwordx4 v[242:243], off
	s_mov_b32 m0, s69
	s_nop 0
	global_load_lds_dwordx4 v[244:245], off
	s_waitcnt vmcnt(8)
	s_waitcnt lgkmcnt(0)
	s_barrier
	v_mfma_f32_16x16x32_bf16 v[60:63], v[138:141], v[208:211], v[60:63]
	v_mfma_f32_16x16x32_bf16 v[56:59], v[160:163], v[208:211], v[56:59]
	v_mfma_f32_16x16x32_bf16 v[44:47], v[138:141], v[216:219], v[44:47]
	v_mfma_f32_16x16x32_bf16 v[40:43], v[160:163], v[216:219], v[40:43]
	v_mfma_f32_16x16x32_bf16 v[28:31], v[138:141], v[224:227], v[28:31]
	v_mfma_f32_16x16x32_bf16 v[24:27], v[160:163], v[224:227], v[24:27]
	v_mfma_f32_16x16x32_bf16 v[12:15], v[138:141], v[232:235], v[12:15]
	v_mfma_f32_16x16x32_bf16 v[8:11], v[160:163], v[232:235], v[8:11]
	v_mfma_f32_16x16x32_bf16 v[60:63], v[156:159], v[212:215], v[60:63]
	v_mfma_f32_16x16x32_bf16 v[56:59], v[164:167], v[212:215], v[56:59]
	v_mfma_f32_16x16x32_bf16 v[44:47], v[156:159], v[220:223], v[44:47]
	v_mfma_f32_16x16x32_bf16 v[40:43], v[164:167], v[220:223], v[40:43]
	v_mfma_f32_16x16x32_bf16 v[28:31], v[156:159], v[228:231], v[28:31]
	v_mfma_f32_16x16x32_bf16 v[24:27], v[164:167], v[228:231], v[24:27]
	v_mfma_f32_16x16x32_bf16 v[12:15], v[156:159], v[236:239], v[12:15]
	v_mfma_f32_16x16x32_bf16 v[8:11], v[164:167], v[236:239], v[8:11]
	v_mfma_f32_16x16x32_bf16 v[52:55], v[168:171], v[208:211], v[52:55]
	v_mfma_f32_16x16x32_bf16 v[48:51], v[176:179], v[208:211], v[48:51]
	v_mfma_f32_16x16x32_bf16 v[36:39], v[168:171], v[216:219], v[36:39]
	v_mfma_f32_16x16x32_bf16 v[32:35], v[176:179], v[216:219], v[32:35]
	v_mfma_f32_16x16x32_bf16 v[20:23], v[168:171], v[224:227], v[20:23]
	v_mfma_f32_16x16x32_bf16 v[16:19], v[176:179], v[224:227], v[16:19]
	v_mfma_f32_16x16x32_bf16 v[4:7], v[168:171], v[232:235], v[4:7]
	v_mfma_f32_16x16x32_bf16 v[0:3], v[176:179], v[232:235], v[0:3]
	v_mfma_f32_16x16x32_bf16 v[52:55], v[172:175], v[212:215], v[52:55]
	v_mfma_f32_16x16x32_bf16 v[48:51], v[204:207], v[212:215], v[48:51]
	v_mfma_f32_16x16x32_bf16 v[36:39], v[172:175], v[220:223], v[36:39]
	v_mfma_f32_16x16x32_bf16 v[32:35], v[204:207], v[220:223], v[32:35]
	v_mfma_f32_16x16x32_bf16 v[20:23], v[172:175], v[228:231], v[20:23]
	v_mfma_f32_16x16x32_bf16 v[16:19], v[204:207], v[228:231], v[16:19]
	v_mfma_f32_16x16x32_bf16 v[4:7], v[172:175], v[236:239], v[4:7]
	v_mfma_f32_16x16x32_bf16 v[0:3], v[204:207], v[236:239], v[0:3]
	s_barrier
	v_add_u32_e32 v164, 0x18000, v143
	v_add_u32_e32 v202, 0x1c000, v143
	ds_read_b128 v[138:141], v164
	ds_read_b128 v[156:159], v164 offset:1024
	ds_read_b128 v[160:163], v164 offset:2048
	ds_read_b128 v[164:167], v164 offset:3072
	ds_read_b128 v[168:171], v202
	ds_read_b128 v[172:175], v202 offset:1024
	ds_read_b128 v[176:179], v202 offset:2048
	ds_read_b128 v[204:207], v202 offset:3072
	ds_read_b128 v[208:211], v155 offset:32768
	ds_read_b128 v[212:215], v155 offset:33792
	ds_read_b128 v[216:219], v155 offset:34816
	ds_read_b128 v[220:223], v155 offset:35840
	ds_read_b128 v[224:227], v155 offset:36864
	ds_read_b128 v[228:231], v155 offset:37888
	ds_read_b128 v[232:235], v155 offset:38912
	ds_read_b128 v[236:239], v155 offset:39936
	s_add_i32 s4, 0, 0x18000
	s_add_i32 s5, 0, 0x1c000
	s_add_u32 s64, s64, 0x40000
	s_addc_u32 s65, s65, 0
	s_mov_b32 m0, s70
	v_lshl_add_u64 v[246:247], s[64:65], 0, v[132:133]
	global_load_lds_dwordx4 v[246:247], off
	s_mov_b32 m0, s71
	v_lshl_add_u64 v[246:247], s[64:65], 0, v[130:131]
	global_load_lds_dwordx4 v[246:247], off
	s_waitcnt vmcnt(8)
	s_waitcnt lgkmcnt(0)
	s_barrier
	v_mfma_f32_16x16x32_bf16 v[124:127], v[138:141], v[208:211], v[124:127]
	v_mfma_f32_16x16x32_bf16 v[120:123], v[160:163], v[208:211], v[120:123]
	v_mfma_f32_16x16x32_bf16 v[108:111], v[138:141], v[216:219], v[108:111]
	v_mfma_f32_16x16x32_bf16 v[104:107], v[160:163], v[216:219], v[104:107]
	v_mfma_f32_16x16x32_bf16 v[92:95], v[138:141], v[224:227], v[92:95]
	v_mfma_f32_16x16x32_bf16 v[88:91], v[160:163], v[224:227], v[88:91]
	v_mfma_f32_16x16x32_bf16 v[76:79], v[138:141], v[232:235], v[76:79]
	v_mfma_f32_16x16x32_bf16 v[72:75], v[160:163], v[232:235], v[72:75]
	v_mfma_f32_16x16x32_bf16 v[124:127], v[156:159], v[212:215], v[124:127]
	v_mfma_f32_16x16x32_bf16 v[120:123], v[164:167], v[212:215], v[120:123]
	v_mfma_f32_16x16x32_bf16 v[108:111], v[156:159], v[220:223], v[108:111]
	v_mfma_f32_16x16x32_bf16 v[104:107], v[164:167], v[220:223], v[104:107]
	v_mfma_f32_16x16x32_bf16 v[92:95], v[156:159], v[228:231], v[92:95]
	v_mfma_f32_16x16x32_bf16 v[88:91], v[164:167], v[228:231], v[88:91]
	v_mfma_f32_16x16x32_bf16 v[76:79], v[156:159], v[236:239], v[76:79]
	v_mfma_f32_16x16x32_bf16 v[72:75], v[164:167], v[236:239], v[72:75]
	v_mfma_f32_16x16x32_bf16 v[116:119], v[168:171], v[208:211], v[116:119]
	v_mfma_f32_16x16x32_bf16 v[112:115], v[176:179], v[208:211], v[112:115]
	v_mfma_f32_16x16x32_bf16 v[100:103], v[168:171], v[216:219], v[100:103]
	v_mfma_f32_16x16x32_bf16 v[96:99], v[176:179], v[216:219], v[96:99]
	v_mfma_f32_16x16x32_bf16 v[84:87], v[168:171], v[224:227], v[84:87]
	v_mfma_f32_16x16x32_bf16 v[80:83], v[176:179], v[224:227], v[80:83]
	v_mfma_f32_16x16x32_bf16 v[68:71], v[168:171], v[232:235], v[68:71]
	v_mfma_f32_16x16x32_bf16 v[64:67], v[176:179], v[232:235], v[64:67]
	v_mfma_f32_16x16x32_bf16 v[116:119], v[172:175], v[212:215], v[116:119]
	v_mfma_f32_16x16x32_bf16 v[112:115], v[204:207], v[212:215], v[112:115]
	v_mfma_f32_16x16x32_bf16 v[100:103], v[172:175], v[220:223], v[100:103]
	v_mfma_f32_16x16x32_bf16 v[96:99], v[204:207], v[220:223], v[96:99]
	v_mfma_f32_16x16x32_bf16 v[84:87], v[172:175], v[228:231], v[84:87]
	v_mfma_f32_16x16x32_bf16 v[80:83], v[204:207], v[228:231], v[80:83]
	v_mfma_f32_16x16x32_bf16 v[68:71], v[172:175], v[236:239], v[68:71]
	v_mfma_f32_16x16x32_bf16 v[64:67], v[204:207], v[236:239], v[64:67]
	s_barrier
	s_add_i32 s4, s4, s28
	v_lshl_add_u64 v[180:181], v[180:181], 0, s[26:27]
	s_mov_b32 m0, s4
	ds_read_b128 v[208:211], v155 offset:49152
	ds_read_b128 v[212:215], v155 offset:50176
	ds_read_b128 v[216:219], v155 offset:51200
	ds_read_b128 v[220:223], v155 offset:52224
	ds_read_b128 v[224:227], v155 offset:53248
	ds_read_b128 v[228:231], v155 offset:54272
	ds_read_b128 v[232:235], v155 offset:55296
	ds_read_b128 v[236:239], v155 offset:56320
	global_load_lds_dwordx4 v[180:181], off
	s_add_i32 m0, s4, 0x2000
	s_add_u32 s34, s34, 0x40080
	v_lshl_add_u64 v[180:181], v[240:241], 0, s[26:27]
	s_addc_u32 s35, s35, 0
	s_add_i32 s4, s5, s28
	global_load_lds_dwordx4 v[180:181], off
	s_mov_b32 m0, s4
	v_lshl_add_u64 v[180:181], s[34:35], 0, v[144:145]
	global_load_lds_dwordx4 v[180:181], off
	s_add_i32 m0, s4, 0x2000
	v_lshl_add_u64 v[180:181], s[34:35], 0, v[128:129]
	global_load_lds_dwordx4 v[180:181], off
	s_mov_b32 m0, s72
	v_lshl_add_u64 v[180:181], v[242:243], 0, s[26:27]
	global_load_lds_dwordx4 v[180:181], off
	s_mov_b32 m0, s73
	v_lshl_add_u64 v[180:181], v[244:245], 0, s[26:27]
	global_load_lds_dwordx4 v[180:181], off
	s_add_i32 s82, s82, 2
	s_add_u32 s62, s62, 0x100
	s_addc_u32 s63, s63, 0
	s_add_u32 s75, s75, 0x100
	s_addc_u32 s79, s79, 0
	s_cmp_gt_u32 s82, 13
	s_waitcnt vmcnt(8)
	s_waitcnt lgkmcnt(0)
	s_barrier
	v_mfma_f32_16x16x32_bf16 v[60:63], v[138:141], v[208:211], v[60:63]
	v_mfma_f32_16x16x32_bf16 v[56:59], v[160:163], v[208:211], v[56:59]
	v_mfma_f32_16x16x32_bf16 v[44:47], v[138:141], v[216:219], v[44:47]
	v_mfma_f32_16x16x32_bf16 v[40:43], v[160:163], v[216:219], v[40:43]
	v_mfma_f32_16x16x32_bf16 v[28:31], v[138:141], v[224:227], v[28:31]
	v_mfma_f32_16x16x32_bf16 v[24:27], v[160:163], v[224:227], v[24:27]
	v_mfma_f32_16x16x32_bf16 v[12:15], v[138:141], v[232:235], v[12:15]
	v_mfma_f32_16x16x32_bf16 v[8:11], v[160:163], v[232:235], v[8:11]
	v_mfma_f32_16x16x32_bf16 v[60:63], v[156:159], v[212:215], v[60:63]
	v_mfma_f32_16x16x32_bf16 v[56:59], v[164:167], v[212:215], v[56:59]
	v_mfma_f32_16x16x32_bf16 v[44:47], v[156:159], v[220:223], v[44:47]
	v_mfma_f32_16x16x32_bf16 v[40:43], v[164:167], v[220:223], v[40:43]
	v_mfma_f32_16x16x32_bf16 v[28:31], v[156:159], v[228:231], v[28:31]
	v_mfma_f32_16x16x32_bf16 v[24:27], v[164:167], v[228:231], v[24:27]
	v_mfma_f32_16x16x32_bf16 v[12:15], v[156:159], v[236:239], v[12:15]
	v_mfma_f32_16x16x32_bf16 v[8:11], v[164:167], v[236:239], v[8:11]
	v_mfma_f32_16x16x32_bf16 v[52:55], v[168:171], v[208:211], v[52:55]
	v_mfma_f32_16x16x32_bf16 v[48:51], v[176:179], v[208:211], v[48:51]
	v_mfma_f32_16x16x32_bf16 v[36:39], v[168:171], v[216:219], v[36:39]
	v_mfma_f32_16x16x32_bf16 v[32:35], v[176:179], v[216:219], v[32:35]
	v_mfma_f32_16x16x32_bf16 v[20:23], v[168:171], v[224:227], v[20:23]
	v_mfma_f32_16x16x32_bf16 v[16:19], v[176:179], v[224:227], v[16:19]
	v_mfma_f32_16x16x32_bf16 v[4:7], v[168:171], v[232:235], v[4:7]
	v_mfma_f32_16x16x32_bf16 v[0:3], v[176:179], v[232:235], v[0:3]
	v_mfma_f32_16x16x32_bf16 v[52:55], v[172:175], v[212:215], v[52:55]
	v_mfma_f32_16x16x32_bf16 v[48:51], v[204:207], v[212:215], v[48:51]
	v_mfma_f32_16x16x32_bf16 v[36:39], v[172:175], v[220:223], v[36:39]
	v_mfma_f32_16x16x32_bf16 v[32:35], v[204:207], v[220:223], v[32:35]
	v_mfma_f32_16x16x32_bf16 v[20:23], v[172:175], v[228:231], v[20:23]
	v_mfma_f32_16x16x32_bf16 v[16:19], v[204:207], v[228:231], v[16:19]
	v_mfma_f32_16x16x32_bf16 v[4:7], v[172:175], v[236:239], v[4:7]
	v_mfma_f32_16x16x32_bf16 v[0:3], v[204:207], v[236:239], v[0:3]
	s_barrier
	s_cbranch_scc0 .LBB0_311
	v_lshl_add_u32 v140, s2, 8, v142
	v_ashrrev_i32_e32 v141, 31, v140
	v_lshl_add_u64 v[156:157], v[140:141], 4, s[48:49]
	global_load_dwordx4 v[208:211], v[156:157], off
	global_load_dwordx4 v[212:215], v[156:157], off offset:256
	global_load_dwordx4 v[216:219], v[156:157], off offset:512
	global_load_dwordx4 v[220:223], v[156:157], off offset:768
	global_load_dwordx4 v[224:227], v[156:157], off offset:2048
	global_load_dwordx4 v[228:231], v[156:157], off offset:2304
	global_load_dwordx4 v[232:235], v[156:157], off offset:2560
	global_load_dwordx4 v[236:239], v[156:157], off offset:2816
	s_and_b64 vcc, exec, s[50:51]
	s_cbranch_vccz .LBB0_314
	s_barrier

.LBB0_406:
	v_add_u32_e32 v142, 0x10000, v160
	ds_read_b128 v[138:141], v142
	ds_read_b128 v[154:157], v142 offset:1024
	ds_read_b128 v[172:175], v142 offset:2048
	ds_read_b128 v[176:179], v142 offset:3072
	v_add_u32_e32 v142, 0x14000, v160
	ds_read_b128 v[204:207], v142
	ds_read_b128 v[208:211], v142 offset:1024
	ds_read_b128 v[212:215], v142 offset:2048
	ds_read_b128 v[216:219], v142 offset:3072
	ds_read_b128 v[220:223], v170
	ds_read_b128 v[224:227], v170 offset:1024
	ds_read_b128 v[228:231], v170 offset:2048
	ds_read_b128 v[232:235], v170 offset:3072
	ds_read_b128 v[236:239], v170 offset:4096
	ds_read_b128 v[240:243], v170 offset:5120
	ds_read_b128 v[244:247], v170 offset:6144
	ds_read_b128 v[248:251], v170 offset:7168
	s_add_u32 s62, s60, 0x100
	s_addc_u32 s63, s61, 0
	s_add_i32 s4, 0, 0x10000
	s_cmp_eq_u32 s29, 40
	s_cselect_b32 s65, s45, s63
	s_cselect_b32 s64, s44, s62
	s_cselect_b32 s35, s59, s28
	s_cselect_b32 s34, s58, s3
	s_add_i32 s5, 0, 0x14000
	s_add_i32 m0, s36, 0xc000
	v_lshl_add_u64 v[142:143], s[60:61], 0, v[134:135]
	global_load_lds_dwordx4 v[142:143], off
	s_add_i32 m0, s36, 0xe000
	v_lshl_add_u64 v[142:143], s[60:61], 0, v[136:137]
	global_load_lds_dwordx4 v[142:143], off
	s_waitcnt vmcnt(8)
	s_waitcnt lgkmcnt(0)
	s_barrier
	v_mfma_f32_16x16x32_bf16 v[124:127], v[138:141], v[220:223], v[124:127]
	v_mfma_f32_16x16x32_bf16 v[120:123], v[172:175], v[220:223], v[120:123]
	v_mfma_f32_16x16x32_bf16 v[108:111], v[138:141], v[228:231], v[108:111]
	v_mfma_f32_16x16x32_bf16 v[104:107], v[172:175], v[228:231], v[104:107]
	v_mfma_f32_16x16x32_bf16 v[92:95], v[138:141], v[236:239], v[92:95]
	v_mfma_f32_16x16x32_bf16 v[88:91], v[172:175], v[236:239], v[88:91]
	v_mfma_f32_16x16x32_bf16 v[76:79], v[138:141], v[244:247], v[76:79]
	v_mfma_f32_16x16x32_bf16 v[72:75], v[172:175], v[244:247], v[72:75]
	v_mfma_f32_16x16x32_bf16 v[124:127], v[154:157], v[224:227], v[124:127]
	v_mfma_f32_16x16x32_bf16 v[120:123], v[176:179], v[224:227], v[120:123]
	v_mfma_f32_16x16x32_bf16 v[108:111], v[154:157], v[232:235], v[108:111]
	v_mfma_f32_16x16x32_bf16 v[104:107], v[176:179], v[232:235], v[104:107]
	v_mfma_f32_16x16x32_bf16 v[92:95], v[154:157], v[240:243], v[92:95]
	v_mfma_f32_16x16x32_bf16 v[88:91], v[176:179], v[240:243], v[88:91]
	v_mfma_f32_16x16x32_bf16 v[76:79], v[154:157], v[248:251], v[76:79]
	v_mfma_f32_16x16x32_bf16 v[72:75], v[176:179], v[248:251], v[72:75]
	v_mfma_f32_16x16x32_bf16 v[116:119], v[204:207], v[220:223], v[116:119]
	v_mfma_f32_16x16x32_bf16 v[112:115], v[212:215], v[220:223], v[112:115]
	v_mfma_f32_16x16x32_bf16 v[100:103], v[204:207], v[228:231], v[100:103]
	v_mfma_f32_16x16x32_bf16 v[96:99], v[212:215], v[228:231], v[96:99]
	v_mfma_f32_16x16x32_bf16 v[84:87], v[204:207], v[236:239], v[84:87]
	v_mfma_f32_16x16x32_bf16 v[80:83], v[212:215], v[236:239], v[80:83]
	v_mfma_f32_16x16x32_bf16 v[68:71], v[204:207], v[244:247], v[68:71]
	v_mfma_f32_16x16x32_bf16 v[64:67], v[212:215], v[244:247], v[64:67]
	v_mfma_f32_16x16x32_bf16 v[116:119], v[208:211], v[224:227], v[116:119]
	v_mfma_f32_16x16x32_bf16 v[112:115], v[216:219], v[224:227], v[112:115]
	v_mfma_f32_16x16x32_bf16 v[100:103], v[208:211], v[232:235], v[100:103]
	v_mfma_f32_16x16x32_bf16 v[96:99], v[216:219], v[232:235], v[96:99]
	v_mfma_f32_16x16x32_bf16 v[84:87], v[208:211], v[240:243], v[84:87]
	v_mfma_f32_16x16x32_bf16 v[80:83], v[216:219], v[240:243], v[80:83]
	v_mfma_f32_16x16x32_bf16 v[68:71], v[208:211], v[248:251], v[68:71]
	v_mfma_f32_16x16x32_bf16 v[64:67], v[216:219], v[248:251], v[64:67]
	s_barrier
	s_add_i32 s4, s4, s33
	v_lshl_add_u64 v[142:143], s[34:35], 0, v[128:129]
	s_mov_b32 m0, s4
	ds_read_b128 v[220:223], v170 offset:16384
	ds_read_b128 v[224:227], v170 offset:17408
	ds_read_b128 v[228:231], v170 offset:18432
	ds_read_b128 v[232:235], v170 offset:19456
	ds_read_b128 v[236:239], v170 offset:20480
	ds_read_b128 v[240:243], v170 offset:21504
	ds_read_b128 v[244:247], v170 offset:22528
	ds_read_b128 v[248:251], v170 offset:23552
	global_load_lds_dwordx4 v[142:143], off
	s_add_i32 m0, s4, 0x2000
	s_add_u32 s60, s34, 0xb0000
	v_lshl_add_u64 v[158:159], s[34:35], 0, v[130:131]
	s_addc_u32 s61, s35, 0
	s_add_i32 s4, s5, s33
	global_load_lds_dwordx4 v[158:159], off
	v_lshl_add_u64 v[180:181], s[60:61], 0, v[128:129]
	s_mov_b32 m0, s4
	v_lshl_add_u64 v[202:203], s[64:65], 0, v[130:131]
	global_load_lds_dwordx4 v[180:181], off
	s_add_i32 m0, s4, 0x2000
	v_lshl_add_u64 v[180:181], s[60:61], 0, v[130:131]
	global_load_lds_dwordx4 v[180:181], off
	s_mov_b32 m0, s36
	v_lshl_add_u64 v[180:181], s[64:65], 0, v[128:129]
	global_load_lds_dwordx4 v[180:181], off
	s_mov_b32 m0, s70
	s_nop 0
	global_load_lds_dwordx4 v[202:203], off
	s_waitcnt vmcnt(8)
	s_waitcnt lgkmcnt(0)
	s_barrier
	v_mfma_f32_16x16x32_bf16 v[60:63], v[138:141], v[220:223], v[60:63]
	v_mfma_f32_16x16x32_bf16 v[56:59], v[172:175], v[220:223], v[56:59]
	v_mfma_f32_16x16x32_bf16 v[44:47], v[138:141], v[228:231], v[44:47]
	v_mfma_f32_16x16x32_bf16 v[40:43], v[172:175], v[228:231], v[40:43]
	v_mfma_f32_16x16x32_bf16 v[28:31], v[138:141], v[236:239], v[28:31]
	v_mfma_f32_16x16x32_bf16 v[24:27], v[172:175], v[236:239], v[24:27]
	v_mfma_f32_16x16x32_bf16 v[12:15], v[138:141], v[244:247], v[12:15]
	v_mfma_f32_16x16x32_bf16 v[8:11], v[172:175], v[244:247], v[8:11]
	v_mfma_f32_16x16x32_bf16 v[60:63], v[154:157], v[224:227], v[60:63]
	v_mfma_f32_16x16x32_bf16 v[56:59], v[176:179], v[224:227], v[56:59]
	v_mfma_f32_16x16x32_bf16 v[44:47], v[154:157], v[232:235], v[44:47]
	v_mfma_f32_16x16x32_bf16 v[40:43], v[176:179], v[232:235], v[40:43]
	v_mfma_f32_16x16x32_bf16 v[28:31], v[154:157], v[240:243], v[28:31]
	v_mfma_f32_16x16x32_bf16 v[24:27], v[176:179], v[240:243], v[24:27]
	v_mfma_f32_16x16x32_bf16 v[12:15], v[154:157], v[248:251], v[12:15]
	v_mfma_f32_16x16x32_bf16 v[8:11], v[176:179], v[248:251], v[8:11]
	v_mfma_f32_16x16x32_bf16 v[52:55], v[204:207], v[220:223], v[52:55]
	v_mfma_f32_16x16x32_bf16 v[48:51], v[212:215], v[220:223], v[48:51]
	v_mfma_f32_16x16x32_bf16 v[36:39], v[204:207], v[228:231], v[36:39]
	v_mfma_f32_16x16x32_bf16 v[32:35], v[212:215], v[228:231], v[32:35]
	v_mfma_f32_16x16x32_bf16 v[20:23], v[204:207], v[236:239], v[20:23]
	v_mfma_f32_16x16x32_bf16 v[16:19], v[212:215], v[236:239], v[16:19]
	v_mfma_f32_16x16x32_bf16 v[4:7], v[204:207], v[244:247], v[4:7]
	v_mfma_f32_16x16x32_bf16 v[0:3], v[212:215], v[244:247], v[0:3]
	v_mfma_f32_16x16x32_bf16 v[52:55], v[208:211], v[224:227], v[52:55]
	v_mfma_f32_16x16x32_bf16 v[48:51], v[216:219], v[224:227], v[48:51]
	v_mfma_f32_16x16x32_bf16 v[36:39], v[208:211], v[232:235], v[36:39]
	v_mfma_f32_16x16x32_bf16 v[32:35], v[216:219], v[232:235], v[32:35]
	v_mfma_f32_16x16x32_bf16 v[20:23], v[208:211], v[240:243], v[20:23]
	v_mfma_f32_16x16x32_bf16 v[16:19], v[216:219], v[240:243], v[16:19]
	v_mfma_f32_16x16x32_bf16 v[4:7], v[208:211], v[248:251], v[4:7]
	v_mfma_f32_16x16x32_bf16 v[0:3], v[216:219], v[248:251], v[0:3]
	s_barrier
	v_add_u32_e32 v144, 0x18000, v160
	ds_read_b128 v[138:141], v144
	ds_read_b128 v[154:157], v144 offset:1024
	ds_read_b128 v[172:175], v144 offset:2048
	ds_read_b128 v[176:179], v144 offset:3072
	v_add_u32_e32 v144, 0x1c000, v160
	ds_read_b128 v[204:207], v144
	ds_read_b128 v[208:211], v144 offset:1024
	ds_read_b128 v[212:215], v144 offset:2048
	ds_read_b128 v[216:219], v144 offset:3072
	ds_read_b128 v[220:223], v170 offset:32768
	ds_read_b128 v[224:227], v170 offset:33792
	ds_read_b128 v[228:231], v170 offset:34816
	ds_read_b128 v[232:235], v170 offset:35840
	ds_read_b128 v[236:239], v170 offset:36864
	ds_read_b128 v[240:243], v170 offset:37888
	ds_read_b128 v[244:247], v170 offset:38912
	ds_read_b128 v[248:251], v170 offset:39936
	s_add_i32 s4, 0, 0x18000
	s_add_i32 s5, 0, 0x1c000
	s_add_u32 s60, s64, 0xb0000
	s_addc_u32 s61, s65, 0
	s_mov_b32 m0, s71
	v_lshl_add_u64 v[252:253], s[60:61], 0, v[128:129]
	global_load_lds_dwordx4 v[252:253], off
	s_mov_b32 m0, s72
	v_lshl_add_u64 v[252:253], s[60:61], 0, v[130:131]
	global_load_lds_dwordx4 v[252:253], off
	s_waitcnt vmcnt(8)
	s_waitcnt lgkmcnt(0)
	s_barrier
	v_mfma_f32_16x16x32_bf16 v[124:127], v[138:141], v[220:223], v[124:127]
	v_mfma_f32_16x16x32_bf16 v[120:123], v[172:175], v[220:223], v[120:123]
	v_mfma_f32_16x16x32_bf16 v[108:111], v[138:141], v[228:231], v[108:111]
	v_mfma_f32_16x16x32_bf16 v[104:107], v[172:175], v[228:231], v[104:107]
	v_mfma_f32_16x16x32_bf16 v[92:95], v[138:141], v[236:239], v[92:95]
	v_mfma_f32_16x16x32_bf16 v[88:91], v[172:175], v[236:239], v[88:91]
	v_mfma_f32_16x16x32_bf16 v[76:79], v[138:141], v[244:247], v[76:79]
	v_mfma_f32_16x16x32_bf16 v[72:75], v[172:175], v[244:247], v[72:75]
	v_mfma_f32_16x16x32_bf16 v[124:127], v[154:157], v[224:227], v[124:127]
	v_mfma_f32_16x16x32_bf16 v[120:123], v[176:179], v[224:227], v[120:123]
	v_mfma_f32_16x16x32_bf16 v[108:111], v[154:157], v[232:235], v[108:111]
	v_mfma_f32_16x16x32_bf16 v[104:107], v[176:179], v[232:235], v[104:107]
	v_mfma_f32_16x16x32_bf16 v[92:95], v[154:157], v[240:243], v[92:95]
	v_mfma_f32_16x16x32_bf16 v[88:91], v[176:179], v[240:243], v[88:91]
	v_mfma_f32_16x16x32_bf16 v[76:79], v[154:157], v[248:251], v[76:79]
	v_mfma_f32_16x16x32_bf16 v[72:75], v[176:179], v[248:251], v[72:75]
	v_mfma_f32_16x16x32_bf16 v[116:119], v[204:207], v[220:223], v[116:119]
	v_mfma_f32_16x16x32_bf16 v[112:115], v[212:215], v[220:223], v[112:115]
	v_mfma_f32_16x16x32_bf16 v[100:103], v[204:207], v[228:231], v[100:103]
	v_mfma_f32_16x16x32_bf16 v[96:99], v[212:215], v[228:231], v[96:99]
	v_mfma_f32_16x16x32_bf16 v[84:87], v[204:207], v[236:239], v[84:87]
	v_mfma_f32_16x16x32_bf16 v[80:83], v[212:215], v[236:239], v[80:83]
	v_mfma_f32_16x16x32_bf16 v[68:71], v[204:207], v[244:247], v[68:71]
	v_mfma_f32_16x16x32_bf16 v[64:67], v[212:215], v[244:247], v[64:67]
	v_mfma_f32_16x16x32_bf16 v[116:119], v[208:211], v[224:227], v[116:119]
	v_mfma_f32_16x16x32_bf16 v[112:115], v[216:219], v[224:227], v[112:115]
	v_mfma_f32_16x16x32_bf16 v[100:103], v[208:211], v[232:235], v[100:103]
	v_mfma_f32_16x16x32_bf16 v[96:99], v[216:219], v[232:235], v[96:99]
	v_mfma_f32_16x16x32_bf16 v[84:87], v[208:211], v[240:243], v[84:87]
	v_mfma_f32_16x16x32_bf16 v[80:83], v[216:219], v[240:243], v[80:83]
	v_mfma_f32_16x16x32_bf16 v[68:71], v[208:211], v[248:251], v[68:71]
	v_mfma_f32_16x16x32_bf16 v[64:67], v[216:219], v[248:251], v[64:67]
	s_barrier
	s_add_i32 s4, s4, s33
	v_lshl_add_u64 v[142:143], v[142:143], 0, s[26:27]
	s_mov_b32 m0, s4
	ds_read_b128 v[220:223], v170 offset:49152
	ds_read_b128 v[224:227], v170 offset:50176
	ds_read_b128 v[228:231], v170 offset:51200
	ds_read_b128 v[232:235], v170 offset:52224
	ds_read_b128 v[236:239], v170 offset:53248
	ds_read_b128 v[240:243], v170 offset:54272
	ds_read_b128 v[244:247], v170 offset:55296
	ds_read_b128 v[248:251], v170 offset:56320
	global_load_lds_dwordx4 v[142:143], off
	s_add_i32 m0, s4, 0x2000
	s_add_u32 s34, s34, 0xb0080
	v_lshl_add_u64 v[142:143], v[158:159], 0, s[26:27]
	s_addc_u32 s35, s35, 0
	s_add_i32 s4, s5, s33
	global_load_lds_dwordx4 v[142:143], off
	s_mov_b32 m0, s4
	v_lshl_add_u64 v[142:143], s[34:35], 0, v[128:129]
	global_load_lds_dwordx4 v[142:143], off
	s_add_i32 m0, s4, 0x2000
	v_lshl_add_u64 v[142:143], s[34:35], 0, v[130:131]
	global_load_lds_dwordx4 v[142:143], off
	s_mov_b32 m0, s73
	v_lshl_add_u64 v[142:143], v[180:181], 0, s[26:27]
	global_load_lds_dwordx4 v[142:143], off
	s_mov_b32 m0, s74
	v_lshl_add_u64 v[142:143], v[202:203], 0, s[26:27]
	global_load_lds_dwordx4 v[142:143], off
	s_add_i32 s29, s29, 2
	s_add_u32 s3, s3, 0x100
	s_addc_u32 s28, s28, 0
	s_cmp_gt_u32 s29, 41
	s_mov_b64 s[60:61], s[62:63]
	s_waitcnt vmcnt(8)
	s_waitcnt lgkmcnt(0)
	s_barrier
	v_mfma_f32_16x16x32_bf16 v[60:63], v[138:141], v[220:223], v[60:63]
	v_mfma_f32_16x16x32_bf16 v[56:59], v[172:175], v[220:223], v[56:59]
	v_mfma_f32_16x16x32_bf16 v[44:47], v[138:141], v[228:231], v[44:47]
	v_mfma_f32_16x16x32_bf16 v[40:43], v[172:175], v[228:231], v[40:43]
	v_mfma_f32_16x16x32_bf16 v[28:31], v[138:141], v[236:239], v[28:31]
	v_mfma_f32_16x16x32_bf16 v[24:27], v[172:175], v[236:239], v[24:27]
	v_mfma_f32_16x16x32_bf16 v[12:15], v[138:141], v[244:247], v[12:15]
	v_mfma_f32_16x16x32_bf16 v[8:11], v[172:175], v[244:247], v[8:11]
	v_mfma_f32_16x16x32_bf16 v[60:63], v[154:157], v[224:227], v[60:63]
	v_mfma_f32_16x16x32_bf16 v[56:59], v[176:179], v[224:227], v[56:59]
	v_mfma_f32_16x16x32_bf16 v[44:47], v[154:157], v[232:235], v[44:47]
	v_mfma_f32_16x16x32_bf16 v[40:43], v[176:179], v[232:235], v[40:43]
	v_mfma_f32_16x16x32_bf16 v[28:31], v[154:157], v[240:243], v[28:31]
	v_mfma_f32_16x16x32_bf16 v[24:27], v[176:179], v[240:243], v[24:27]
	v_mfma_f32_16x16x32_bf16 v[12:15], v[154:157], v[248:251], v[12:15]
	v_mfma_f32_16x16x32_bf16 v[8:11], v[176:179], v[248:251], v[8:11]
	v_mfma_f32_16x16x32_bf16 v[52:55], v[204:207], v[220:223], v[52:55]
	v_mfma_f32_16x16x32_bf16 v[48:51], v[212:215], v[220:223], v[48:51]
	v_mfma_f32_16x16x32_bf16 v[36:39], v[204:207], v[228:231], v[36:39]
	v_mfma_f32_16x16x32_bf16 v[32:35], v[212:215], v[228:231], v[32:35]
	v_mfma_f32_16x16x32_bf16 v[20:23], v[204:207], v[236:239], v[20:23]
	v_mfma_f32_16x16x32_bf16 v[16:19], v[212:215], v[236:239], v[16:19]
	v_mfma_f32_16x16x32_bf16 v[4:7], v[204:207], v[244:247], v[4:7]
	v_mfma_f32_16x16x32_bf16 v[0:3], v[212:215], v[244:247], v[0:3]
	v_mfma_f32_16x16x32_bf16 v[52:55], v[208:211], v[224:227], v[52:55]
	v_mfma_f32_16x16x32_bf16 v[48:51], v[216:219], v[224:227], v[48:51]
	v_mfma_f32_16x16x32_bf16 v[36:39], v[208:211], v[232:235], v[36:39]
	v_mfma_f32_16x16x32_bf16 v[32:35], v[216:219], v[232:235], v[32:35]
	v_mfma_f32_16x16x32_bf16 v[20:23], v[208:211], v[240:243], v[20:23]
	v_mfma_f32_16x16x32_bf16 v[16:19], v[216:219], v[240:243], v[16:19]
	v_mfma_f32_16x16x32_bf16 v[4:7], v[208:211], v[248:251], v[4:7]
	v_mfma_f32_16x16x32_bf16 v[0:3], v[216:219], v[248:251], v[0:3]
	s_barrier
	s_cbranch_scc0 .LBB0_406
	s_and_b64 vcc, exec, s[54:55]
	s_cbranch_vccz .LBB0_409
	s_barrier

.LBB0_456:
	v_add_u32_e32 v140, 0x10000, v166
	v_add_u32_e32 v144, 0x14000, v166
	ds_read_b128 v[128:131], v140
	ds_read_b128 v[132:135], v140 offset:1024
	ds_read_b128 v[136:139], v140 offset:2048
	ds_read_b128 v[140:143], v140 offset:3072
	ds_read_b128 v[178:181], v144
	ds_read_b128 v[204:207], v144 offset:1024
	ds_read_b128 v[208:211], v144 offset:2048
	ds_read_b128 v[212:215], v144 offset:3072
	ds_read_b128 v[216:219], v176
	ds_read_b128 v[220:223], v176 offset:1024
	ds_read_b128 v[224:227], v176 offset:2048
	ds_read_b128 v[228:231], v176 offset:3072
	ds_read_b128 v[232:235], v176 offset:4096
	ds_read_b128 v[236:239], v176 offset:5120
	ds_read_b128 v[240:243], v176 offset:6144
	ds_read_b128 v[244:247], v176 offset:7168
	s_add_u32 s60, s58, 0x100
	s_addc_u32 s61, s59, 0
	s_add_i32 s4, 0, 0x10000
	s_cmp_eq_u32 s51, 40
	s_cselect_b32 s63, s45, s61
	s_cselect_b32 s62, s44, s60
	s_cselect_b32 s35, s47, s29
	s_cselect_b32 s34, s46, s28
	s_add_i32 s5, 0, 0x14000
	s_add_i32 m0, s36, 0xc000
	v_lshl_add_u64 v[164:165], s[58:59], 0, v[160:161]
	global_load_lds_dwordx4 v[164:165], off
	s_add_i32 m0, s36, 0xe000
	v_lshl_add_u64 v[164:165], s[58:59], 0, v[162:163]
	global_load_lds_dwordx4 v[164:165], off
	s_waitcnt vmcnt(8)
	s_waitcnt lgkmcnt(0)
	s_barrier
	v_mfma_f32_16x16x32_bf16 v[124:127], v[128:131], v[216:219], v[124:127]
	v_mfma_f32_16x16x32_bf16 v[120:123], v[136:139], v[216:219], v[120:123]
	v_mfma_f32_16x16x32_bf16 v[108:111], v[128:131], v[224:227], v[108:111]
	v_mfma_f32_16x16x32_bf16 v[104:107], v[136:139], v[224:227], v[104:107]
	v_mfma_f32_16x16x32_bf16 v[92:95], v[128:131], v[232:235], v[92:95]
	v_mfma_f32_16x16x32_bf16 v[88:91], v[136:139], v[232:235], v[88:91]
	v_mfma_f32_16x16x32_bf16 v[76:79], v[128:131], v[240:243], v[76:79]
	v_mfma_f32_16x16x32_bf16 v[72:75], v[136:139], v[240:243], v[72:75]
	v_mfma_f32_16x16x32_bf16 v[124:127], v[132:135], v[220:223], v[124:127]
	v_mfma_f32_16x16x32_bf16 v[120:123], v[140:143], v[220:223], v[120:123]
	v_mfma_f32_16x16x32_bf16 v[108:111], v[132:135], v[228:231], v[108:111]
	v_mfma_f32_16x16x32_bf16 v[104:107], v[140:143], v[228:231], v[104:107]
	v_mfma_f32_16x16x32_bf16 v[92:95], v[132:135], v[236:239], v[92:95]
	v_mfma_f32_16x16x32_bf16 v[88:91], v[140:143], v[236:239], v[88:91]
	v_mfma_f32_16x16x32_bf16 v[76:79], v[132:135], v[244:247], v[76:79]
	v_mfma_f32_16x16x32_bf16 v[72:75], v[140:143], v[244:247], v[72:75]
	v_mfma_f32_16x16x32_bf16 v[116:119], v[178:181], v[216:219], v[116:119]
	v_mfma_f32_16x16x32_bf16 v[112:115], v[208:211], v[216:219], v[112:115]
	v_mfma_f32_16x16x32_bf16 v[100:103], v[178:181], v[224:227], v[100:103]
	v_mfma_f32_16x16x32_bf16 v[96:99], v[208:211], v[224:227], v[96:99]
	v_mfma_f32_16x16x32_bf16 v[84:87], v[178:181], v[232:235], v[84:87]
	v_mfma_f32_16x16x32_bf16 v[80:83], v[208:211], v[232:235], v[80:83]
	v_mfma_f32_16x16x32_bf16 v[68:71], v[178:181], v[240:243], v[68:71]
	v_mfma_f32_16x16x32_bf16 v[64:67], v[208:211], v[240:243], v[64:67]
	v_mfma_f32_16x16x32_bf16 v[116:119], v[204:207], v[220:223], v[116:119]
	v_mfma_f32_16x16x32_bf16 v[112:115], v[212:215], v[220:223], v[112:115]
	v_mfma_f32_16x16x32_bf16 v[100:103], v[204:207], v[228:231], v[100:103]
	v_mfma_f32_16x16x32_bf16 v[96:99], v[212:215], v[228:231], v[96:99]
	v_mfma_f32_16x16x32_bf16 v[84:87], v[204:207], v[236:239], v[84:87]
	v_mfma_f32_16x16x32_bf16 v[80:83], v[212:215], v[236:239], v[80:83]
	v_mfma_f32_16x16x32_bf16 v[68:71], v[204:207], v[244:247], v[68:71]
	v_mfma_f32_16x16x32_bf16 v[64:67], v[212:215], v[244:247], v[64:67]
	s_barrier
	s_add_i32 s4, s4, s33
	v_lshl_add_u64 v[164:165], s[34:35], 0, v[154:155]
	s_mov_b32 m0, s4
	ds_read_b128 v[216:219], v176 offset:16384
	ds_read_b128 v[220:223], v176 offset:17408
	ds_read_b128 v[224:227], v176 offset:18432
	ds_read_b128 v[228:231], v176 offset:19456
	ds_read_b128 v[232:235], v176 offset:20480
	ds_read_b128 v[236:239], v176 offset:21504
	ds_read_b128 v[240:243], v176 offset:22528
	ds_read_b128 v[244:247], v176 offset:23552
	global_load_lds_dwordx4 v[164:165], off
	s_add_i32 m0, s4, 0x2000
	s_add_u32 s58, s34, 0xb0000
	v_lshl_add_u64 v[248:249], s[34:35], 0, v[156:157]
	s_addc_u32 s59, s35, 0
	s_add_i32 s4, s5, s33
	global_load_lds_dwordx4 v[248:249], off
	v_lshl_add_u64 v[250:251], s[58:59], 0, v[154:155]
	s_mov_b32 m0, s4
	v_lshl_add_u64 v[252:253], s[62:63], 0, v[156:157]
	global_load_lds_dwordx4 v[250:251], off
	s_add_i32 m0, s4, 0x2000
	v_lshl_add_u64 v[250:251], s[58:59], 0, v[156:157]
	global_load_lds_dwordx4 v[250:251], off
	s_mov_b32 m0, s36
	v_lshl_add_u64 v[250:251], s[62:63], 0, v[154:155]
	global_load_lds_dwordx4 v[250:251], off
	s_mov_b32 m0, s64
	s_nop 0
	global_load_lds_dwordx4 v[252:253], off
	s_waitcnt vmcnt(8)
	s_waitcnt lgkmcnt(0)
	s_barrier
	v_mfma_f32_16x16x32_bf16 v[60:63], v[128:131], v[216:219], v[60:63]
	v_mfma_f32_16x16x32_bf16 v[56:59], v[136:139], v[216:219], v[56:59]
	v_mfma_f32_16x16x32_bf16 v[44:47], v[128:131], v[224:227], v[44:47]
	v_mfma_f32_16x16x32_bf16 v[40:43], v[136:139], v[224:227], v[40:43]
	v_mfma_f32_16x16x32_bf16 v[28:31], v[128:131], v[232:235], v[28:31]
	v_mfma_f32_16x16x32_bf16 v[24:27], v[136:139], v[232:235], v[24:27]
	v_mfma_f32_16x16x32_bf16 v[12:15], v[128:131], v[240:243], v[12:15]
	v_mfma_f32_16x16x32_bf16 v[8:11], v[136:139], v[240:243], v[8:11]
	v_mfma_f32_16x16x32_bf16 v[60:63], v[132:135], v[220:223], v[60:63]
	v_mfma_f32_16x16x32_bf16 v[56:59], v[140:143], v[220:223], v[56:59]
	v_mfma_f32_16x16x32_bf16 v[44:47], v[132:135], v[228:231], v[44:47]
	v_mfma_f32_16x16x32_bf16 v[40:43], v[140:143], v[228:231], v[40:43]
	v_mfma_f32_16x16x32_bf16 v[28:31], v[132:135], v[236:239], v[28:31]
	v_mfma_f32_16x16x32_bf16 v[24:27], v[140:143], v[236:239], v[24:27]
	v_mfma_f32_16x16x32_bf16 v[12:15], v[132:135], v[244:247], v[12:15]
	v_mfma_f32_16x16x32_bf16 v[8:11], v[140:143], v[244:247], v[8:11]
	v_mfma_f32_16x16x32_bf16 v[52:55], v[178:181], v[216:219], v[52:55]
	v_mfma_f32_16x16x32_bf16 v[48:51], v[208:211], v[216:219], v[48:51]
	v_mfma_f32_16x16x32_bf16 v[36:39], v[178:181], v[224:227], v[36:39]
	v_mfma_f32_16x16x32_bf16 v[32:35], v[208:211], v[224:227], v[32:35]
	v_mfma_f32_16x16x32_bf16 v[20:23], v[178:181], v[232:235], v[20:23]
	v_mfma_f32_16x16x32_bf16 v[16:19], v[208:211], v[232:235], v[16:19]
	v_mfma_f32_16x16x32_bf16 v[4:7], v[178:181], v[240:243], v[4:7]
	v_mfma_f32_16x16x32_bf16 v[0:3], v[208:211], v[240:243], v[0:3]
	v_mfma_f32_16x16x32_bf16 v[52:55], v[204:207], v[220:223], v[52:55]
	v_mfma_f32_16x16x32_bf16 v[48:51], v[212:215], v[220:223], v[48:51]
	v_mfma_f32_16x16x32_bf16 v[36:39], v[204:207], v[228:231], v[36:39]
	v_mfma_f32_16x16x32_bf16 v[32:35], v[212:215], v[228:231], v[32:35]
	v_mfma_f32_16x16x32_bf16 v[20:23], v[204:207], v[236:239], v[20:23]
	v_mfma_f32_16x16x32_bf16 v[16:19], v[212:215], v[236:239], v[16:19]
	v_mfma_f32_16x16x32_bf16 v[4:7], v[204:207], v[244:247], v[4:7]
	v_mfma_f32_16x16x32_bf16 v[0:3], v[212:215], v[244:247], v[0:3]
	s_barrier
	v_add_u32_e32 v140, 0x18000, v166
	v_add_u32_e32 v144, 0x1c000, v166
	ds_read_b128 v[128:131], v140
	ds_read_b128 v[132:135], v140 offset:1024
	ds_read_b128 v[136:139], v140 offset:2048
	ds_read_b128 v[140:143], v140 offset:3072
	ds_read_b128 v[178:181], v144
	ds_read_b128 v[204:207], v144 offset:1024
	ds_read_b128 v[208:211], v144 offset:2048
	ds_read_b128 v[212:215], v144 offset:3072
	ds_read_b128 v[216:219], v176 offset:32768
	ds_read_b128 v[220:223], v176 offset:33792
	ds_read_b128 v[224:227], v176 offset:34816
	ds_read_b128 v[228:231], v176 offset:35840
	ds_read_b128 v[232:235], v176 offset:36864
	ds_read_b128 v[236:239], v176 offset:37888
	ds_read_b128 v[240:243], v176 offset:38912
	ds_read_b128 v[244:247], v176 offset:39936
	s_add_i32 s4, 0, 0x18000
	s_add_i32 s5, 0, 0x1c000
	s_add_u32 s58, s62, 0xb0000
	s_addc_u32 s59, s63, 0
	s_mov_b32 m0, s65
	v_lshl_add_u64 v[202:203], s[58:59], 0, v[154:155]
	global_load_lds_dwordx4 v[202:203], off
	s_mov_b32 m0, s70
	v_lshl_add_u64 v[202:203], s[58:59], 0, v[156:157]
	global_load_lds_dwordx4 v[202:203], off
	s_waitcnt vmcnt(8)
	s_waitcnt lgkmcnt(0)
	s_barrier
	v_mfma_f32_16x16x32_bf16 v[124:127], v[128:131], v[216:219], v[124:127]
	v_mfma_f32_16x16x32_bf16 v[120:123], v[136:139], v[216:219], v[120:123]
	v_mfma_f32_16x16x32_bf16 v[108:111], v[128:131], v[224:227], v[108:111]
	v_mfma_f32_16x16x32_bf16 v[104:107], v[136:139], v[224:227], v[104:107]
	v_mfma_f32_16x16x32_bf16 v[92:95], v[128:131], v[232:235], v[92:95]
	v_mfma_f32_16x16x32_bf16 v[88:91], v[136:139], v[232:235], v[88:91]
	v_mfma_f32_16x16x32_bf16 v[76:79], v[128:131], v[240:243], v[76:79]
	v_mfma_f32_16x16x32_bf16 v[72:75], v[136:139], v[240:243], v[72:75]
	v_mfma_f32_16x16x32_bf16 v[124:127], v[132:135], v[220:223], v[124:127]
	v_mfma_f32_16x16x32_bf16 v[120:123], v[140:143], v[220:223], v[120:123]
	v_mfma_f32_16x16x32_bf16 v[108:111], v[132:135], v[228:231], v[108:111]
	v_mfma_f32_16x16x32_bf16 v[104:107], v[140:143], v[228:231], v[104:107]
	v_mfma_f32_16x16x32_bf16 v[92:95], v[132:135], v[236:239], v[92:95]
	v_mfma_f32_16x16x32_bf16 v[88:91], v[140:143], v[236:239], v[88:91]
	v_mfma_f32_16x16x32_bf16 v[76:79], v[132:135], v[244:247], v[76:79]
	v_mfma_f32_16x16x32_bf16 v[72:75], v[140:143], v[244:247], v[72:75]
	v_mfma_f32_16x16x32_bf16 v[116:119], v[178:181], v[216:219], v[116:119]
	v_mfma_f32_16x16x32_bf16 v[112:115], v[208:211], v[216:219], v[112:115]
	v_mfma_f32_16x16x32_bf16 v[100:103], v[178:181], v[224:227], v[100:103]
	v_mfma_f32_16x16x32_bf16 v[96:99], v[208:211], v[224:227], v[96:99]
	v_mfma_f32_16x16x32_bf16 v[84:87], v[178:181], v[232:235], v[84:87]
	v_mfma_f32_16x16x32_bf16 v[80:83], v[208:211], v[232:235], v[80:83]
	v_mfma_f32_16x16x32_bf16 v[68:71], v[178:181], v[240:243], v[68:71]
	v_mfma_f32_16x16x32_bf16 v[64:67], v[208:211], v[240:243], v[64:67]
	v_mfma_f32_16x16x32_bf16 v[116:119], v[204:207], v[220:223], v[116:119]
	v_mfma_f32_16x16x32_bf16 v[112:115], v[212:215], v[220:223], v[112:115]
	v_mfma_f32_16x16x32_bf16 v[100:103], v[204:207], v[228:231], v[100:103]
	v_mfma_f32_16x16x32_bf16 v[96:99], v[212:215], v[228:231], v[96:99]
	v_mfma_f32_16x16x32_bf16 v[84:87], v[204:207], v[236:239], v[84:87]
	v_mfma_f32_16x16x32_bf16 v[80:83], v[212:215], v[236:239], v[80:83]
	v_mfma_f32_16x16x32_bf16 v[68:71], v[204:207], v[244:247], v[68:71]
	v_mfma_f32_16x16x32_bf16 v[64:67], v[212:215], v[244:247], v[64:67]
	s_barrier
	s_add_i32 s4, s4, s33
	v_lshl_add_u64 v[164:165], v[164:165], 0, s[26:27]
	s_mov_b32 m0, s4
	ds_read_b128 v[216:219], v176 offset:49152
	ds_read_b128 v[220:223], v176 offset:50176
	ds_read_b128 v[224:227], v176 offset:51200
	ds_read_b128 v[228:231], v176 offset:52224
	ds_read_b128 v[232:235], v176 offset:53248
	ds_read_b128 v[236:239], v176 offset:54272
	ds_read_b128 v[240:243], v176 offset:55296
	ds_read_b128 v[244:247], v176 offset:56320
	global_load_lds_dwordx4 v[164:165], off
	s_add_i32 m0, s4, 0x2000
	s_add_u32 s34, s34, 0xb0080
	v_lshl_add_u64 v[164:165], v[248:249], 0, s[26:27]
	s_addc_u32 s35, s35, 0
	s_add_i32 s4, s5, s33
	global_load_lds_dwordx4 v[164:165], off
	s_mov_b32 m0, s4
	v_lshl_add_u64 v[164:165], s[34:35], 0, v[154:155]
	global_load_lds_dwordx4 v[164:165], off
	s_add_i32 m0, s4, 0x2000
	v_lshl_add_u64 v[164:165], s[34:35], 0, v[156:157]
	global_load_lds_dwordx4 v[164:165], off
	s_mov_b32 m0, s71
	v_lshl_add_u64 v[164:165], v[250:251], 0, s[26:27]
	global_load_lds_dwordx4 v[164:165], off
	s_mov_b32 m0, s72
	v_lshl_add_u64 v[164:165], v[252:253], 0, s[26:27]
	global_load_lds_dwordx4 v[164:165], off
	s_add_i32 s51, s51, 2
	s_add_u32 s28, s28, 0x100
	s_addc_u32 s29, s29, 0
	s_cmp_gt_u32 s51, 41
	s_mov_b64 s[58:59], s[60:61]
	s_waitcnt vmcnt(8)
	s_waitcnt lgkmcnt(0)
	s_barrier
	v_mfma_f32_16x16x32_bf16 v[60:63], v[128:131], v[216:219], v[60:63]
	v_mfma_f32_16x16x32_bf16 v[56:59], v[136:139], v[216:219], v[56:59]
	v_mfma_f32_16x16x32_bf16 v[44:47], v[128:131], v[224:227], v[44:47]
	v_mfma_f32_16x16x32_bf16 v[40:43], v[136:139], v[224:227], v[40:43]
	v_mfma_f32_16x16x32_bf16 v[28:31], v[128:131], v[232:235], v[28:31]
	v_mfma_f32_16x16x32_bf16 v[24:27], v[136:139], v[232:235], v[24:27]
	v_mfma_f32_16x16x32_bf16 v[12:15], v[128:131], v[240:243], v[12:15]
	v_mfma_f32_16x16x32_bf16 v[8:11], v[136:139], v[240:243], v[8:11]
	v_mfma_f32_16x16x32_bf16 v[60:63], v[132:135], v[220:223], v[60:63]
	v_mfma_f32_16x16x32_bf16 v[56:59], v[140:143], v[220:223], v[56:59]
	v_mfma_f32_16x16x32_bf16 v[44:47], v[132:135], v[228:231], v[44:47]
	v_mfma_f32_16x16x32_bf16 v[40:43], v[140:143], v[228:231], v[40:43]
	v_mfma_f32_16x16x32_bf16 v[28:31], v[132:135], v[236:239], v[28:31]
	v_mfma_f32_16x16x32_bf16 v[24:27], v[140:143], v[236:239], v[24:27]
	v_mfma_f32_16x16x32_bf16 v[12:15], v[132:135], v[244:247], v[12:15]
	v_mfma_f32_16x16x32_bf16 v[8:11], v[140:143], v[244:247], v[8:11]
	v_mfma_f32_16x16x32_bf16 v[52:55], v[178:181], v[216:219], v[52:55]
	v_mfma_f32_16x16x32_bf16 v[48:51], v[208:211], v[216:219], v[48:51]
	v_mfma_f32_16x16x32_bf16 v[36:39], v[178:181], v[224:227], v[36:39]
	v_mfma_f32_16x16x32_bf16 v[32:35], v[208:211], v[224:227], v[32:35]
	v_mfma_f32_16x16x32_bf16 v[20:23], v[178:181], v[232:235], v[20:23]
	v_mfma_f32_16x16x32_bf16 v[16:19], v[208:211], v[232:235], v[16:19]
	v_mfma_f32_16x16x32_bf16 v[4:7], v[178:181], v[240:243], v[4:7]
	v_mfma_f32_16x16x32_bf16 v[0:3], v[208:211], v[240:243], v[0:3]
	v_mfma_f32_16x16x32_bf16 v[52:55], v[204:207], v[220:223], v[52:55]
	v_mfma_f32_16x16x32_bf16 v[48:51], v[212:215], v[220:223], v[48:51]
	v_mfma_f32_16x16x32_bf16 v[36:39], v[204:207], v[228:231], v[36:39]
	v_mfma_f32_16x16x32_bf16 v[32:35], v[212:215], v[228:231], v[32:35]
	v_mfma_f32_16x16x32_bf16 v[20:23], v[204:207], v[236:239], v[20:23]
	v_mfma_f32_16x16x32_bf16 v[16:19], v[212:215], v[236:239], v[16:19]
	v_mfma_f32_16x16x32_bf16 v[4:7], v[204:207], v[244:247], v[4:7]
	v_mfma_f32_16x16x32_bf16 v[0:3], v[212:215], v[244:247], v[0:3]
	s_barrier
	s_cbranch_scc0 .LBB0_456
	s_and_b64 vcc, exec, s[54:55]
	s_cbranch_vccz .LBB0_459
	s_barrier

.LBB0_605:
	v_add_u32_e32 v140, 0x10000, v203
	v_add_u32_e32 v144, 0x14000, v203
	ds_read_b128 v[128:131], v140
	ds_read_b128 v[132:135], v140 offset:1024
	ds_read_b128 v[136:139], v140 offset:2048
	ds_read_b128 v[140:143], v140 offset:3072
	ds_read_b128 v[168:171], v144
	ds_read_b128 v[172:175], v144 offset:1024
	ds_read_b128 v[176:179], v144 offset:2048
	ds_read_b128 v[206:209], v144 offset:3072
	ds_read_b128 v[210:213], v205
	ds_read_b128 v[214:217], v205 offset:1024
	ds_read_b128 v[218:221], v205 offset:2048
	ds_read_b128 v[222:225], v205 offset:3072
	ds_read_b128 v[226:229], v205 offset:4096
	ds_read_b128 v[230:233], v205 offset:5120
	ds_read_b128 v[234:237], v205 offset:6144
	ds_read_b128 v[238:241], v205 offset:7168
	s_add_u32 s4, s0, 0xfffc0080
	s_addc_u32 s5, s1, -1
	s_add_i32 s89, 0, 0x10000
	s_cmp_eq_u32 s88, 12
	s_cselect_b32 s43, s3, s5
	s_cselect_b32 s42, s36, s4
	s_cselect_b32 s35, s39, s84
	s_cselect_b32 s34, s71, s79
	s_add_i32 s4, 0, 0x14000
	s_add_i32 m0, s69, 0xc000
	v_lshl_add_u64 v[180:181], s[0:1], 0, v[164:165]
	global_load_lds_dwordx4 v[180:181], off
	s_add_i32 m0, s69, 0xe000
	v_lshl_add_u64 v[180:181], s[0:1], 0, v[166:167]
	global_load_lds_dwordx4 v[180:181], off
	s_waitcnt vmcnt(8)
	s_waitcnt lgkmcnt(0)
	s_barrier
	v_mfma_f32_16x16x32_bf16 v[124:127], v[128:131], v[210:213], v[124:127]
	v_mfma_f32_16x16x32_bf16 v[120:123], v[136:139], v[210:213], v[120:123]
	v_mfma_f32_16x16x32_bf16 v[112:115], v[128:131], v[218:221], v[112:115]
	v_mfma_f32_16x16x32_bf16 v[108:111], v[136:139], v[218:221], v[108:111]
	v_mfma_f32_16x16x32_bf16 v[100:103], v[128:131], v[226:229], v[100:103]
	v_mfma_f32_16x16x32_bf16 v[92:95], v[136:139], v[226:229], v[92:95]
	v_mfma_f32_16x16x32_bf16 v[84:87], v[128:131], v[234:237], v[84:87]
	v_mfma_f32_16x16x32_bf16 v[76:79], v[136:139], v[234:237], v[76:79]
	v_mfma_f32_16x16x32_bf16 v[124:127], v[132:135], v[214:217], v[124:127]
	v_mfma_f32_16x16x32_bf16 v[120:123], v[140:143], v[214:217], v[120:123]
	v_mfma_f32_16x16x32_bf16 v[112:115], v[132:135], v[222:225], v[112:115]
	v_mfma_f32_16x16x32_bf16 v[108:111], v[140:143], v[222:225], v[108:111]
	v_mfma_f32_16x16x32_bf16 v[100:103], v[132:135], v[230:233], v[100:103]
	v_mfma_f32_16x16x32_bf16 v[92:95], v[140:143], v[230:233], v[92:95]
	v_mfma_f32_16x16x32_bf16 v[84:87], v[132:135], v[238:241], v[84:87]
	v_mfma_f32_16x16x32_bf16 v[76:79], v[140:143], v[238:241], v[76:79]
	v_mfma_f32_16x16x32_bf16 v[116:119], v[168:171], v[210:213], v[116:119]
	v_mfma_f32_16x16x32_bf16 v[104:107], v[176:179], v[210:213], v[104:107]
	v_mfma_f32_16x16x32_bf16 v[96:99], v[168:171], v[218:221], v[96:99]
	v_mfma_f32_16x16x32_bf16 v[88:91], v[176:179], v[218:221], v[88:91]
	v_mfma_f32_16x16x32_bf16 v[80:83], v[168:171], v[226:229], v[80:83]
	v_mfma_f32_16x16x32_bf16 v[72:75], v[176:179], v[226:229], v[72:75]
	v_mfma_f32_16x16x32_bf16 v[68:71], v[168:171], v[234:237], v[68:71]
	v_mfma_f32_16x16x32_bf16 v[64:67], v[176:179], v[234:237], v[64:67]
	v_mfma_f32_16x16x32_bf16 v[116:119], v[172:175], v[214:217], v[116:119]
	v_mfma_f32_16x16x32_bf16 v[104:107], v[206:209], v[214:217], v[104:107]
	v_mfma_f32_16x16x32_bf16 v[96:99], v[172:175], v[222:225], v[96:99]
	v_mfma_f32_16x16x32_bf16 v[88:91], v[206:209], v[222:225], v[88:91]
	v_mfma_f32_16x16x32_bf16 v[80:83], v[172:175], v[230:233], v[80:83]
	v_mfma_f32_16x16x32_bf16 v[72:75], v[206:209], v[230:233], v[72:75]
	v_mfma_f32_16x16x32_bf16 v[68:71], v[172:175], v[238:241], v[68:71]
	v_mfma_f32_16x16x32_bf16 v[64:67], v[206:209], v[238:241], v[64:67]
	s_barrier
	s_add_i32 s5, s89, s28
	v_lshl_add_u64 v[180:181], s[34:35], 0, v[156:157]
	s_mov_b32 m0, s5
	ds_read_b128 v[210:213], v205 offset:16384
	ds_read_b128 v[214:217], v205 offset:17408
	ds_read_b128 v[218:221], v205 offset:18432
	ds_read_b128 v[222:225], v205 offset:19456
	ds_read_b128 v[226:229], v205 offset:20480
	ds_read_b128 v[230:233], v205 offset:21504
	ds_read_b128 v[234:237], v205 offset:22528
	ds_read_b128 v[238:241], v205 offset:23552
	global_load_lds_dwordx4 v[180:181], off
	s_add_i32 m0, s5, 0x2000
	s_add_u32 s90, s34, 0x40000
	v_lshl_add_u64 v[242:243], s[34:35], 0, v[160:161]
	s_addc_u32 s91, s35, 0
	s_add_i32 s4, s4, s28
	global_load_lds_dwordx4 v[242:243], off
	v_lshl_add_u64 v[244:245], s[90:91], 0, v[156:157]
	s_mov_b32 m0, s4
	v_lshl_add_u64 v[246:247], s[42:43], 0, v[158:159]
	global_load_lds_dwordx4 v[244:245], off
	s_add_i32 m0, s4, 0x2000
	v_lshl_add_u64 v[244:245], s[90:91], 0, v[160:161]
	global_load_lds_dwordx4 v[244:245], off
	s_mov_b32 m0, s69
	v_lshl_add_u64 v[244:245], s[42:43], 0, v[154:155]
	global_load_lds_dwordx4 v[244:245], off
	s_mov_b32 m0, s62
	s_nop 0
	global_load_lds_dwordx4 v[246:247], off
	s_waitcnt vmcnt(8)
	s_waitcnt lgkmcnt(0)
	s_barrier
	v_mfma_f32_16x16x32_bf16 v[60:63], v[128:131], v[210:213], v[60:63]
	v_mfma_f32_16x16x32_bf16 v[56:59], v[136:139], v[210:213], v[56:59]
	v_mfma_f32_16x16x32_bf16 v[52:55], v[128:131], v[218:221], v[52:55]
	v_mfma_f32_16x16x32_bf16 v[44:47], v[136:139], v[218:221], v[44:47]
	v_mfma_f32_16x16x32_bf16 v[36:39], v[128:131], v[226:229], v[36:39]
	v_mfma_f32_16x16x32_bf16 v[28:31], v[136:139], v[226:229], v[28:31]
	v_mfma_f32_16x16x32_bf16 v[20:23], v[128:131], v[234:237], v[20:23]
	v_mfma_f32_16x16x32_bf16 v[12:15], v[136:139], v[234:237], v[12:15]
	v_mfma_f32_16x16x32_bf16 v[60:63], v[132:135], v[214:217], v[60:63]
	v_mfma_f32_16x16x32_bf16 v[56:59], v[140:143], v[214:217], v[56:59]
	v_mfma_f32_16x16x32_bf16 v[52:55], v[132:135], v[222:225], v[52:55]
	v_mfma_f32_16x16x32_bf16 v[44:47], v[140:143], v[222:225], v[44:47]
	v_mfma_f32_16x16x32_bf16 v[36:39], v[132:135], v[230:233], v[36:39]
	v_mfma_f32_16x16x32_bf16 v[28:31], v[140:143], v[230:233], v[28:31]
	v_mfma_f32_16x16x32_bf16 v[20:23], v[132:135], v[238:241], v[20:23]
	v_mfma_f32_16x16x32_bf16 v[12:15], v[140:143], v[238:241], v[12:15]
	v_mfma_f32_16x16x32_bf16 v[48:51], v[168:171], v[210:213], v[48:51]
	v_mfma_f32_16x16x32_bf16 v[40:43], v[176:179], v[210:213], v[40:43]
	v_mfma_f32_16x16x32_bf16 v[32:35], v[168:171], v[218:221], v[32:35]
	v_mfma_f32_16x16x32_bf16 v[24:27], v[176:179], v[218:221], v[24:27]
	v_mfma_f32_16x16x32_bf16 v[16:19], v[168:171], v[226:229], v[16:19]
	v_mfma_f32_16x16x32_bf16 v[8:11], v[176:179], v[226:229], v[8:11]
	v_mfma_f32_16x16x32_bf16 v[4:7], v[168:171], v[234:237], v[4:7]
	v_mfma_f32_16x16x32_bf16 v[0:3], v[176:179], v[234:237], v[0:3]
	v_mfma_f32_16x16x32_bf16 v[48:51], v[172:175], v[214:217], v[48:51]
	v_mfma_f32_16x16x32_bf16 v[40:43], v[206:209], v[214:217], v[40:43]
	v_mfma_f32_16x16x32_bf16 v[32:35], v[172:175], v[222:225], v[32:35]
	v_mfma_f32_16x16x32_bf16 v[24:27], v[206:209], v[222:225], v[24:27]
	v_mfma_f32_16x16x32_bf16 v[16:19], v[172:175], v[230:233], v[16:19]
	v_mfma_f32_16x16x32_bf16 v[8:11], v[206:209], v[230:233], v[8:11]
	v_mfma_f32_16x16x32_bf16 v[4:7], v[172:175], v[238:241], v[4:7]
	v_mfma_f32_16x16x32_bf16 v[0:3], v[206:209], v[238:241], v[0:3]
	s_barrier
	v_add_u32_e32 v140, 0x18000, v203
	v_add_u32_e32 v144, 0x1c000, v203
	ds_read_b128 v[128:131], v140
	ds_read_b128 v[132:135], v140 offset:1024
	ds_read_b128 v[136:139], v140 offset:2048
	ds_read_b128 v[140:143], v140 offset:3072
	ds_read_b128 v[168:171], v144
	ds_read_b128 v[172:175], v144 offset:1024
	ds_read_b128 v[176:179], v144 offset:2048
	ds_read_b128 v[206:209], v144 offset:3072
	ds_read_b128 v[210:213], v205 offset:32768
	ds_read_b128 v[214:217], v205 offset:33792
	ds_read_b128 v[218:221], v205 offset:34816
	ds_read_b128 v[222:225], v205 offset:35840
	ds_read_b128 v[226:229], v205 offset:36864
	ds_read_b128 v[230:233], v205 offset:37888
	ds_read_b128 v[234:237], v205 offset:38912
	ds_read_b128 v[238:241], v205 offset:39936
	s_add_i32 s4, 0, 0x18000
	s_add_i32 s5, 0, 0x1c000
	s_add_u32 s42, s42, 0x40000
	s_addc_u32 s43, s43, 0
	s_mov_b32 m0, s63
	v_lshl_add_u64 v[248:249], s[42:43], 0, v[154:155]
	global_load_lds_dwordx4 v[248:249], off
	s_mov_b32 m0, s50
	v_lshl_add_u64 v[248:249], s[42:43], 0, v[158:159]
	global_load_lds_dwordx4 v[248:249], off
	s_waitcnt vmcnt(8)
	s_waitcnt lgkmcnt(0)
	s_barrier
	v_mfma_f32_16x16x32_bf16 v[124:127], v[128:131], v[210:213], v[124:127]
	v_mfma_f32_16x16x32_bf16 v[120:123], v[136:139], v[210:213], v[120:123]
	v_mfma_f32_16x16x32_bf16 v[112:115], v[128:131], v[218:221], v[112:115]
	v_mfma_f32_16x16x32_bf16 v[108:111], v[136:139], v[218:221], v[108:111]
	v_mfma_f32_16x16x32_bf16 v[100:103], v[128:131], v[226:229], v[100:103]
	v_mfma_f32_16x16x32_bf16 v[92:95], v[136:139], v[226:229], v[92:95]
	v_mfma_f32_16x16x32_bf16 v[84:87], v[128:131], v[234:237], v[84:87]
	v_mfma_f32_16x16x32_bf16 v[76:79], v[136:139], v[234:237], v[76:79]
	v_mfma_f32_16x16x32_bf16 v[124:127], v[132:135], v[214:217], v[124:127]
	v_mfma_f32_16x16x32_bf16 v[120:123], v[140:143], v[214:217], v[120:123]
	v_mfma_f32_16x16x32_bf16 v[112:115], v[132:135], v[222:225], v[112:115]
	v_mfma_f32_16x16x32_bf16 v[108:111], v[140:143], v[222:225], v[108:111]
	v_mfma_f32_16x16x32_bf16 v[100:103], v[132:135], v[230:233], v[100:103]
	v_mfma_f32_16x16x32_bf16 v[92:95], v[140:143], v[230:233], v[92:95]
	v_mfma_f32_16x16x32_bf16 v[84:87], v[132:135], v[238:241], v[84:87]
	v_mfma_f32_16x16x32_bf16 v[76:79], v[140:143], v[238:241], v[76:79]
	v_mfma_f32_16x16x32_bf16 v[116:119], v[168:171], v[210:213], v[116:119]
	v_mfma_f32_16x16x32_bf16 v[104:107], v[176:179], v[210:213], v[104:107]
	v_mfma_f32_16x16x32_bf16 v[96:99], v[168:171], v[218:221], v[96:99]
	v_mfma_f32_16x16x32_bf16 v[88:91], v[176:179], v[218:221], v[88:91]
	v_mfma_f32_16x16x32_bf16 v[80:83], v[168:171], v[226:229], v[80:83]
	v_mfma_f32_16x16x32_bf16 v[72:75], v[176:179], v[226:229], v[72:75]
	v_mfma_f32_16x16x32_bf16 v[68:71], v[168:171], v[234:237], v[68:71]
	v_mfma_f32_16x16x32_bf16 v[64:67], v[176:179], v[234:237], v[64:67]
	v_mfma_f32_16x16x32_bf16 v[116:119], v[172:175], v[214:217], v[116:119]
	v_mfma_f32_16x16x32_bf16 v[104:107], v[206:209], v[214:217], v[104:107]
	v_mfma_f32_16x16x32_bf16 v[96:99], v[172:175], v[222:225], v[96:99]
	v_mfma_f32_16x16x32_bf16 v[88:91], v[206:209], v[222:225], v[88:91]
	v_mfma_f32_16x16x32_bf16 v[80:83], v[172:175], v[230:233], v[80:83]
	v_mfma_f32_16x16x32_bf16 v[72:75], v[206:209], v[230:233], v[72:75]
	v_mfma_f32_16x16x32_bf16 v[68:71], v[172:175], v[238:241], v[68:71]
	v_mfma_f32_16x16x32_bf16 v[64:67], v[206:209], v[238:241], v[64:67]
	s_barrier
	s_add_i32 s4, s4, s28
	v_lshl_add_u64 v[180:181], v[180:181], 0, s[26:27]
	s_mov_b32 m0, s4
	ds_read_b128 v[210:213], v205 offset:49152
	ds_read_b128 v[214:217], v205 offset:50176
	ds_read_b128 v[218:221], v205 offset:51200
	ds_read_b128 v[222:225], v205 offset:52224
	ds_read_b128 v[226:229], v205 offset:53248
	ds_read_b128 v[230:233], v205 offset:54272
	ds_read_b128 v[234:237], v205 offset:55296
	ds_read_b128 v[238:241], v205 offset:56320
	global_load_lds_dwordx4 v[180:181], off
	s_add_i32 m0, s4, 0x2000
	s_add_u32 s34, s34, 0x40080
	v_lshl_add_u64 v[180:181], v[242:243], 0, s[26:27]
	s_addc_u32 s35, s35, 0
	s_add_i32 s4, s5, s28
	global_load_lds_dwordx4 v[180:181], off
	s_mov_b32 m0, s4
	v_lshl_add_u64 v[180:181], s[34:35], 0, v[156:157]
	global_load_lds_dwordx4 v[180:181], off
	s_add_i32 m0, s4, 0x2000
	v_lshl_add_u64 v[180:181], s[34:35], 0, v[160:161]
	global_load_lds_dwordx4 v[180:181], off
	s_mov_b32 m0, s51
	v_lshl_add_u64 v[180:181], v[244:245], 0, s[26:27]
	global_load_lds_dwordx4 v[180:181], off
	s_mov_b32 m0, s64
	v_lshl_add_u64 v[180:181], v[246:247], 0, s[26:27]
	global_load_lds_dwordx4 v[180:181], off
	s_add_i32 s88, s88, 2
	s_add_u32 s0, s0, 0x100
	s_addc_u32 s1, s1, 0
	s_add_u32 s79, s79, 0x100
	s_addc_u32 s84, s84, 0
	s_cmp_gt_u32 s88, 13
	s_waitcnt vmcnt(8)
	s_waitcnt lgkmcnt(0)
	s_barrier
	v_mfma_f32_16x16x32_bf16 v[60:63], v[128:131], v[210:213], v[60:63]
	v_mfma_f32_16x16x32_bf16 v[56:59], v[136:139], v[210:213], v[56:59]
	v_mfma_f32_16x16x32_bf16 v[52:55], v[128:131], v[218:221], v[52:55]
	v_mfma_f32_16x16x32_bf16 v[44:47], v[136:139], v[218:221], v[44:47]
	v_mfma_f32_16x16x32_bf16 v[36:39], v[128:131], v[226:229], v[36:39]
	v_mfma_f32_16x16x32_bf16 v[28:31], v[136:139], v[226:229], v[28:31]
	v_mfma_f32_16x16x32_bf16 v[20:23], v[128:131], v[234:237], v[20:23]
	v_mfma_f32_16x16x32_bf16 v[12:15], v[136:139], v[234:237], v[12:15]
	v_mfma_f32_16x16x32_bf16 v[60:63], v[132:135], v[214:217], v[60:63]
	v_mfma_f32_16x16x32_bf16 v[56:59], v[140:143], v[214:217], v[56:59]
	v_mfma_f32_16x16x32_bf16 v[52:55], v[132:135], v[222:225], v[52:55]
	v_mfma_f32_16x16x32_bf16 v[44:47], v[140:143], v[222:225], v[44:47]
	v_mfma_f32_16x16x32_bf16 v[36:39], v[132:135], v[230:233], v[36:39]
	v_mfma_f32_16x16x32_bf16 v[28:31], v[140:143], v[230:233], v[28:31]
	v_mfma_f32_16x16x32_bf16 v[20:23], v[132:135], v[238:241], v[20:23]
	v_mfma_f32_16x16x32_bf16 v[12:15], v[140:143], v[238:241], v[12:15]
	v_mfma_f32_16x16x32_bf16 v[48:51], v[168:171], v[210:213], v[48:51]
	v_mfma_f32_16x16x32_bf16 v[40:43], v[176:179], v[210:213], v[40:43]
	v_mfma_f32_16x16x32_bf16 v[32:35], v[168:171], v[218:221], v[32:35]
	v_mfma_f32_16x16x32_bf16 v[24:27], v[176:179], v[218:221], v[24:27]
	v_mfma_f32_16x16x32_bf16 v[16:19], v[168:171], v[226:229], v[16:19]
	v_mfma_f32_16x16x32_bf16 v[8:11], v[176:179], v[226:229], v[8:11]
	v_mfma_f32_16x16x32_bf16 v[4:7], v[168:171], v[234:237], v[4:7]
	v_mfma_f32_16x16x32_bf16 v[0:3], v[176:179], v[234:237], v[0:3]
	v_mfma_f32_16x16x32_bf16 v[48:51], v[172:175], v[214:217], v[48:51]
	v_mfma_f32_16x16x32_bf16 v[40:43], v[206:209], v[214:217], v[40:43]
	v_mfma_f32_16x16x32_bf16 v[32:35], v[172:175], v[222:225], v[32:35]
	v_mfma_f32_16x16x32_bf16 v[24:27], v[206:209], v[222:225], v[24:27]
	v_mfma_f32_16x16x32_bf16 v[16:19], v[172:175], v[230:233], v[16:19]
	v_mfma_f32_16x16x32_bf16 v[8:11], v[206:209], v[230:233], v[8:11]
	v_mfma_f32_16x16x32_bf16 v[4:7], v[172:175], v[238:241], v[4:7]
	v_mfma_f32_16x16x32_bf16 v[0:3], v[206:209], v[238:241], v[0:3]
	s_barrier
	s_cbranch_scc0 .LBB0_605
	s_and_b64 vcc, exec, s[66:67]
	s_cbranch_vccz .LBB0_608
	s_barrier

.LBB0_1005:
	v_add_u32_e32 v138, 0x10000, v141
	ds_read_b128 v[154:157], v138
	ds_read_b128 v[158:161], v138 offset:1024
	ds_read_b128 v[162:165], v138 offset:2048
	ds_read_b128 v[166:169], v138 offset:3072
	v_add_u32_e32 v138, 0x14000, v141
	ds_read_b128 v[170:173], v138
	ds_read_b128 v[174:177], v138 offset:1024
	ds_read_b128 v[178:181], v138 offset:2048
	ds_read_b128 v[204:207], v138 offset:3072
	ds_read_b128 v[208:211], v143
	ds_read_b128 v[212:215], v143 offset:1024
	ds_read_b128 v[216:219], v143 offset:2048
	ds_read_b128 v[220:223], v143 offset:3072
	ds_read_b128 v[224:227], v143 offset:4096
	ds_read_b128 v[228:231], v143 offset:5120
	ds_read_b128 v[232:235], v143 offset:6144
	ds_read_b128 v[236:239], v143 offset:7168
	s_add_u32 s4, s54, 0xfffe0080
	s_addc_u32 s5, s55, -1
	s_add_i32 s72, 0, 0x10000
	s_cmp_eq_u32 s71, 4
	s_cselect_b32 s59, s29, s5
	s_cselect_b32 s58, s47, s4
	s_cselect_b32 s35, s45, s70
	s_cselect_b32 s34, s68, s69
	s_add_i32 s73, 0, 0x14000
	s_add_i32 m0, s53, 0xc000
	v_lshl_add_u64 v[138:139], s[54:55], 0, v[134:135]
	global_load_lds_dwordx4 v[138:139], off
	s_add_i32 m0, s53, 0xe000
	v_lshl_add_u64 v[138:139], s[54:55], 0, v[136:137]
	global_load_lds_dwordx4 v[138:139], off
	s_waitcnt vmcnt(8)
	s_waitcnt lgkmcnt(0)
	s_barrier
	v_mfma_f32_16x16x32_bf16 v[120:123], v[154:157], v[208:211], v[120:123]
	v_mfma_f32_16x16x32_bf16 v[124:127], v[162:165], v[208:211], v[124:127]
	v_mfma_f32_16x16x32_bf16 v[104:107], v[154:157], v[216:219], v[104:107]
	v_mfma_f32_16x16x32_bf16 v[108:111], v[162:165], v[216:219], v[108:111]
	v_mfma_f32_16x16x32_bf16 v[88:91], v[154:157], v[224:227], v[88:91]
	v_mfma_f32_16x16x32_bf16 v[92:95], v[162:165], v[224:227], v[92:95]
	v_mfma_f32_16x16x32_bf16 v[72:75], v[154:157], v[232:235], v[72:75]
	v_mfma_f32_16x16x32_bf16 v[76:79], v[162:165], v[232:235], v[76:79]
	v_mfma_f32_16x16x32_bf16 v[120:123], v[158:161], v[212:215], v[120:123]
	v_mfma_f32_16x16x32_bf16 v[124:127], v[166:169], v[212:215], v[124:127]
	v_mfma_f32_16x16x32_bf16 v[104:107], v[158:161], v[220:223], v[104:107]
	v_mfma_f32_16x16x32_bf16 v[108:111], v[166:169], v[220:223], v[108:111]
	v_mfma_f32_16x16x32_bf16 v[88:91], v[158:161], v[228:231], v[88:91]
	v_mfma_f32_16x16x32_bf16 v[92:95], v[166:169], v[228:231], v[92:95]
	v_mfma_f32_16x16x32_bf16 v[72:75], v[158:161], v[236:239], v[72:75]
	v_mfma_f32_16x16x32_bf16 v[76:79], v[166:169], v[236:239], v[76:79]
	v_mfma_f32_16x16x32_bf16 v[112:115], v[170:173], v[208:211], v[112:115]
	v_mfma_f32_16x16x32_bf16 v[116:119], v[178:181], v[208:211], v[116:119]
	v_mfma_f32_16x16x32_bf16 v[96:99], v[170:173], v[216:219], v[96:99]
	v_mfma_f32_16x16x32_bf16 v[100:103], v[178:181], v[216:219], v[100:103]
	v_mfma_f32_16x16x32_bf16 v[80:83], v[170:173], v[224:227], v[80:83]
	v_mfma_f32_16x16x32_bf16 v[84:87], v[178:181], v[224:227], v[84:87]
	v_mfma_f32_16x16x32_bf16 v[64:67], v[170:173], v[232:235], v[64:67]
	v_mfma_f32_16x16x32_bf16 v[68:71], v[178:181], v[232:235], v[68:71]
	v_mfma_f32_16x16x32_bf16 v[112:115], v[174:177], v[212:215], v[112:115]
	v_mfma_f32_16x16x32_bf16 v[116:119], v[204:207], v[212:215], v[116:119]
	v_mfma_f32_16x16x32_bf16 v[96:99], v[174:177], v[220:223], v[96:99]
	v_mfma_f32_16x16x32_bf16 v[100:103], v[204:207], v[220:223], v[100:103]
	v_mfma_f32_16x16x32_bf16 v[80:83], v[174:177], v[228:231], v[80:83]
	v_mfma_f32_16x16x32_bf16 v[84:87], v[204:207], v[228:231], v[84:87]
	v_mfma_f32_16x16x32_bf16 v[64:67], v[174:177], v[236:239], v[64:67]
	v_mfma_f32_16x16x32_bf16 v[68:71], v[204:207], v[236:239], v[68:71]
	s_barrier
	s_add_i32 s4, s72, s30
	v_lshl_add_u64 v[138:139], s[34:35], 0, v[144:145]
	s_mov_b32 m0, s4
	ds_read_b128 v[208:211], v143 offset:16384
	ds_read_b128 v[212:215], v143 offset:17408
	ds_read_b128 v[216:219], v143 offset:18432
	ds_read_b128 v[220:223], v143 offset:19456
	ds_read_b128 v[224:227], v143 offset:20480
	ds_read_b128 v[228:231], v143 offset:21504
	ds_read_b128 v[232:235], v143 offset:22528
	ds_read_b128 v[236:239], v143 offset:23552
	global_load_lds_dwordx4 v[138:139], off
	s_add_i32 m0, s4, 0x2000
	s_add_u32 s4, s34, 0x20000
	v_lshl_add_u64 v[202:203], s[34:35], 0, v[132:133]
	s_addc_u32 s5, s35, 0
	s_add_i32 s72, s73, s30
	global_load_lds_dwordx4 v[202:203], off
	v_lshl_add_u64 v[240:241], s[4:5], 0, v[144:145]
	s_mov_b32 m0, s72
	v_lshl_add_u64 v[242:243], s[58:59], 0, v[130:131]
	global_load_lds_dwordx4 v[240:241], off
	s_add_i32 m0, s72, 0x2000
	v_lshl_add_u64 v[240:241], s[4:5], 0, v[132:133]
	global_load_lds_dwordx4 v[240:241], off
	s_mov_b32 m0, s53
	v_lshl_add_u64 v[240:241], s[58:59], 0, v[128:129]
	global_load_lds_dwordx4 v[240:241], off
	s_mov_b32 m0, s62
	s_nop 0
	global_load_lds_dwordx4 v[242:243], off
	s_waitcnt vmcnt(8)
	s_waitcnt lgkmcnt(0)
	s_barrier
	v_mfma_f32_16x16x32_bf16 v[56:59], v[154:157], v[208:211], v[56:59]
	v_mfma_f32_16x16x32_bf16 v[60:63], v[162:165], v[208:211], v[60:63]
	v_mfma_f32_16x16x32_bf16 v[40:43], v[154:157], v[216:219], v[40:43]
	v_mfma_f32_16x16x32_bf16 v[44:47], v[162:165], v[216:219], v[44:47]
	v_mfma_f32_16x16x32_bf16 v[24:27], v[154:157], v[224:227], v[24:27]
	v_mfma_f32_16x16x32_bf16 v[28:31], v[162:165], v[224:227], v[28:31]
	v_mfma_f32_16x16x32_bf16 v[8:11], v[154:157], v[232:235], v[8:11]
	v_mfma_f32_16x16x32_bf16 v[12:15], v[162:165], v[232:235], v[12:15]
	v_mfma_f32_16x16x32_bf16 v[56:59], v[158:161], v[212:215], v[56:59]
	v_mfma_f32_16x16x32_bf16 v[60:63], v[166:169], v[212:215], v[60:63]
	v_mfma_f32_16x16x32_bf16 v[40:43], v[158:161], v[220:223], v[40:43]
	v_mfma_f32_16x16x32_bf16 v[44:47], v[166:169], v[220:223], v[44:47]
	v_mfma_f32_16x16x32_bf16 v[24:27], v[158:161], v[228:231], v[24:27]
	v_mfma_f32_16x16x32_bf16 v[28:31], v[166:169], v[228:231], v[28:31]
	v_mfma_f32_16x16x32_bf16 v[8:11], v[158:161], v[236:239], v[8:11]
	v_mfma_f32_16x16x32_bf16 v[12:15], v[166:169], v[236:239], v[12:15]
	v_mfma_f32_16x16x32_bf16 v[48:51], v[170:173], v[208:211], v[48:51]
	v_mfma_f32_16x16x32_bf16 v[52:55], v[178:181], v[208:211], v[52:55]
	v_mfma_f32_16x16x32_bf16 v[32:35], v[170:173], v[216:219], v[32:35]
	v_mfma_f32_16x16x32_bf16 v[36:39], v[178:181], v[216:219], v[36:39]
	v_mfma_f32_16x16x32_bf16 v[16:19], v[170:173], v[224:227], v[16:19]
	v_mfma_f32_16x16x32_bf16 v[20:23], v[178:181], v[224:227], v[20:23]
	v_mfma_f32_16x16x32_bf16 v[0:3], v[170:173], v[232:235], v[0:3]
	v_mfma_f32_16x16x32_bf16 v[4:7], v[178:181], v[232:235], v[4:7]
	v_mfma_f32_16x16x32_bf16 v[48:51], v[174:177], v[212:215], v[48:51]
	v_mfma_f32_16x16x32_bf16 v[52:55], v[204:207], v[212:215], v[52:55]
	v_mfma_f32_16x16x32_bf16 v[32:35], v[174:177], v[220:223], v[32:35]
	v_mfma_f32_16x16x32_bf16 v[36:39], v[204:207], v[220:223], v[36:39]
	v_mfma_f32_16x16x32_bf16 v[16:19], v[174:177], v[228:231], v[16:19]
	v_mfma_f32_16x16x32_bf16 v[20:23], v[204:207], v[228:231], v[20:23]
	v_mfma_f32_16x16x32_bf16 v[0:3], v[174:177], v[236:239], v[0:3]
	v_mfma_f32_16x16x32_bf16 v[4:7], v[204:207], v[236:239], v[4:7]
	s_barrier
	v_add_u32_e32 v166, 0x18000, v141
	v_add_u32_e32 v204, 0x1c000, v141
	ds_read_b128 v[154:157], v166
	ds_read_b128 v[158:161], v166 offset:1024
	ds_read_b128 v[162:165], v166 offset:2048
	ds_read_b128 v[166:169], v166 offset:3072
	ds_read_b128 v[170:173], v204
	ds_read_b128 v[174:177], v204 offset:1024
	ds_read_b128 v[178:181], v204 offset:2048
	ds_read_b128 v[204:207], v204 offset:3072
	ds_read_b128 v[208:211], v143 offset:32768
	ds_read_b128 v[212:215], v143 offset:33792
	ds_read_b128 v[216:219], v143 offset:34816
	ds_read_b128 v[220:223], v143 offset:35840
	ds_read_b128 v[224:227], v143 offset:36864
	ds_read_b128 v[228:231], v143 offset:37888
	ds_read_b128 v[232:235], v143 offset:38912
	ds_read_b128 v[236:239], v143 offset:39936
	s_add_i32 s72, 0, 0x18000
	s_add_i32 s73, 0, 0x1c000
	s_add_u32 s4, s58, 0x20000
	s_addc_u32 s5, s59, 0
	s_mov_b32 m0, s63
	v_lshl_add_u64 v[244:245], s[4:5], 0, v[128:129]
	global_load_lds_dwordx4 v[244:245], off
	s_mov_b32 m0, s64
	v_lshl_add_u64 v[244:245], s[4:5], 0, v[130:131]
	global_load_lds_dwordx4 v[244:245], off
	s_waitcnt vmcnt(8)
	s_waitcnt lgkmcnt(0)
	s_barrier
	v_mfma_f32_16x16x32_bf16 v[120:123], v[154:157], v[208:211], v[120:123]
	v_mfma_f32_16x16x32_bf16 v[124:127], v[162:165], v[208:211], v[124:127]
	v_mfma_f32_16x16x32_bf16 v[104:107], v[154:157], v[216:219], v[104:107]
	v_mfma_f32_16x16x32_bf16 v[108:111], v[162:165], v[216:219], v[108:111]
	v_mfma_f32_16x16x32_bf16 v[88:91], v[154:157], v[224:227], v[88:91]
	v_mfma_f32_16x16x32_bf16 v[92:95], v[162:165], v[224:227], v[92:95]
	v_mfma_f32_16x16x32_bf16 v[72:75], v[154:157], v[232:235], v[72:75]
	v_mfma_f32_16x16x32_bf16 v[76:79], v[162:165], v[232:235], v[76:79]
	v_mfma_f32_16x16x32_bf16 v[120:123], v[158:161], v[212:215], v[120:123]
	v_mfma_f32_16x16x32_bf16 v[124:127], v[166:169], v[212:215], v[124:127]
	v_mfma_f32_16x16x32_bf16 v[104:107], v[158:161], v[220:223], v[104:107]
	v_mfma_f32_16x16x32_bf16 v[108:111], v[166:169], v[220:223], v[108:111]
	v_mfma_f32_16x16x32_bf16 v[88:91], v[158:161], v[228:231], v[88:91]
	v_mfma_f32_16x16x32_bf16 v[92:95], v[166:169], v[228:231], v[92:95]
	v_mfma_f32_16x16x32_bf16 v[72:75], v[158:161], v[236:239], v[72:75]
	v_mfma_f32_16x16x32_bf16 v[76:79], v[166:169], v[236:239], v[76:79]
	v_mfma_f32_16x16x32_bf16 v[112:115], v[170:173], v[208:211], v[112:115]
	v_mfma_f32_16x16x32_bf16 v[116:119], v[178:181], v[208:211], v[116:119]
	v_mfma_f32_16x16x32_bf16 v[96:99], v[170:173], v[216:219], v[96:99]
	v_mfma_f32_16x16x32_bf16 v[100:103], v[178:181], v[216:219], v[100:103]
	v_mfma_f32_16x16x32_bf16 v[80:83], v[170:173], v[224:227], v[80:83]
	v_mfma_f32_16x16x32_bf16 v[84:87], v[178:181], v[224:227], v[84:87]
	v_mfma_f32_16x16x32_bf16 v[64:67], v[170:173], v[232:235], v[64:67]
	v_mfma_f32_16x16x32_bf16 v[68:71], v[178:181], v[232:235], v[68:71]
	v_mfma_f32_16x16x32_bf16 v[112:115], v[174:177], v[212:215], v[112:115]
	v_mfma_f32_16x16x32_bf16 v[116:119], v[204:207], v[212:215], v[116:119]
	v_mfma_f32_16x16x32_bf16 v[96:99], v[174:177], v[220:223], v[96:99]
	v_mfma_f32_16x16x32_bf16 v[100:103], v[204:207], v[220:223], v[100:103]
	v_mfma_f32_16x16x32_bf16 v[80:83], v[174:177], v[228:231], v[80:83]
	v_mfma_f32_16x16x32_bf16 v[84:87], v[204:207], v[228:231], v[84:87]
	v_mfma_f32_16x16x32_bf16 v[64:67], v[174:177], v[236:239], v[64:67]
	v_mfma_f32_16x16x32_bf16 v[68:71], v[204:207], v[236:239], v[68:71]
	s_barrier
	s_add_i32 s4, s72, s30
	v_lshl_add_u64 v[138:139], v[138:139], 0, s[26:27]
	s_mov_b32 m0, s4
	ds_read_b128 v[208:211], v143 offset:49152
	ds_read_b128 v[212:215], v143 offset:50176
	ds_read_b128 v[216:219], v143 offset:51200
	ds_read_b128 v[220:223], v143 offset:52224
	ds_read_b128 v[224:227], v143 offset:53248
	ds_read_b128 v[228:231], v143 offset:54272
	ds_read_b128 v[232:235], v143 offset:55296
	ds_read_b128 v[236:239], v143 offset:56320
	global_load_lds_dwordx4 v[138:139], off
	s_add_i32 m0, s4, 0x2000
	s_add_u32 s4, s34, 0x20080
	v_lshl_add_u64 v[138:139], v[202:203], 0, s[26:27]
	s_addc_u32 s5, s35, 0
	s_add_i32 s34, s73, s30
	global_load_lds_dwordx4 v[138:139], off
	s_mov_b32 m0, s34
	v_lshl_add_u64 v[138:139], s[4:5], 0, v[144:145]
	global_load_lds_dwordx4 v[138:139], off
	s_add_i32 m0, s34, 0x2000
	v_lshl_add_u64 v[138:139], s[4:5], 0, v[132:133]
	global_load_lds_dwordx4 v[138:139], off
	s_mov_b32 m0, s65
	v_lshl_add_u64 v[138:139], v[240:241], 0, s[26:27]
	global_load_lds_dwordx4 v[138:139], off
	s_mov_b32 m0, s66
	v_lshl_add_u64 v[138:139], v[242:243], 0, s[26:27]
	global_load_lds_dwordx4 v[138:139], off
	s_add_i32 s71, s71, 2
	s_add_u32 s54, s54, 0x100
	s_addc_u32 s55, s55, 0
	s_add_u32 s69, s69, 0x100
	s_addc_u32 s70, s70, 0
	s_cmp_gt_u32 s71, 5
	s_waitcnt vmcnt(8)
	s_waitcnt lgkmcnt(0)
	s_barrier
	v_mfma_f32_16x16x32_bf16 v[56:59], v[154:157], v[208:211], v[56:59]
	v_mfma_f32_16x16x32_bf16 v[60:63], v[162:165], v[208:211], v[60:63]
	v_mfma_f32_16x16x32_bf16 v[40:43], v[154:157], v[216:219], v[40:43]
	v_mfma_f32_16x16x32_bf16 v[44:47], v[162:165], v[216:219], v[44:47]
	v_mfma_f32_16x16x32_bf16 v[24:27], v[154:157], v[224:227], v[24:27]
	v_mfma_f32_16x16x32_bf16 v[28:31], v[162:165], v[224:227], v[28:31]
	v_mfma_f32_16x16x32_bf16 v[8:11], v[154:157], v[232:235], v[8:11]
	v_mfma_f32_16x16x32_bf16 v[12:15], v[162:165], v[232:235], v[12:15]
	v_mfma_f32_16x16x32_bf16 v[56:59], v[158:161], v[212:215], v[56:59]
	v_mfma_f32_16x16x32_bf16 v[60:63], v[166:169], v[212:215], v[60:63]
	v_mfma_f32_16x16x32_bf16 v[40:43], v[158:161], v[220:223], v[40:43]
	v_mfma_f32_16x16x32_bf16 v[44:47], v[166:169], v[220:223], v[44:47]
	v_mfma_f32_16x16x32_bf16 v[24:27], v[158:161], v[228:231], v[24:27]
	v_mfma_f32_16x16x32_bf16 v[28:31], v[166:169], v[228:231], v[28:31]
	v_mfma_f32_16x16x32_bf16 v[8:11], v[158:161], v[236:239], v[8:11]
	v_mfma_f32_16x16x32_bf16 v[12:15], v[166:169], v[236:239], v[12:15]
	v_mfma_f32_16x16x32_bf16 v[48:51], v[170:173], v[208:211], v[48:51]
	v_mfma_f32_16x16x32_bf16 v[52:55], v[178:181], v[208:211], v[52:55]
	v_mfma_f32_16x16x32_bf16 v[32:35], v[170:173], v[216:219], v[32:35]
	v_mfma_f32_16x16x32_bf16 v[36:39], v[178:181], v[216:219], v[36:39]
	v_mfma_f32_16x16x32_bf16 v[16:19], v[170:173], v[224:227], v[16:19]
	v_mfma_f32_16x16x32_bf16 v[20:23], v[178:181], v[224:227], v[20:23]
	v_mfma_f32_16x16x32_bf16 v[0:3], v[170:173], v[232:235], v[0:3]
	v_mfma_f32_16x16x32_bf16 v[4:7], v[178:181], v[232:235], v[4:7]
	v_mfma_f32_16x16x32_bf16 v[48:51], v[174:177], v[212:215], v[48:51]
	v_mfma_f32_16x16x32_bf16 v[52:55], v[204:207], v[212:215], v[52:55]
	v_mfma_f32_16x16x32_bf16 v[32:35], v[174:177], v[220:223], v[32:35]
	v_mfma_f32_16x16x32_bf16 v[36:39], v[204:207], v[220:223], v[36:39]
	v_mfma_f32_16x16x32_bf16 v[16:19], v[174:177], v[228:231], v[16:19]
	v_mfma_f32_16x16x32_bf16 v[20:23], v[204:207], v[228:231], v[20:23]
	v_mfma_f32_16x16x32_bf16 v[0:3], v[174:177], v[236:239], v[0:3]
	v_mfma_f32_16x16x32_bf16 v[4:7], v[204:207], v[236:239], v[4:7]
	s_barrier
	s_cbranch_scc0 .LBB0_1005
	v_readlane_b32 s68, v255, 7
	s_and_b64 vcc, exec, s[42:43]
	v_readlane_b32 s69, v255, 8
	s_cbranch_vccz .LBB0_1008
	s_barrier

.LBB0_1093:
	v_add_u32_e32 v164, 0x10000, v143
	v_add_u32_e32 v180, 0x14000, v143
	ds_read_b128 v[138:141], v164
	ds_read_b128 v[156:159], v164 offset:1024
	ds_read_b128 v[160:163], v164 offset:2048
	ds_read_b128 v[164:167], v164 offset:3072
	ds_read_b128 v[168:171], v180
	ds_read_b128 v[172:175], v180 offset:1024
	ds_read_b128 v[176:179], v180 offset:2048
	ds_read_b128 v[204:207], v180 offset:3072
	ds_read_b128 v[208:211], v155
	ds_read_b128 v[212:215], v155 offset:1024
	ds_read_b128 v[216:219], v155 offset:2048
	ds_read_b128 v[220:223], v155 offset:3072
	ds_read_b128 v[224:227], v155 offset:4096
	ds_read_b128 v[228:231], v155 offset:5120
	ds_read_b128 v[232:235], v155 offset:6144
	ds_read_b128 v[236:239], v155 offset:7168
	s_add_u32 s4, s58, 0xfffe0080
	s_addc_u32 s5, s59, -1
	s_add_i32 s74, 0, 0x10000
	s_cmp_eq_u32 s73, 4
	s_cselect_b32 s61, s33, s5
	s_cselect_b32 s60, s36, s4
	s_cselect_b32 s35, s49, s72
	s_cselect_b32 s34, s51, s71
	s_add_i32 s75, 0, 0x14000
	s_add_i32 m0, s64, 0xc000
	v_lshl_add_u64 v[180:181], s[58:59], 0, v[134:135]
	global_load_lds_dwordx4 v[180:181], off
	s_add_i32 m0, s64, 0xe000
	v_lshl_add_u64 v[180:181], s[58:59], 0, v[136:137]
	global_load_lds_dwordx4 v[180:181], off
	s_waitcnt vmcnt(8)
	s_waitcnt lgkmcnt(0)
	s_barrier
	v_mfma_f32_16x16x32_bf16 v[124:127], v[138:141], v[208:211], v[124:127]
	v_mfma_f32_16x16x32_bf16 v[120:123], v[160:163], v[208:211], v[120:123]
	v_mfma_f32_16x16x32_bf16 v[108:111], v[138:141], v[216:219], v[108:111]
	v_mfma_f32_16x16x32_bf16 v[104:107], v[160:163], v[216:219], v[104:107]
	v_mfma_f32_16x16x32_bf16 v[92:95], v[138:141], v[224:227], v[92:95]
	v_mfma_f32_16x16x32_bf16 v[88:91], v[160:163], v[224:227], v[88:91]
	v_mfma_f32_16x16x32_bf16 v[76:79], v[138:141], v[232:235], v[76:79]
	v_mfma_f32_16x16x32_bf16 v[72:75], v[160:163], v[232:235], v[72:75]
	v_mfma_f32_16x16x32_bf16 v[124:127], v[156:159], v[212:215], v[124:127]
	v_mfma_f32_16x16x32_bf16 v[120:123], v[164:167], v[212:215], v[120:123]
	v_mfma_f32_16x16x32_bf16 v[108:111], v[156:159], v[220:223], v[108:111]
	v_mfma_f32_16x16x32_bf16 v[104:107], v[164:167], v[220:223], v[104:107]
	v_mfma_f32_16x16x32_bf16 v[92:95], v[156:159], v[228:231], v[92:95]
	v_mfma_f32_16x16x32_bf16 v[88:91], v[164:167], v[228:231], v[88:91]
	v_mfma_f32_16x16x32_bf16 v[76:79], v[156:159], v[236:239], v[76:79]
	v_mfma_f32_16x16x32_bf16 v[72:75], v[164:167], v[236:239], v[72:75]
	v_mfma_f32_16x16x32_bf16 v[116:119], v[168:171], v[208:211], v[116:119]
	v_mfma_f32_16x16x32_bf16 v[112:115], v[176:179], v[208:211], v[112:115]
	v_mfma_f32_16x16x32_bf16 v[100:103], v[168:171], v[216:219], v[100:103]
	v_mfma_f32_16x16x32_bf16 v[96:99], v[176:179], v[216:219], v[96:99]
	v_mfma_f32_16x16x32_bf16 v[84:87], v[168:171], v[224:227], v[84:87]
	v_mfma_f32_16x16x32_bf16 v[80:83], v[176:179], v[224:227], v[80:83]
	v_mfma_f32_16x16x32_bf16 v[68:71], v[168:171], v[232:235], v[68:71]
	v_mfma_f32_16x16x32_bf16 v[64:67], v[176:179], v[232:235], v[64:67]
	v_mfma_f32_16x16x32_bf16 v[116:119], v[172:175], v[212:215], v[116:119]
	v_mfma_f32_16x16x32_bf16 v[112:115], v[204:207], v[212:215], v[112:115]
	v_mfma_f32_16x16x32_bf16 v[100:103], v[172:175], v[220:223], v[100:103]
	v_mfma_f32_16x16x32_bf16 v[96:99], v[204:207], v[220:223], v[96:99]
	v_mfma_f32_16x16x32_bf16 v[84:87], v[172:175], v[228:231], v[84:87]
	v_mfma_f32_16x16x32_bf16 v[80:83], v[204:207], v[228:231], v[80:83]
	v_mfma_f32_16x16x32_bf16 v[68:71], v[172:175], v[236:239], v[68:71]
	v_mfma_f32_16x16x32_bf16 v[64:67], v[204:207], v[236:239], v[64:67]
	s_barrier
	s_add_i32 s4, s74, s28
	v_lshl_add_u64 v[180:181], s[34:35], 0, v[144:145]
	s_mov_b32 m0, s4
	ds_read_b128 v[208:211], v155 offset:16384
	ds_read_b128 v[212:215], v155 offset:17408
	ds_read_b128 v[216:219], v155 offset:18432
	ds_read_b128 v[220:223], v155 offset:19456
	ds_read_b128 v[224:227], v155 offset:20480
	ds_read_b128 v[228:231], v155 offset:21504
	ds_read_b128 v[232:235], v155 offset:22528
	ds_read_b128 v[236:239], v155 offset:23552
	global_load_lds_dwordx4 v[180:181], off
	s_add_i32 m0, s4, 0x2000
	s_add_u32 s4, s34, 0x20000
	v_lshl_add_u64 v[202:203], s[34:35], 0, v[132:133]
	s_addc_u32 s5, s35, 0
	s_add_i32 s74, s75, s28
	global_load_lds_dwordx4 v[202:203], off
	v_lshl_add_u64 v[240:241], s[4:5], 0, v[144:145]
	s_mov_b32 m0, s74
	v_lshl_add_u64 v[242:243], s[60:61], 0, v[130:131]
	global_load_lds_dwordx4 v[240:241], off
	s_add_i32 m0, s74, 0x2000
	v_lshl_add_u64 v[240:241], s[4:5], 0, v[132:133]
	global_load_lds_dwordx4 v[240:241], off
	s_mov_b32 m0, s64
	v_lshl_add_u64 v[240:241], s[60:61], 0, v[128:129]
	global_load_lds_dwordx4 v[240:241], off
	s_mov_b32 m0, s65
	s_nop 0
	global_load_lds_dwordx4 v[242:243], off
	s_waitcnt vmcnt(8)
	s_waitcnt lgkmcnt(0)
	s_barrier
	v_mfma_f32_16x16x32_bf16 v[60:63], v[138:141], v[208:211], v[60:63]
	v_mfma_f32_16x16x32_bf16 v[56:59], v[160:163], v[208:211], v[56:59]
	v_mfma_f32_16x16x32_bf16 v[44:47], v[138:141], v[216:219], v[44:47]
	v_mfma_f32_16x16x32_bf16 v[40:43], v[160:163], v[216:219], v[40:43]
	v_mfma_f32_16x16x32_bf16 v[28:31], v[138:141], v[224:227], v[28:31]
	v_mfma_f32_16x16x32_bf16 v[24:27], v[160:163], v[224:227], v[24:27]
	v_mfma_f32_16x16x32_bf16 v[12:15], v[138:141], v[232:235], v[12:15]
	v_mfma_f32_16x16x32_bf16 v[8:11], v[160:163], v[232:235], v[8:11]
	v_mfma_f32_16x16x32_bf16 v[60:63], v[156:159], v[212:215], v[60:63]
	v_mfma_f32_16x16x32_bf16 v[56:59], v[164:167], v[212:215], v[56:59]
	v_mfma_f32_16x16x32_bf16 v[44:47], v[156:159], v[220:223], v[44:47]
	v_mfma_f32_16x16x32_bf16 v[40:43], v[164:167], v[220:223], v[40:43]
	v_mfma_f32_16x16x32_bf16 v[28:31], v[156:159], v[228:231], v[28:31]
	v_mfma_f32_16x16x32_bf16 v[24:27], v[164:167], v[228:231], v[24:27]
	v_mfma_f32_16x16x32_bf16 v[12:15], v[156:159], v[236:239], v[12:15]
	v_mfma_f32_16x16x32_bf16 v[8:11], v[164:167], v[236:239], v[8:11]
	v_mfma_f32_16x16x32_bf16 v[52:55], v[168:171], v[208:211], v[52:55]
	v_mfma_f32_16x16x32_bf16 v[48:51], v[176:179], v[208:211], v[48:51]
	v_mfma_f32_16x16x32_bf16 v[36:39], v[168:171], v[216:219], v[36:39]
	v_mfma_f32_16x16x32_bf16 v[32:35], v[176:179], v[216:219], v[32:35]
	v_mfma_f32_16x16x32_bf16 v[20:23], v[168:171], v[224:227], v[20:23]
	v_mfma_f32_16x16x32_bf16 v[16:19], v[176:179], v[224:227], v[16:19]
	v_mfma_f32_16x16x32_bf16 v[4:7], v[168:171], v[232:235], v[4:7]
	v_mfma_f32_16x16x32_bf16 v[0:3], v[176:179], v[232:235], v[0:3]
	v_mfma_f32_16x16x32_bf16 v[52:55], v[172:175], v[212:215], v[52:55]
	v_mfma_f32_16x16x32_bf16 v[48:51], v[204:207], v[212:215], v[48:51]
	v_mfma_f32_16x16x32_bf16 v[36:39], v[172:175], v[220:223], v[36:39]
	v_mfma_f32_16x16x32_bf16 v[32:35], v[204:207], v[220:223], v[32:35]
	v_mfma_f32_16x16x32_bf16 v[20:23], v[172:175], v[228:231], v[20:23]
	v_mfma_f32_16x16x32_bf16 v[16:19], v[204:207], v[228:231], v[16:19]
	v_mfma_f32_16x16x32_bf16 v[4:7], v[172:175], v[236:239], v[4:7]
	v_mfma_f32_16x16x32_bf16 v[0:3], v[204:207], v[236:239], v[0:3]
	s_barrier
	v_add_u32_e32 v164, 0x18000, v143
	v_add_u32_e32 v204, 0x1c000, v143
	ds_read_b128 v[138:141], v164
	ds_read_b128 v[156:159], v164 offset:1024
	ds_read_b128 v[160:163], v164 offset:2048
	ds_read_b128 v[164:167], v164 offset:3072
	ds_read_b128 v[168:171], v204
	ds_read_b128 v[172:175], v204 offset:1024
	ds_read_b128 v[176:179], v204 offset:2048
	ds_read_b128 v[204:207], v204 offset:3072
	ds_read_b128 v[208:211], v155 offset:32768
	ds_read_b128 v[212:215], v155 offset:33792
	ds_read_b128 v[216:219], v155 offset:34816
	ds_read_b128 v[220:223], v155 offset:35840
	ds_read_b128 v[224:227], v155 offset:36864
	ds_read_b128 v[228:231], v155 offset:37888
	ds_read_b128 v[232:235], v155 offset:38912
	ds_read_b128 v[236:239], v155 offset:39936
	s_add_i32 s74, 0, 0x18000
	s_add_i32 s75, 0, 0x1c000
	s_add_u32 s4, s60, 0x20000
	s_addc_u32 s5, s61, 0
	s_mov_b32 m0, s66
	v_lshl_add_u64 v[244:245], s[4:5], 0, v[128:129]
	global_load_lds_dwordx4 v[244:245], off
	s_mov_b32 m0, s67
	v_lshl_add_u64 v[244:245], s[4:5], 0, v[130:131]
	global_load_lds_dwordx4 v[244:245], off
	s_waitcnt vmcnt(8)
	s_waitcnt lgkmcnt(0)
	s_barrier
	v_mfma_f32_16x16x32_bf16 v[124:127], v[138:141], v[208:211], v[124:127]
	v_mfma_f32_16x16x32_bf16 v[120:123], v[160:163], v[208:211], v[120:123]
	v_mfma_f32_16x16x32_bf16 v[108:111], v[138:141], v[216:219], v[108:111]
	v_mfma_f32_16x16x32_bf16 v[104:107], v[160:163], v[216:219], v[104:107]
	v_mfma_f32_16x16x32_bf16 v[92:95], v[138:141], v[224:227], v[92:95]
	v_mfma_f32_16x16x32_bf16 v[88:91], v[160:163], v[224:227], v[88:91]
	v_mfma_f32_16x16x32_bf16 v[76:79], v[138:141], v[232:235], v[76:79]
	v_mfma_f32_16x16x32_bf16 v[72:75], v[160:163], v[232:235], v[72:75]
	v_mfma_f32_16x16x32_bf16 v[124:127], v[156:159], v[212:215], v[124:127]
	v_mfma_f32_16x16x32_bf16 v[120:123], v[164:167], v[212:215], v[120:123]
	v_mfma_f32_16x16x32_bf16 v[108:111], v[156:159], v[220:223], v[108:111]
	v_mfma_f32_16x16x32_bf16 v[104:107], v[164:167], v[220:223], v[104:107]
	v_mfma_f32_16x16x32_bf16 v[92:95], v[156:159], v[228:231], v[92:95]
	v_mfma_f32_16x16x32_bf16 v[88:91], v[164:167], v[228:231], v[88:91]
	v_mfma_f32_16x16x32_bf16 v[76:79], v[156:159], v[236:239], v[76:79]
	v_mfma_f32_16x16x32_bf16 v[72:75], v[164:167], v[236:239], v[72:75]
	v_mfma_f32_16x16x32_bf16 v[116:119], v[168:171], v[208:211], v[116:119]
	v_mfma_f32_16x16x32_bf16 v[112:115], v[176:179], v[208:211], v[112:115]
	v_mfma_f32_16x16x32_bf16 v[100:103], v[168:171], v[216:219], v[100:103]
	v_mfma_f32_16x16x32_bf16 v[96:99], v[176:179], v[216:219], v[96:99]
	v_mfma_f32_16x16x32_bf16 v[84:87], v[168:171], v[224:227], v[84:87]
	v_mfma_f32_16x16x32_bf16 v[80:83], v[176:179], v[224:227], v[80:83]
	v_mfma_f32_16x16x32_bf16 v[68:71], v[168:171], v[232:235], v[68:71]
	v_mfma_f32_16x16x32_bf16 v[64:67], v[176:179], v[232:235], v[64:67]
	v_mfma_f32_16x16x32_bf16 v[116:119], v[172:175], v[212:215], v[116:119]
	v_mfma_f32_16x16x32_bf16 v[112:115], v[204:207], v[212:215], v[112:115]
	v_mfma_f32_16x16x32_bf16 v[100:103], v[172:175], v[220:223], v[100:103]
	v_mfma_f32_16x16x32_bf16 v[96:99], v[204:207], v[220:223], v[96:99]
	v_mfma_f32_16x16x32_bf16 v[84:87], v[172:175], v[228:231], v[84:87]
	v_mfma_f32_16x16x32_bf16 v[80:83], v[204:207], v[228:231], v[80:83]
	v_mfma_f32_16x16x32_bf16 v[68:71], v[172:175], v[236:239], v[68:71]
	v_mfma_f32_16x16x32_bf16 v[64:67], v[204:207], v[236:239], v[64:67]
	s_barrier
	s_add_i32 s4, s74, s28
	v_lshl_add_u64 v[180:181], v[180:181], 0, s[26:27]
	s_mov_b32 m0, s4
	ds_read_b128 v[208:211], v155 offset:49152
	ds_read_b128 v[212:215], v155 offset:50176
	ds_read_b128 v[216:219], v155 offset:51200
	ds_read_b128 v[220:223], v155 offset:52224
	ds_read_b128 v[224:227], v155 offset:53248
	ds_read_b128 v[228:231], v155 offset:54272
	ds_read_b128 v[232:235], v155 offset:55296
	ds_read_b128 v[236:239], v155 offset:56320
	global_load_lds_dwordx4 v[180:181], off
	s_add_i32 m0, s4, 0x2000
	s_add_u32 s4, s34, 0x20080
	v_lshl_add_u64 v[180:181], v[202:203], 0, s[26:27]
	s_addc_u32 s5, s35, 0
	s_add_i32 s34, s75, s28
	global_load_lds_dwordx4 v[180:181], off
	s_mov_b32 m0, s34
	v_lshl_add_u64 v[180:181], s[4:5], 0, v[144:145]
	global_load_lds_dwordx4 v[180:181], off
	s_add_i32 m0, s34, 0x2000
	v_lshl_add_u64 v[180:181], s[4:5], 0, v[132:133]
	global_load_lds_dwordx4 v[180:181], off
	s_mov_b32 m0, s68
	v_lshl_add_u64 v[180:181], v[240:241], 0, s[26:27]
	global_load_lds_dwordx4 v[180:181], off
	s_mov_b32 m0, s69
	v_lshl_add_u64 v[180:181], v[242:243], 0, s[26:27]
	global_load_lds_dwordx4 v[180:181], off
	s_add_i32 s73, s73, 2
	s_add_u32 s58, s58, 0x100
	s_addc_u32 s59, s59, 0
	s_add_u32 s71, s71, 0x100
	s_addc_u32 s72, s72, 0
	s_cmp_gt_u32 s73, 5
	s_waitcnt vmcnt(8)
	s_waitcnt lgkmcnt(0)
	s_barrier
	v_mfma_f32_16x16x32_bf16 v[60:63], v[138:141], v[208:211], v[60:63]
	v_mfma_f32_16x16x32_bf16 v[56:59], v[160:163], v[208:211], v[56:59]
	v_mfma_f32_16x16x32_bf16 v[44:47], v[138:141], v[216:219], v[44:47]
	v_mfma_f32_16x16x32_bf16 v[40:43], v[160:163], v[216:219], v[40:43]
	v_mfma_f32_16x16x32_bf16 v[28:31], v[138:141], v[224:227], v[28:31]
	v_mfma_f32_16x16x32_bf16 v[24:27], v[160:163], v[224:227], v[24:27]
	v_mfma_f32_16x16x32_bf16 v[12:15], v[138:141], v[232:235], v[12:15]
	v_mfma_f32_16x16x32_bf16 v[8:11], v[160:163], v[232:235], v[8:11]
	v_mfma_f32_16x16x32_bf16 v[60:63], v[156:159], v[212:215], v[60:63]
	v_mfma_f32_16x16x32_bf16 v[56:59], v[164:167], v[212:215], v[56:59]
	v_mfma_f32_16x16x32_bf16 v[44:47], v[156:159], v[220:223], v[44:47]
	v_mfma_f32_16x16x32_bf16 v[40:43], v[164:167], v[220:223], v[40:43]
	v_mfma_f32_16x16x32_bf16 v[28:31], v[156:159], v[228:231], v[28:31]
	v_mfma_f32_16x16x32_bf16 v[24:27], v[164:167], v[228:231], v[24:27]
	v_mfma_f32_16x16x32_bf16 v[12:15], v[156:159], v[236:239], v[12:15]
	v_mfma_f32_16x16x32_bf16 v[8:11], v[164:167], v[236:239], v[8:11]
	v_mfma_f32_16x16x32_bf16 v[52:55], v[168:171], v[208:211], v[52:55]
	v_mfma_f32_16x16x32_bf16 v[48:51], v[176:179], v[208:211], v[48:51]
	v_mfma_f32_16x16x32_bf16 v[36:39], v[168:171], v[216:219], v[36:39]
	v_mfma_f32_16x16x32_bf16 v[32:35], v[176:179], v[216:219], v[32:35]
	v_mfma_f32_16x16x32_bf16 v[20:23], v[168:171], v[224:227], v[20:23]
	v_mfma_f32_16x16x32_bf16 v[16:19], v[176:179], v[224:227], v[16:19]
	v_mfma_f32_16x16x32_bf16 v[4:7], v[168:171], v[232:235], v[4:7]
	v_mfma_f32_16x16x32_bf16 v[0:3], v[176:179], v[232:235], v[0:3]
	v_mfma_f32_16x16x32_bf16 v[52:55], v[172:175], v[212:215], v[52:55]
	v_mfma_f32_16x16x32_bf16 v[48:51], v[204:207], v[212:215], v[48:51]
	v_mfma_f32_16x16x32_bf16 v[36:39], v[172:175], v[220:223], v[36:39]
	v_mfma_f32_16x16x32_bf16 v[32:35], v[204:207], v[220:223], v[32:35]
	v_mfma_f32_16x16x32_bf16 v[20:23], v[172:175], v[228:231], v[20:23]
	v_mfma_f32_16x16x32_bf16 v[16:19], v[204:207], v[228:231], v[16:19]
	v_mfma_f32_16x16x32_bf16 v[4:7], v[172:175], v[236:239], v[4:7]
	v_mfma_f32_16x16x32_bf16 v[0:3], v[204:207], v[236:239], v[0:3]
	s_barrier
	s_cbranch_scc0 .LBB0_1093
	s_and_b64 vcc, exec, s[46:47]
	s_cbranch_vccz .LBB0_1096
	s_barrier

.LBB0_1117:
	v_add_u32_e32 v164, 0x10000, v143
	v_add_u32_e32 v180, 0x14000, v143
	ds_read_b128 v[138:141], v164
	ds_read_b128 v[156:159], v164 offset:1024
	ds_read_b128 v[160:163], v164 offset:2048
	ds_read_b128 v[164:167], v164 offset:3072
	ds_read_b128 v[168:171], v180
	ds_read_b128 v[172:175], v180 offset:1024
	ds_read_b128 v[176:179], v180 offset:2048
	ds_read_b128 v[204:207], v180 offset:3072
	ds_read_b128 v[208:211], v155
	ds_read_b128 v[212:215], v155 offset:1024
	ds_read_b128 v[216:219], v155 offset:2048
	ds_read_b128 v[220:223], v155 offset:3072
	ds_read_b128 v[224:227], v155 offset:4096
	ds_read_b128 v[228:231], v155 offset:5120
	ds_read_b128 v[232:235], v155 offset:6144
	ds_read_b128 v[236:239], v155 offset:7168
	s_add_u32 s4, s54, 0xfffe0080
	s_addc_u32 s5, s55, -1
	s_add_i32 s74, 0, 0x10000
	s_cmp_eq_u32 s73, 4
	s_cselect_b32 s59, s33, s5
	s_cselect_b32 s58, s36, s4
	s_cselect_b32 s35, s47, s72
	s_cselect_b32 s34, s49, s71
	s_add_i32 s75, 0, 0x14000
	s_add_i32 m0, s64, 0xc000
	v_lshl_add_u64 v[180:181], s[54:55], 0, v[134:135]
	global_load_lds_dwordx4 v[180:181], off
	s_add_i32 m0, s64, 0xe000
	v_lshl_add_u64 v[180:181], s[54:55], 0, v[136:137]
	global_load_lds_dwordx4 v[180:181], off
	s_waitcnt vmcnt(8)
	s_waitcnt lgkmcnt(0)
	s_barrier
	v_mfma_f32_16x16x32_bf16 v[124:127], v[138:141], v[208:211], v[124:127]
	v_mfma_f32_16x16x32_bf16 v[120:123], v[160:163], v[208:211], v[120:123]
	v_mfma_f32_16x16x32_bf16 v[108:111], v[138:141], v[216:219], v[108:111]
	v_mfma_f32_16x16x32_bf16 v[104:107], v[160:163], v[216:219], v[104:107]
	v_mfma_f32_16x16x32_bf16 v[92:95], v[138:141], v[224:227], v[92:95]
	v_mfma_f32_16x16x32_bf16 v[88:91], v[160:163], v[224:227], v[88:91]
	v_mfma_f32_16x16x32_bf16 v[76:79], v[138:141], v[232:235], v[76:79]
	v_mfma_f32_16x16x32_bf16 v[72:75], v[160:163], v[232:235], v[72:75]
	v_mfma_f32_16x16x32_bf16 v[124:127], v[156:159], v[212:215], v[124:127]
	v_mfma_f32_16x16x32_bf16 v[120:123], v[164:167], v[212:215], v[120:123]
	v_mfma_f32_16x16x32_bf16 v[108:111], v[156:159], v[220:223], v[108:111]
	v_mfma_f32_16x16x32_bf16 v[104:107], v[164:167], v[220:223], v[104:107]
	v_mfma_f32_16x16x32_bf16 v[92:95], v[156:159], v[228:231], v[92:95]
	v_mfma_f32_16x16x32_bf16 v[88:91], v[164:167], v[228:231], v[88:91]
	v_mfma_f32_16x16x32_bf16 v[76:79], v[156:159], v[236:239], v[76:79]
	v_mfma_f32_16x16x32_bf16 v[72:75], v[164:167], v[236:239], v[72:75]
	v_mfma_f32_16x16x32_bf16 v[116:119], v[168:171], v[208:211], v[116:119]
	v_mfma_f32_16x16x32_bf16 v[112:115], v[176:179], v[208:211], v[112:115]
	v_mfma_f32_16x16x32_bf16 v[100:103], v[168:171], v[216:219], v[100:103]
	v_mfma_f32_16x16x32_bf16 v[96:99], v[176:179], v[216:219], v[96:99]
	v_mfma_f32_16x16x32_bf16 v[84:87], v[168:171], v[224:227], v[84:87]
	v_mfma_f32_16x16x32_bf16 v[80:83], v[176:179], v[224:227], v[80:83]
	v_mfma_f32_16x16x32_bf16 v[68:71], v[168:171], v[232:235], v[68:71]
	v_mfma_f32_16x16x32_bf16 v[64:67], v[176:179], v[232:235], v[64:67]
	v_mfma_f32_16x16x32_bf16 v[116:119], v[172:175], v[212:215], v[116:119]
	v_mfma_f32_16x16x32_bf16 v[112:115], v[204:207], v[212:215], v[112:115]
	v_mfma_f32_16x16x32_bf16 v[100:103], v[172:175], v[220:223], v[100:103]
	v_mfma_f32_16x16x32_bf16 v[96:99], v[204:207], v[220:223], v[96:99]
	v_mfma_f32_16x16x32_bf16 v[84:87], v[172:175], v[228:231], v[84:87]
	v_mfma_f32_16x16x32_bf16 v[80:83], v[204:207], v[228:231], v[80:83]
	v_mfma_f32_16x16x32_bf16 v[68:71], v[172:175], v[236:239], v[68:71]
	v_mfma_f32_16x16x32_bf16 v[64:67], v[204:207], v[236:239], v[64:67]
	s_barrier
	s_add_i32 s4, s74, s63
	v_lshl_add_u64 v[180:181], s[34:35], 0, v[144:145]
	s_mov_b32 m0, s4
	ds_read_b128 v[208:211], v155 offset:16384
	ds_read_b128 v[212:215], v155 offset:17408
	ds_read_b128 v[216:219], v155 offset:18432
	ds_read_b128 v[220:223], v155 offset:19456
	ds_read_b128 v[224:227], v155 offset:20480
	ds_read_b128 v[228:231], v155 offset:21504
	ds_read_b128 v[232:235], v155 offset:22528
	ds_read_b128 v[236:239], v155 offset:23552
	global_load_lds_dwordx4 v[180:181], off
	s_add_i32 m0, s4, 0x2000
	s_add_u32 s4, s34, 0x20000
	v_lshl_add_u64 v[202:203], s[34:35], 0, v[132:133]
	s_addc_u32 s5, s35, 0
	s_add_i32 s74, s75, s63
	global_load_lds_dwordx4 v[202:203], off
	v_lshl_add_u64 v[240:241], s[4:5], 0, v[144:145]
	s_mov_b32 m0, s74
	v_lshl_add_u64 v[242:243], s[58:59], 0, v[130:131]
	global_load_lds_dwordx4 v[240:241], off
	s_add_i32 m0, s74, 0x2000
	v_lshl_add_u64 v[240:241], s[4:5], 0, v[132:133]
	global_load_lds_dwordx4 v[240:241], off
	s_mov_b32 m0, s64
	v_lshl_add_u64 v[240:241], s[58:59], 0, v[128:129]
	global_load_lds_dwordx4 v[240:241], off
	s_mov_b32 m0, s65
	s_nop 0
	global_load_lds_dwordx4 v[242:243], off
	s_waitcnt vmcnt(8)
	s_waitcnt lgkmcnt(0)
	s_barrier
	v_mfma_f32_16x16x32_bf16 v[60:63], v[138:141], v[208:211], v[60:63]
	v_mfma_f32_16x16x32_bf16 v[56:59], v[160:163], v[208:211], v[56:59]
	v_mfma_f32_16x16x32_bf16 v[44:47], v[138:141], v[216:219], v[44:47]
	v_mfma_f32_16x16x32_bf16 v[40:43], v[160:163], v[216:219], v[40:43]
	v_mfma_f32_16x16x32_bf16 v[28:31], v[138:141], v[224:227], v[28:31]
	v_mfma_f32_16x16x32_bf16 v[24:27], v[160:163], v[224:227], v[24:27]
	v_mfma_f32_16x16x32_bf16 v[12:15], v[138:141], v[232:235], v[12:15]
	v_mfma_f32_16x16x32_bf16 v[8:11], v[160:163], v[232:235], v[8:11]
	v_mfma_f32_16x16x32_bf16 v[60:63], v[156:159], v[212:215], v[60:63]
	v_mfma_f32_16x16x32_bf16 v[56:59], v[164:167], v[212:215], v[56:59]
	v_mfma_f32_16x16x32_bf16 v[44:47], v[156:159], v[220:223], v[44:47]
	v_mfma_f32_16x16x32_bf16 v[40:43], v[164:167], v[220:223], v[40:43]
	v_mfma_f32_16x16x32_bf16 v[28:31], v[156:159], v[228:231], v[28:31]
	v_mfma_f32_16x16x32_bf16 v[24:27], v[164:167], v[228:231], v[24:27]
	v_mfma_f32_16x16x32_bf16 v[12:15], v[156:159], v[236:239], v[12:15]
	v_mfma_f32_16x16x32_bf16 v[8:11], v[164:167], v[236:239], v[8:11]
	v_mfma_f32_16x16x32_bf16 v[52:55], v[168:171], v[208:211], v[52:55]
	v_mfma_f32_16x16x32_bf16 v[48:51], v[176:179], v[208:211], v[48:51]
	v_mfma_f32_16x16x32_bf16 v[36:39], v[168:171], v[216:219], v[36:39]
	v_mfma_f32_16x16x32_bf16 v[32:35], v[176:179], v[216:219], v[32:35]
	v_mfma_f32_16x16x32_bf16 v[20:23], v[168:171], v[224:227], v[20:23]
	v_mfma_f32_16x16x32_bf16 v[16:19], v[176:179], v[224:227], v[16:19]
	v_mfma_f32_16x16x32_bf16 v[4:7], v[168:171], v[232:235], v[4:7]
	v_mfma_f32_16x16x32_bf16 v[0:3], v[176:179], v[232:235], v[0:3]
	v_mfma_f32_16x16x32_bf16 v[52:55], v[172:175], v[212:215], v[52:55]
	v_mfma_f32_16x16x32_bf16 v[48:51], v[204:207], v[212:215], v[48:51]
	v_mfma_f32_16x16x32_bf16 v[36:39], v[172:175], v[220:223], v[36:39]
	v_mfma_f32_16x16x32_bf16 v[32:35], v[204:207], v[220:223], v[32:35]
	v_mfma_f32_16x16x32_bf16 v[20:23], v[172:175], v[228:231], v[20:23]
	v_mfma_f32_16x16x32_bf16 v[16:19], v[204:207], v[228:231], v[16:19]
	v_mfma_f32_16x16x32_bf16 v[4:7], v[172:175], v[236:239], v[4:7]
	v_mfma_f32_16x16x32_bf16 v[0:3], v[204:207], v[236:239], v[0:3]
	s_barrier
	v_add_u32_e32 v164, 0x18000, v143
	v_add_u32_e32 v204, 0x1c000, v143
	ds_read_b128 v[138:141], v164
	ds_read_b128 v[156:159], v164 offset:1024
	ds_read_b128 v[160:163], v164 offset:2048
	ds_read_b128 v[164:167], v164 offset:3072
	ds_read_b128 v[168:171], v204
	ds_read_b128 v[172:175], v204 offset:1024
	ds_read_b128 v[176:179], v204 offset:2048
	ds_read_b128 v[204:207], v204 offset:3072
	ds_read_b128 v[208:211], v155 offset:32768
	ds_read_b128 v[212:215], v155 offset:33792
	ds_read_b128 v[216:219], v155 offset:34816
	ds_read_b128 v[220:223], v155 offset:35840
	ds_read_b128 v[224:227], v155 offset:36864
	ds_read_b128 v[228:231], v155 offset:37888
	ds_read_b128 v[232:235], v155 offset:38912
	ds_read_b128 v[236:239], v155 offset:39936
	s_add_i32 s74, 0, 0x18000
	s_add_i32 s75, 0, 0x1c000
	s_add_u32 s4, s58, 0x20000
	s_addc_u32 s5, s59, 0
	s_mov_b32 m0, s66
	v_lshl_add_u64 v[244:245], s[4:5], 0, v[128:129]
	global_load_lds_dwordx4 v[244:245], off
	s_mov_b32 m0, s67
	v_lshl_add_u64 v[244:245], s[4:5], 0, v[130:131]
	global_load_lds_dwordx4 v[244:245], off
	s_waitcnt vmcnt(8)
	s_waitcnt lgkmcnt(0)
	s_barrier
	v_mfma_f32_16x16x32_bf16 v[124:127], v[138:141], v[208:211], v[124:127]
	v_mfma_f32_16x16x32_bf16 v[120:123], v[160:163], v[208:211], v[120:123]
	v_mfma_f32_16x16x32_bf16 v[108:111], v[138:141], v[216:219], v[108:111]
	v_mfma_f32_16x16x32_bf16 v[104:107], v[160:163], v[216:219], v[104:107]
	v_mfma_f32_16x16x32_bf16 v[92:95], v[138:141], v[224:227], v[92:95]
	v_mfma_f32_16x16x32_bf16 v[88:91], v[160:163], v[224:227], v[88:91]
	v_mfma_f32_16x16x32_bf16 v[76:79], v[138:141], v[232:235], v[76:79]
	v_mfma_f32_16x16x32_bf16 v[72:75], v[160:163], v[232:235], v[72:75]
	v_mfma_f32_16x16x32_bf16 v[124:127], v[156:159], v[212:215], v[124:127]
	v_mfma_f32_16x16x32_bf16 v[120:123], v[164:167], v[212:215], v[120:123]
	v_mfma_f32_16x16x32_bf16 v[108:111], v[156:159], v[220:223], v[108:111]
	v_mfma_f32_16x16x32_bf16 v[104:107], v[164:167], v[220:223], v[104:107]
	v_mfma_f32_16x16x32_bf16 v[92:95], v[156:159], v[228:231], v[92:95]
	v_mfma_f32_16x16x32_bf16 v[88:91], v[164:167], v[228:231], v[88:91]
	v_mfma_f32_16x16x32_bf16 v[76:79], v[156:159], v[236:239], v[76:79]
	v_mfma_f32_16x16x32_bf16 v[72:75], v[164:167], v[236:239], v[72:75]
	v_mfma_f32_16x16x32_bf16 v[116:119], v[168:171], v[208:211], v[116:119]
	v_mfma_f32_16x16x32_bf16 v[112:115], v[176:179], v[208:211], v[112:115]
	v_mfma_f32_16x16x32_bf16 v[100:103], v[168:171], v[216:219], v[100:103]
	v_mfma_f32_16x16x32_bf16 v[96:99], v[176:179], v[216:219], v[96:99]
	v_mfma_f32_16x16x32_bf16 v[84:87], v[168:171], v[224:227], v[84:87]
	v_mfma_f32_16x16x32_bf16 v[80:83], v[176:179], v[224:227], v[80:83]
	v_mfma_f32_16x16x32_bf16 v[68:71], v[168:171], v[232:235], v[68:71]
	v_mfma_f32_16x16x32_bf16 v[64:67], v[176:179], v[232:235], v[64:67]
	v_mfma_f32_16x16x32_bf16 v[116:119], v[172:175], v[212:215], v[116:119]
	v_mfma_f32_16x16x32_bf16 v[112:115], v[204:207], v[212:215], v[112:115]
	v_mfma_f32_16x16x32_bf16 v[100:103], v[172:175], v[220:223], v[100:103]
	v_mfma_f32_16x16x32_bf16 v[96:99], v[204:207], v[220:223], v[96:99]
	v_mfma_f32_16x16x32_bf16 v[84:87], v[172:175], v[228:231], v[84:87]
	v_mfma_f32_16x16x32_bf16 v[80:83], v[204:207], v[228:231], v[80:83]
	v_mfma_f32_16x16x32_bf16 v[68:71], v[172:175], v[236:239], v[68:71]
	v_mfma_f32_16x16x32_bf16 v[64:67], v[204:207], v[236:239], v[64:67]
	s_barrier
	s_add_i32 s4, s74, s63
	v_lshl_add_u64 v[180:181], v[180:181], 0, s[26:27]
	s_mov_b32 m0, s4
	ds_read_b128 v[208:211], v155 offset:49152
	ds_read_b128 v[212:215], v155 offset:50176
	ds_read_b128 v[216:219], v155 offset:51200
	ds_read_b128 v[220:223], v155 offset:52224
	ds_read_b128 v[224:227], v155 offset:53248
	ds_read_b128 v[228:231], v155 offset:54272
	ds_read_b128 v[232:235], v155 offset:55296
	ds_read_b128 v[236:239], v155 offset:56320
	global_load_lds_dwordx4 v[180:181], off
	s_add_i32 m0, s4, 0x2000
	s_add_u32 s4, s34, 0x20080
	v_lshl_add_u64 v[180:181], v[202:203], 0, s[26:27]
	s_addc_u32 s5, s35, 0
	s_add_i32 s34, s75, s63
	global_load_lds_dwordx4 v[180:181], off
	s_mov_b32 m0, s34
	v_lshl_add_u64 v[180:181], s[4:5], 0, v[144:145]
	global_load_lds_dwordx4 v[180:181], off
	s_add_i32 m0, s34, 0x2000
	v_lshl_add_u64 v[180:181], s[4:5], 0, v[132:133]
	global_load_lds_dwordx4 v[180:181], off
	s_mov_b32 m0, s68
	v_lshl_add_u64 v[180:181], v[240:241], 0, s[26:27]
	global_load_lds_dwordx4 v[180:181], off
	s_mov_b32 m0, s69
	v_lshl_add_u64 v[180:181], v[242:243], 0, s[26:27]
	global_load_lds_dwordx4 v[180:181], off
	s_add_i32 s73, s73, 2
	s_add_u32 s54, s54, 0x100
	s_addc_u32 s55, s55, 0
	s_add_u32 s71, s71, 0x100
	s_addc_u32 s72, s72, 0
	s_cmp_gt_u32 s73, 5
	s_waitcnt vmcnt(8)
	s_waitcnt lgkmcnt(0)
	s_barrier
	v_mfma_f32_16x16x32_bf16 v[60:63], v[138:141], v[208:211], v[60:63]
	v_mfma_f32_16x16x32_bf16 v[56:59], v[160:163], v[208:211], v[56:59]
	v_mfma_f32_16x16x32_bf16 v[44:47], v[138:141], v[216:219], v[44:47]
	v_mfma_f32_16x16x32_bf16 v[40:43], v[160:163], v[216:219], v[40:43]
	v_mfma_f32_16x16x32_bf16 v[28:31], v[138:141], v[224:227], v[28:31]
	v_mfma_f32_16x16x32_bf16 v[24:27], v[160:163], v[224:227], v[24:27]
	v_mfma_f32_16x16x32_bf16 v[12:15], v[138:141], v[232:235], v[12:15]
	v_mfma_f32_16x16x32_bf16 v[8:11], v[160:163], v[232:235], v[8:11]
	v_mfma_f32_16x16x32_bf16 v[60:63], v[156:159], v[212:215], v[60:63]
	v_mfma_f32_16x16x32_bf16 v[56:59], v[164:167], v[212:215], v[56:59]
	v_mfma_f32_16x16x32_bf16 v[44:47], v[156:159], v[220:223], v[44:47]
	v_mfma_f32_16x16x32_bf16 v[40:43], v[164:167], v[220:223], v[40:43]
	v_mfma_f32_16x16x32_bf16 v[28:31], v[156:159], v[228:231], v[28:31]
	v_mfma_f32_16x16x32_bf16 v[24:27], v[164:167], v[228:231], v[24:27]
	v_mfma_f32_16x16x32_bf16 v[12:15], v[156:159], v[236:239], v[12:15]
	v_mfma_f32_16x16x32_bf16 v[8:11], v[164:167], v[236:239], v[8:11]
	v_mfma_f32_16x16x32_bf16 v[52:55], v[168:171], v[208:211], v[52:55]
	v_mfma_f32_16x16x32_bf16 v[48:51], v[176:179], v[208:211], v[48:51]
	v_mfma_f32_16x16x32_bf16 v[36:39], v[168:171], v[216:219], v[36:39]
	v_mfma_f32_16x16x32_bf16 v[32:35], v[176:179], v[216:219], v[32:35]
	v_mfma_f32_16x16x32_bf16 v[20:23], v[168:171], v[224:227], v[20:23]
	v_mfma_f32_16x16x32_bf16 v[16:19], v[176:179], v[224:227], v[16:19]
	v_mfma_f32_16x16x32_bf16 v[4:7], v[168:171], v[232:235], v[4:7]
	v_mfma_f32_16x16x32_bf16 v[0:3], v[176:179], v[232:235], v[0:3]
	v_mfma_f32_16x16x32_bf16 v[52:55], v[172:175], v[212:215], v[52:55]
	v_mfma_f32_16x16x32_bf16 v[48:51], v[204:207], v[212:215], v[48:51]
	v_mfma_f32_16x16x32_bf16 v[36:39], v[172:175], v[220:223], v[36:39]
	v_mfma_f32_16x16x32_bf16 v[32:35], v[204:207], v[220:223], v[32:35]
	v_mfma_f32_16x16x32_bf16 v[20:23], v[172:175], v[228:231], v[20:23]
	v_mfma_f32_16x16x32_bf16 v[16:19], v[204:207], v[228:231], v[16:19]
	v_mfma_f32_16x16x32_bf16 v[4:7], v[172:175], v[236:239], v[4:7]
	v_mfma_f32_16x16x32_bf16 v[0:3], v[204:207], v[236:239], v[0:3]
	s_barrier
	s_cbranch_scc0 .LBB0_1117
	s_and_b64 vcc, exec, s[44:45]
	s_cbranch_vccz .LBB0_1120
	s_barrier

.LBB0_1207:
	v_add_u32_e32 v142, 0x10000, v160
	ds_read_b128 v[138:141], v142
	ds_read_b128 v[154:157], v142 offset:1024
	ds_read_b128 v[172:175], v142 offset:2048
	ds_read_b128 v[176:179], v142 offset:3072
	v_add_u32_e32 v142, 0x14000, v160
	ds_read_b128 v[204:207], v142
	ds_read_b128 v[208:211], v142 offset:1024
	ds_read_b128 v[212:215], v142 offset:2048
	ds_read_b128 v[216:219], v142 offset:3072
	ds_read_b128 v[220:223], v170
	ds_read_b128 v[224:227], v170 offset:1024
	ds_read_b128 v[228:231], v170 offset:2048
	ds_read_b128 v[232:235], v170 offset:3072
	ds_read_b128 v[236:239], v170 offset:4096
	ds_read_b128 v[240:243], v170 offset:5120
	ds_read_b128 v[244:247], v170 offset:6144
	ds_read_b128 v[248:251], v170 offset:7168
	s_add_u32 s62, s60, 0x100
	s_addc_u32 s63, s61, 0
	s_add_i32 s4, 0, 0x10000
	s_cmp_eq_u32 s29, 12
	s_cselect_b32 s65, s55, s63
	s_cselect_b32 s64, s54, s62
	s_cselect_b32 s35, s59, s28
	s_cselect_b32 s34, s58, s3
	s_add_i32 s45, 0, 0x14000
	s_add_i32 m0, s69, 0xc000
	v_lshl_add_u64 v[142:143], s[60:61], 0, v[134:135]
	global_load_lds_dwordx4 v[142:143], off
	s_add_i32 m0, s69, 0xe000
	v_lshl_add_u64 v[142:143], s[60:61], 0, v[136:137]
	global_load_lds_dwordx4 v[142:143], off
	s_waitcnt vmcnt(8)
	s_waitcnt lgkmcnt(0)
	s_barrier
	v_mfma_f32_16x16x32_bf16 v[124:127], v[138:141], v[220:223], v[124:127]
	v_mfma_f32_16x16x32_bf16 v[120:123], v[172:175], v[220:223], v[120:123]
	v_mfma_f32_16x16x32_bf16 v[108:111], v[138:141], v[228:231], v[108:111]
	v_mfma_f32_16x16x32_bf16 v[104:107], v[172:175], v[228:231], v[104:107]
	v_mfma_f32_16x16x32_bf16 v[92:95], v[138:141], v[236:239], v[92:95]
	v_mfma_f32_16x16x32_bf16 v[88:91], v[172:175], v[236:239], v[88:91]
	v_mfma_f32_16x16x32_bf16 v[76:79], v[138:141], v[244:247], v[76:79]
	v_mfma_f32_16x16x32_bf16 v[72:75], v[172:175], v[244:247], v[72:75]
	v_mfma_f32_16x16x32_bf16 v[124:127], v[154:157], v[224:227], v[124:127]
	v_mfma_f32_16x16x32_bf16 v[120:123], v[176:179], v[224:227], v[120:123]
	v_mfma_f32_16x16x32_bf16 v[108:111], v[154:157], v[232:235], v[108:111]
	v_mfma_f32_16x16x32_bf16 v[104:107], v[176:179], v[232:235], v[104:107]
	v_mfma_f32_16x16x32_bf16 v[92:95], v[154:157], v[240:243], v[92:95]
	v_mfma_f32_16x16x32_bf16 v[88:91], v[176:179], v[240:243], v[88:91]
	v_mfma_f32_16x16x32_bf16 v[76:79], v[154:157], v[248:251], v[76:79]
	v_mfma_f32_16x16x32_bf16 v[72:75], v[176:179], v[248:251], v[72:75]
	v_mfma_f32_16x16x32_bf16 v[116:119], v[204:207], v[220:223], v[116:119]
	v_mfma_f32_16x16x32_bf16 v[112:115], v[212:215], v[220:223], v[112:115]
	v_mfma_f32_16x16x32_bf16 v[100:103], v[204:207], v[228:231], v[100:103]
	v_mfma_f32_16x16x32_bf16 v[96:99], v[212:215], v[228:231], v[96:99]
	v_mfma_f32_16x16x32_bf16 v[84:87], v[204:207], v[236:239], v[84:87]
	v_mfma_f32_16x16x32_bf16 v[80:83], v[212:215], v[236:239], v[80:83]
	v_mfma_f32_16x16x32_bf16 v[68:71], v[204:207], v[244:247], v[68:71]
	v_mfma_f32_16x16x32_bf16 v[64:67], v[212:215], v[244:247], v[64:67]
	v_mfma_f32_16x16x32_bf16 v[116:119], v[208:211], v[224:227], v[116:119]
	v_mfma_f32_16x16x32_bf16 v[112:115], v[216:219], v[224:227], v[112:115]
	v_mfma_f32_16x16x32_bf16 v[100:103], v[208:211], v[232:235], v[100:103]
	v_mfma_f32_16x16x32_bf16 v[96:99], v[216:219], v[232:235], v[96:99]
	v_mfma_f32_16x16x32_bf16 v[84:87], v[208:211], v[240:243], v[84:87]
	v_mfma_f32_16x16x32_bf16 v[80:83], v[216:219], v[240:243], v[80:83]
	v_mfma_f32_16x16x32_bf16 v[68:71], v[208:211], v[248:251], v[68:71]
	v_mfma_f32_16x16x32_bf16 v[64:67], v[216:219], v[248:251], v[64:67]
	s_barrier
	s_add_i32 s4, s4, s33
	v_lshl_add_u64 v[142:143], s[34:35], 0, v[128:129]
	s_mov_b32 m0, s4
	ds_read_b128 v[220:223], v170 offset:16384
	ds_read_b128 v[224:227], v170 offset:17408
	ds_read_b128 v[228:231], v170 offset:18432
	ds_read_b128 v[232:235], v170 offset:19456
	ds_read_b128 v[236:239], v170 offset:20480
	ds_read_b128 v[240:243], v170 offset:21504
	ds_read_b128 v[244:247], v170 offset:22528
	ds_read_b128 v[248:251], v170 offset:23552
	global_load_lds_dwordx4 v[142:143], off
	s_add_i32 m0, s4, 0x2000
	s_add_u32 s4, s34, 0x40000
	v_lshl_add_u64 v[158:159], s[34:35], 0, v[130:131]
	s_addc_u32 s5, s35, 0
	s_add_i32 s45, s45, s33
	global_load_lds_dwordx4 v[158:159], off
	v_lshl_add_u64 v[180:181], s[4:5], 0, v[128:129]
	s_mov_b32 m0, s45
	v_lshl_add_u64 v[202:203], s[64:65], 0, v[130:131]
	global_load_lds_dwordx4 v[180:181], off
	s_add_i32 m0, s45, 0x2000
	v_lshl_add_u64 v[180:181], s[4:5], 0, v[130:131]
	global_load_lds_dwordx4 v[180:181], off
	s_mov_b32 m0, s69
	v_lshl_add_u64 v[180:181], s[64:65], 0, v[128:129]
	global_load_lds_dwordx4 v[180:181], off
	s_mov_b32 m0, s70
	s_nop 0
	global_load_lds_dwordx4 v[202:203], off
	s_waitcnt vmcnt(8)
	s_waitcnt lgkmcnt(0)
	s_barrier
	v_mfma_f32_16x16x32_bf16 v[60:63], v[138:141], v[220:223], v[60:63]
	v_mfma_f32_16x16x32_bf16 v[56:59], v[172:175], v[220:223], v[56:59]
	v_mfma_f32_16x16x32_bf16 v[44:47], v[138:141], v[228:231], v[44:47]
	v_mfma_f32_16x16x32_bf16 v[40:43], v[172:175], v[228:231], v[40:43]
	v_mfma_f32_16x16x32_bf16 v[28:31], v[138:141], v[236:239], v[28:31]
	v_mfma_f32_16x16x32_bf16 v[24:27], v[172:175], v[236:239], v[24:27]
	v_mfma_f32_16x16x32_bf16 v[12:15], v[138:141], v[244:247], v[12:15]
	v_mfma_f32_16x16x32_bf16 v[8:11], v[172:175], v[244:247], v[8:11]
	v_mfma_f32_16x16x32_bf16 v[60:63], v[154:157], v[224:227], v[60:63]
	v_mfma_f32_16x16x32_bf16 v[56:59], v[176:179], v[224:227], v[56:59]
	v_mfma_f32_16x16x32_bf16 v[44:47], v[154:157], v[232:235], v[44:47]
	v_mfma_f32_16x16x32_bf16 v[40:43], v[176:179], v[232:235], v[40:43]
	v_mfma_f32_16x16x32_bf16 v[28:31], v[154:157], v[240:243], v[28:31]
	v_mfma_f32_16x16x32_bf16 v[24:27], v[176:179], v[240:243], v[24:27]
	v_mfma_f32_16x16x32_bf16 v[12:15], v[154:157], v[248:251], v[12:15]
	v_mfma_f32_16x16x32_bf16 v[8:11], v[176:179], v[248:251], v[8:11]
	v_mfma_f32_16x16x32_bf16 v[52:55], v[204:207], v[220:223], v[52:55]
	v_mfma_f32_16x16x32_bf16 v[48:51], v[212:215], v[220:223], v[48:51]
	v_mfma_f32_16x16x32_bf16 v[36:39], v[204:207], v[228:231], v[36:39]
	v_mfma_f32_16x16x32_bf16 v[32:35], v[212:215], v[228:231], v[32:35]
	v_mfma_f32_16x16x32_bf16 v[20:23], v[204:207], v[236:239], v[20:23]
	v_mfma_f32_16x16x32_bf16 v[16:19], v[212:215], v[236:239], v[16:19]
	v_mfma_f32_16x16x32_bf16 v[4:7], v[204:207], v[244:247], v[4:7]
	v_mfma_f32_16x16x32_bf16 v[0:3], v[212:215], v[244:247], v[0:3]
	v_mfma_f32_16x16x32_bf16 v[52:55], v[208:211], v[224:227], v[52:55]
	v_mfma_f32_16x16x32_bf16 v[48:51], v[216:219], v[224:227], v[48:51]
	v_mfma_f32_16x16x32_bf16 v[36:39], v[208:211], v[232:235], v[36:39]
	v_mfma_f32_16x16x32_bf16 v[32:35], v[216:219], v[232:235], v[32:35]
	v_mfma_f32_16x16x32_bf16 v[20:23], v[208:211], v[240:243], v[20:23]
	v_mfma_f32_16x16x32_bf16 v[16:19], v[216:219], v[240:243], v[16:19]
	v_mfma_f32_16x16x32_bf16 v[4:7], v[208:211], v[248:251], v[4:7]
	v_mfma_f32_16x16x32_bf16 v[0:3], v[216:219], v[248:251], v[0:3]
	s_barrier
	v_add_u32_e32 v144, 0x18000, v160
	ds_read_b128 v[138:141], v144
	ds_read_b128 v[154:157], v144 offset:1024
	ds_read_b128 v[172:175], v144 offset:2048
	ds_read_b128 v[176:179], v144 offset:3072
	v_add_u32_e32 v144, 0x1c000, v160
	ds_read_b128 v[204:207], v144
	ds_read_b128 v[208:211], v144 offset:1024
	ds_read_b128 v[212:215], v144 offset:2048
	ds_read_b128 v[216:219], v144 offset:3072
	ds_read_b128 v[220:223], v170 offset:32768
	ds_read_b128 v[224:227], v170 offset:33792
	ds_read_b128 v[228:231], v170 offset:34816
	ds_read_b128 v[232:235], v170 offset:35840
	ds_read_b128 v[236:239], v170 offset:36864
	ds_read_b128 v[240:243], v170 offset:37888
	ds_read_b128 v[244:247], v170 offset:38912
	ds_read_b128 v[248:251], v170 offset:39936
	s_add_i32 s45, 0, 0x18000
	s_add_i32 s51, 0, 0x1c000
	s_add_u32 s4, s64, 0x40000
	s_addc_u32 s5, s65, 0
	s_mov_b32 m0, s71
	v_lshl_add_u64 v[252:253], s[4:5], 0, v[128:129]
	global_load_lds_dwordx4 v[252:253], off
	s_mov_b32 m0, s72
	v_lshl_add_u64 v[252:253], s[4:5], 0, v[130:131]
	global_load_lds_dwordx4 v[252:253], off
	s_waitcnt vmcnt(8)
	s_waitcnt lgkmcnt(0)
	s_barrier
	v_mfma_f32_16x16x32_bf16 v[124:127], v[138:141], v[220:223], v[124:127]
	v_mfma_f32_16x16x32_bf16 v[120:123], v[172:175], v[220:223], v[120:123]
	v_mfma_f32_16x16x32_bf16 v[108:111], v[138:141], v[228:231], v[108:111]
	v_mfma_f32_16x16x32_bf16 v[104:107], v[172:175], v[228:231], v[104:107]
	v_mfma_f32_16x16x32_bf16 v[92:95], v[138:141], v[236:239], v[92:95]
	v_mfma_f32_16x16x32_bf16 v[88:91], v[172:175], v[236:239], v[88:91]
	v_mfma_f32_16x16x32_bf16 v[76:79], v[138:141], v[244:247], v[76:79]
	v_mfma_f32_16x16x32_bf16 v[72:75], v[172:175], v[244:247], v[72:75]
	v_mfma_f32_16x16x32_bf16 v[124:127], v[154:157], v[224:227], v[124:127]
	v_mfma_f32_16x16x32_bf16 v[120:123], v[176:179], v[224:227], v[120:123]
	v_mfma_f32_16x16x32_bf16 v[108:111], v[154:157], v[232:235], v[108:111]
	v_mfma_f32_16x16x32_bf16 v[104:107], v[176:179], v[232:235], v[104:107]
	v_mfma_f32_16x16x32_bf16 v[92:95], v[154:157], v[240:243], v[92:95]
	v_mfma_f32_16x16x32_bf16 v[88:91], v[176:179], v[240:243], v[88:91]
	v_mfma_f32_16x16x32_bf16 v[76:79], v[154:157], v[248:251], v[76:79]
	v_mfma_f32_16x16x32_bf16 v[72:75], v[176:179], v[248:251], v[72:75]
	v_mfma_f32_16x16x32_bf16 v[116:119], v[204:207], v[220:223], v[116:119]
	v_mfma_f32_16x16x32_bf16 v[112:115], v[212:215], v[220:223], v[112:115]
	v_mfma_f32_16x16x32_bf16 v[100:103], v[204:207], v[228:231], v[100:103]
	v_mfma_f32_16x16x32_bf16 v[96:99], v[212:215], v[228:231], v[96:99]
	v_mfma_f32_16x16x32_bf16 v[84:87], v[204:207], v[236:239], v[84:87]
	v_mfma_f32_16x16x32_bf16 v[80:83], v[212:215], v[236:239], v[80:83]
	v_mfma_f32_16x16x32_bf16 v[68:71], v[204:207], v[244:247], v[68:71]
	v_mfma_f32_16x16x32_bf16 v[64:67], v[212:215], v[244:247], v[64:67]
	v_mfma_f32_16x16x32_bf16 v[116:119], v[208:211], v[224:227], v[116:119]
	v_mfma_f32_16x16x32_bf16 v[112:115], v[216:219], v[224:227], v[112:115]
	v_mfma_f32_16x16x32_bf16 v[100:103], v[208:211], v[232:235], v[100:103]
	v_mfma_f32_16x16x32_bf16 v[96:99], v[216:219], v[232:235], v[96:99]
	v_mfma_f32_16x16x32_bf16 v[84:87], v[208:211], v[240:243], v[84:87]
	v_mfma_f32_16x16x32_bf16 v[80:83], v[216:219], v[240:243], v[80:83]
	v_mfma_f32_16x16x32_bf16 v[68:71], v[208:211], v[248:251], v[68:71]
	v_mfma_f32_16x16x32_bf16 v[64:67], v[216:219], v[248:251], v[64:67]
	s_barrier
	s_add_i32 s4, s45, s33
	v_lshl_add_u64 v[142:143], v[142:143], 0, s[26:27]
	s_mov_b32 m0, s4
	ds_read_b128 v[220:223], v170 offset:49152
	ds_read_b128 v[224:227], v170 offset:50176
	ds_read_b128 v[228:231], v170 offset:51200
	ds_read_b128 v[232:235], v170 offset:52224
	ds_read_b128 v[236:239], v170 offset:53248
	ds_read_b128 v[240:243], v170 offset:54272
	ds_read_b128 v[244:247], v170 offset:55296
	ds_read_b128 v[248:251], v170 offset:56320
	global_load_lds_dwordx4 v[142:143], off
	s_add_i32 m0, s4, 0x2000
	s_add_u32 s4, s34, 0x40080
	v_lshl_add_u64 v[142:143], v[158:159], 0, s[26:27]
	s_addc_u32 s5, s35, 0
	s_add_i32 s34, s51, s33
	global_load_lds_dwordx4 v[142:143], off
	s_mov_b32 m0, s34
	v_lshl_add_u64 v[142:143], s[4:5], 0, v[128:129]
	global_load_lds_dwordx4 v[142:143], off
	s_add_i32 m0, s34, 0x2000
	v_lshl_add_u64 v[142:143], s[4:5], 0, v[130:131]
	global_load_lds_dwordx4 v[142:143], off
	s_mov_b32 m0, s73
	v_lshl_add_u64 v[142:143], v[180:181], 0, s[26:27]
	global_load_lds_dwordx4 v[142:143], off
	s_mov_b32 m0, s74
	v_lshl_add_u64 v[142:143], v[202:203], 0, s[26:27]
	global_load_lds_dwordx4 v[142:143], off
	s_add_i32 s29, s29, 2
	s_add_u32 s3, s3, 0x100
	s_addc_u32 s28, s28, 0
	s_cmp_gt_u32 s29, 13
	s_mov_b64 s[60:61], s[62:63]
	s_waitcnt vmcnt(8)
	s_waitcnt lgkmcnt(0)
	s_barrier
	v_mfma_f32_16x16x32_bf16 v[60:63], v[138:141], v[220:223], v[60:63]
	v_mfma_f32_16x16x32_bf16 v[56:59], v[172:175], v[220:223], v[56:59]
	v_mfma_f32_16x16x32_bf16 v[44:47], v[138:141], v[228:231], v[44:47]
	v_mfma_f32_16x16x32_bf16 v[40:43], v[172:175], v[228:231], v[40:43]
	v_mfma_f32_16x16x32_bf16 v[28:31], v[138:141], v[236:239], v[28:31]
	v_mfma_f32_16x16x32_bf16 v[24:27], v[172:175], v[236:239], v[24:27]
	v_mfma_f32_16x16x32_bf16 v[12:15], v[138:141], v[244:247], v[12:15]
	v_mfma_f32_16x16x32_bf16 v[8:11], v[172:175], v[244:247], v[8:11]
	v_mfma_f32_16x16x32_bf16 v[60:63], v[154:157], v[224:227], v[60:63]
	v_mfma_f32_16x16x32_bf16 v[56:59], v[176:179], v[224:227], v[56:59]
	v_mfma_f32_16x16x32_bf16 v[44:47], v[154:157], v[232:235], v[44:47]
	v_mfma_f32_16x16x32_bf16 v[40:43], v[176:179], v[232:235], v[40:43]
	v_mfma_f32_16x16x32_bf16 v[28:31], v[154:157], v[240:243], v[28:31]
	v_mfma_f32_16x16x32_bf16 v[24:27], v[176:179], v[240:243], v[24:27]
	v_mfma_f32_16x16x32_bf16 v[12:15], v[154:157], v[248:251], v[12:15]
	v_mfma_f32_16x16x32_bf16 v[8:11], v[176:179], v[248:251], v[8:11]
	v_mfma_f32_16x16x32_bf16 v[52:55], v[204:207], v[220:223], v[52:55]
	v_mfma_f32_16x16x32_bf16 v[48:51], v[212:215], v[220:223], v[48:51]
	v_mfma_f32_16x16x32_bf16 v[36:39], v[204:207], v[228:231], v[36:39]
	v_mfma_f32_16x16x32_bf16 v[32:35], v[212:215], v[228:231], v[32:35]
	v_mfma_f32_16x16x32_bf16 v[20:23], v[204:207], v[236:239], v[20:23]
	v_mfma_f32_16x16x32_bf16 v[16:19], v[212:215], v[236:239], v[16:19]
	v_mfma_f32_16x16x32_bf16 v[4:7], v[204:207], v[244:247], v[4:7]
	v_mfma_f32_16x16x32_bf16 v[0:3], v[212:215], v[244:247], v[0:3]
	v_mfma_f32_16x16x32_bf16 v[52:55], v[208:211], v[224:227], v[52:55]
	v_mfma_f32_16x16x32_bf16 v[48:51], v[216:219], v[224:227], v[48:51]
	v_mfma_f32_16x16x32_bf16 v[36:39], v[208:211], v[232:235], v[36:39]
	v_mfma_f32_16x16x32_bf16 v[32:35], v[216:219], v[232:235], v[32:35]
	v_mfma_f32_16x16x32_bf16 v[20:23], v[208:211], v[240:243], v[20:23]
	v_mfma_f32_16x16x32_bf16 v[16:19], v[216:219], v[240:243], v[16:19]
	v_mfma_f32_16x16x32_bf16 v[4:7], v[208:211], v[248:251], v[4:7]
	v_mfma_f32_16x16x32_bf16 v[0:3], v[216:219], v[248:251], v[0:3]
	s_barrier
	s_cbranch_scc0 .LBB0_1207
	s_and_b64 vcc, exec, s[48:49]
	s_cbranch_vccz .LBB0_1210
	s_barrier

.LBB0_1305:
	v_add_u32_e32 v164, 0x10000, v143
	v_add_u32_e32 v180, 0x14000, v143
	ds_read_b128 v[138:141], v164
	ds_read_b128 v[156:159], v164 offset:1024
	ds_read_b128 v[160:163], v164 offset:2048
	ds_read_b128 v[164:167], v164 offset:3072
	ds_read_b128 v[168:171], v180
	ds_read_b128 v[172:175], v180 offset:1024
	ds_read_b128 v[176:179], v180 offset:2048
	ds_read_b128 v[204:207], v180 offset:3072
	ds_read_b128 v[208:211], v155
	ds_read_b128 v[212:215], v155 offset:1024
	ds_read_b128 v[216:219], v155 offset:2048
	ds_read_b128 v[220:223], v155 offset:3072
	ds_read_b128 v[224:227], v155 offset:4096
	ds_read_b128 v[228:231], v155 offset:5120
	ds_read_b128 v[232:235], v155 offset:6144
	ds_read_b128 v[236:239], v155 offset:7168
	s_add_u32 s4, s2, 0xfffc0080
	s_addc_u32 s5, s3, -1
	s_add_i32 s74, 0, 0x10000
	s_cmp_eq_u32 s73, 12
	s_cselect_b32 s61, s36, s5
	s_cselect_b32 s60, s51, s4
	s_cselect_b32 s35, s49, s72
	s_cselect_b32 s34, s70, s71
	s_add_i32 s75, 0, 0x14000
	s_add_i32 m0, s59, 0xc000
	v_lshl_add_u64 v[180:181], s[2:3], 0, v[134:135]
	global_load_lds_dwordx4 v[180:181], off
	s_add_i32 m0, s59, 0xe000
	v_lshl_add_u64 v[180:181], s[2:3], 0, v[136:137]
	global_load_lds_dwordx4 v[180:181], off
	s_waitcnt vmcnt(8)
	s_waitcnt lgkmcnt(0)
	s_barrier
	v_mfma_f32_16x16x32_bf16 v[124:127], v[138:141], v[208:211], v[124:127]
	v_mfma_f32_16x16x32_bf16 v[120:123], v[160:163], v[208:211], v[120:123]
	v_mfma_f32_16x16x32_bf16 v[108:111], v[138:141], v[216:219], v[108:111]
	v_mfma_f32_16x16x32_bf16 v[104:107], v[160:163], v[216:219], v[104:107]
	v_mfma_f32_16x16x32_bf16 v[92:95], v[138:141], v[224:227], v[92:95]
	v_mfma_f32_16x16x32_bf16 v[88:91], v[160:163], v[224:227], v[88:91]
	v_mfma_f32_16x16x32_bf16 v[76:79], v[138:141], v[232:235], v[76:79]
	v_mfma_f32_16x16x32_bf16 v[72:75], v[160:163], v[232:235], v[72:75]
	v_mfma_f32_16x16x32_bf16 v[124:127], v[156:159], v[212:215], v[124:127]
	v_mfma_f32_16x16x32_bf16 v[120:123], v[164:167], v[212:215], v[120:123]
	v_mfma_f32_16x16x32_bf16 v[108:111], v[156:159], v[220:223], v[108:111]
	v_mfma_f32_16x16x32_bf16 v[104:107], v[164:167], v[220:223], v[104:107]
	v_mfma_f32_16x16x32_bf16 v[92:95], v[156:159], v[228:231], v[92:95]
	v_mfma_f32_16x16x32_bf16 v[88:91], v[164:167], v[228:231], v[88:91]
	v_mfma_f32_16x16x32_bf16 v[76:79], v[156:159], v[236:239], v[76:79]
	v_mfma_f32_16x16x32_bf16 v[72:75], v[164:167], v[236:239], v[72:75]
	v_mfma_f32_16x16x32_bf16 v[116:119], v[168:171], v[208:211], v[116:119]
	v_mfma_f32_16x16x32_bf16 v[112:115], v[176:179], v[208:211], v[112:115]
	v_mfma_f32_16x16x32_bf16 v[100:103], v[168:171], v[216:219], v[100:103]
	v_mfma_f32_16x16x32_bf16 v[96:99], v[176:179], v[216:219], v[96:99]
	v_mfma_f32_16x16x32_bf16 v[84:87], v[168:171], v[224:227], v[84:87]
	v_mfma_f32_16x16x32_bf16 v[80:83], v[176:179], v[224:227], v[80:83]
	v_mfma_f32_16x16x32_bf16 v[68:71], v[168:171], v[232:235], v[68:71]
	v_mfma_f32_16x16x32_bf16 v[64:67], v[176:179], v[232:235], v[64:67]
	v_mfma_f32_16x16x32_bf16 v[116:119], v[172:175], v[212:215], v[116:119]
	v_mfma_f32_16x16x32_bf16 v[112:115], v[204:207], v[212:215], v[112:115]
	v_mfma_f32_16x16x32_bf16 v[100:103], v[172:175], v[220:223], v[100:103]
	v_mfma_f32_16x16x32_bf16 v[96:99], v[204:207], v[220:223], v[96:99]
	v_mfma_f32_16x16x32_bf16 v[84:87], v[172:175], v[228:231], v[84:87]
	v_mfma_f32_16x16x32_bf16 v[80:83], v[204:207], v[228:231], v[80:83]
	v_mfma_f32_16x16x32_bf16 v[68:71], v[172:175], v[236:239], v[68:71]
	v_mfma_f32_16x16x32_bf16 v[64:67], v[204:207], v[236:239], v[64:67]
	s_barrier
	s_add_i32 s4, s74, s1
	v_lshl_add_u64 v[180:181], s[34:35], 0, v[144:145]
	s_mov_b32 m0, s4
	ds_read_b128 v[208:211], v155 offset:16384
	ds_read_b128 v[212:215], v155 offset:17408
	ds_read_b128 v[216:219], v155 offset:18432
	ds_read_b128 v[220:223], v155 offset:19456
	ds_read_b128 v[224:227], v155 offset:20480
	ds_read_b128 v[228:231], v155 offset:21504
	ds_read_b128 v[232:235], v155 offset:22528
	ds_read_b128 v[236:239], v155 offset:23552
	global_load_lds_dwordx4 v[180:181], off
	s_add_i32 m0, s4, 0x2000
	s_add_u32 s4, s34, 0x40000
	v_lshl_add_u64 v[202:203], s[34:35], 0, v[128:129]
	s_addc_u32 s5, s35, 0
	s_add_i32 s74, s75, s1
	global_load_lds_dwordx4 v[202:203], off
	v_lshl_add_u64 v[240:241], s[4:5], 0, v[144:145]
	s_mov_b32 m0, s74
	v_lshl_add_u64 v[242:243], s[60:61], 0, v[130:131]
	global_load_lds_dwordx4 v[240:241], off
	s_add_i32 m0, s74, 0x2000
	v_lshl_add_u64 v[240:241], s[4:5], 0, v[128:129]
	global_load_lds_dwordx4 v[240:241], off
	s_mov_b32 m0, s59
	v_lshl_add_u64 v[240:241], s[60:61], 0, v[132:133]
	global_load_lds_dwordx4 v[240:241], off
	s_mov_b32 m0, s64
	s_nop 0
	global_load_lds_dwordx4 v[242:243], off
	s_waitcnt vmcnt(8)
	s_waitcnt lgkmcnt(0)
	s_barrier
	v_mfma_f32_16x16x32_bf16 v[60:63], v[138:141], v[208:211], v[60:63]
	v_mfma_f32_16x16x32_bf16 v[56:59], v[160:163], v[208:211], v[56:59]
	v_mfma_f32_16x16x32_bf16 v[44:47], v[138:141], v[216:219], v[44:47]
	v_mfma_f32_16x16x32_bf16 v[40:43], v[160:163], v[216:219], v[40:43]
	v_mfma_f32_16x16x32_bf16 v[28:31], v[138:141], v[224:227], v[28:31]
	v_mfma_f32_16x16x32_bf16 v[24:27], v[160:163], v[224:227], v[24:27]
	v_mfma_f32_16x16x32_bf16 v[12:15], v[138:141], v[232:235], v[12:15]
	v_mfma_f32_16x16x32_bf16 v[8:11], v[160:163], v[232:235], v[8:11]
	v_mfma_f32_16x16x32_bf16 v[60:63], v[156:159], v[212:215], v[60:63]
	v_mfma_f32_16x16x32_bf16 v[56:59], v[164:167], v[212:215], v[56:59]
	v_mfma_f32_16x16x32_bf16 v[44:47], v[156:159], v[220:223], v[44:47]
	v_mfma_f32_16x16x32_bf16 v[40:43], v[164:167], v[220:223], v[40:43]
	v_mfma_f32_16x16x32_bf16 v[28:31], v[156:159], v[228:231], v[28:31]
	v_mfma_f32_16x16x32_bf16 v[24:27], v[164:167], v[228:231], v[24:27]
	v_mfma_f32_16x16x32_bf16 v[12:15], v[156:159], v[236:239], v[12:15]
	v_mfma_f32_16x16x32_bf16 v[8:11], v[164:167], v[236:239], v[8:11]
	v_mfma_f32_16x16x32_bf16 v[52:55], v[168:171], v[208:211], v[52:55]
	v_mfma_f32_16x16x32_bf16 v[48:51], v[176:179], v[208:211], v[48:51]
	v_mfma_f32_16x16x32_bf16 v[36:39], v[168:171], v[216:219], v[36:39]
	v_mfma_f32_16x16x32_bf16 v[32:35], v[176:179], v[216:219], v[32:35]
	v_mfma_f32_16x16x32_bf16 v[20:23], v[168:171], v[224:227], v[20:23]
	v_mfma_f32_16x16x32_bf16 v[16:19], v[176:179], v[224:227], v[16:19]
	v_mfma_f32_16x16x32_bf16 v[4:7], v[168:171], v[232:235], v[4:7]
	v_mfma_f32_16x16x32_bf16 v[0:3], v[176:179], v[232:235], v[0:3]
	v_mfma_f32_16x16x32_bf16 v[52:55], v[172:175], v[212:215], v[52:55]
	v_mfma_f32_16x16x32_bf16 v[48:51], v[204:207], v[212:215], v[48:51]
	v_mfma_f32_16x16x32_bf16 v[36:39], v[172:175], v[220:223], v[36:39]
	v_mfma_f32_16x16x32_bf16 v[32:35], v[204:207], v[220:223], v[32:35]
	v_mfma_f32_16x16x32_bf16 v[20:23], v[172:175], v[228:231], v[20:23]
	v_mfma_f32_16x16x32_bf16 v[16:19], v[204:207], v[228:231], v[16:19]
	v_mfma_f32_16x16x32_bf16 v[4:7], v[172:175], v[236:239], v[4:7]
	v_mfma_f32_16x16x32_bf16 v[0:3], v[204:207], v[236:239], v[0:3]
	s_barrier
	v_add_u32_e32 v164, 0x18000, v143
	v_add_u32_e32 v204, 0x1c000, v143
	ds_read_b128 v[138:141], v164
	ds_read_b128 v[156:159], v164 offset:1024
	ds_read_b128 v[160:163], v164 offset:2048
	ds_read_b128 v[164:167], v164 offset:3072
	ds_read_b128 v[168:171], v204
	ds_read_b128 v[172:175], v204 offset:1024
	ds_read_b128 v[176:179], v204 offset:2048
	ds_read_b128 v[204:207], v204 offset:3072
	ds_read_b128 v[208:211], v155 offset:32768
	ds_read_b128 v[212:215], v155 offset:33792
	ds_read_b128 v[216:219], v155 offset:34816
	ds_read_b128 v[220:223], v155 offset:35840
	ds_read_b128 v[224:227], v155 offset:36864
	ds_read_b128 v[228:231], v155 offset:37888
	ds_read_b128 v[232:235], v155 offset:38912
	ds_read_b128 v[236:239], v155 offset:39936
	s_add_i32 s74, 0, 0x18000
	s_add_i32 s75, 0, 0x1c000
	s_add_u32 s4, s60, 0x40000
	s_addc_u32 s5, s61, 0
	s_mov_b32 m0, s65
	v_lshl_add_u64 v[244:245], s[4:5], 0, v[132:133]
	global_load_lds_dwordx4 v[244:245], off
	s_mov_b32 m0, s66
	v_lshl_add_u64 v[244:245], s[4:5], 0, v[130:131]
	global_load_lds_dwordx4 v[244:245], off
	s_waitcnt vmcnt(8)
	s_waitcnt lgkmcnt(0)
	s_barrier
	v_mfma_f32_16x16x32_bf16 v[124:127], v[138:141], v[208:211], v[124:127]
	v_mfma_f32_16x16x32_bf16 v[120:123], v[160:163], v[208:211], v[120:123]
	v_mfma_f32_16x16x32_bf16 v[108:111], v[138:141], v[216:219], v[108:111]
	v_mfma_f32_16x16x32_bf16 v[104:107], v[160:163], v[216:219], v[104:107]
	v_mfma_f32_16x16x32_bf16 v[92:95], v[138:141], v[224:227], v[92:95]
	v_mfma_f32_16x16x32_bf16 v[88:91], v[160:163], v[224:227], v[88:91]
	v_mfma_f32_16x16x32_bf16 v[76:79], v[138:141], v[232:235], v[76:79]
	v_mfma_f32_16x16x32_bf16 v[72:75], v[160:163], v[232:235], v[72:75]
	v_mfma_f32_16x16x32_bf16 v[124:127], v[156:159], v[212:215], v[124:127]
	v_mfma_f32_16x16x32_bf16 v[120:123], v[164:167], v[212:215], v[120:123]
	v_mfma_f32_16x16x32_bf16 v[108:111], v[156:159], v[220:223], v[108:111]
	v_mfma_f32_16x16x32_bf16 v[104:107], v[164:167], v[220:223], v[104:107]
	v_mfma_f32_16x16x32_bf16 v[92:95], v[156:159], v[228:231], v[92:95]
	v_mfma_f32_16x16x32_bf16 v[88:91], v[164:167], v[228:231], v[88:91]
	v_mfma_f32_16x16x32_bf16 v[76:79], v[156:159], v[236:239], v[76:79]
	v_mfma_f32_16x16x32_bf16 v[72:75], v[164:167], v[236:239], v[72:75]
	v_mfma_f32_16x16x32_bf16 v[116:119], v[168:171], v[208:211], v[116:119]
	v_mfma_f32_16x16x32_bf16 v[112:115], v[176:179], v[208:211], v[112:115]
	v_mfma_f32_16x16x32_bf16 v[100:103], v[168:171], v[216:219], v[100:103]
	v_mfma_f32_16x16x32_bf16 v[96:99], v[176:179], v[216:219], v[96:99]
	v_mfma_f32_16x16x32_bf16 v[84:87], v[168:171], v[224:227], v[84:87]
	v_mfma_f32_16x16x32_bf16 v[80:83], v[176:179], v[224:227], v[80:83]
	v_mfma_f32_16x16x32_bf16 v[68:71], v[168:171], v[232:235], v[68:71]
	v_mfma_f32_16x16x32_bf16 v[64:67], v[176:179], v[232:235], v[64:67]
	v_mfma_f32_16x16x32_bf16 v[116:119], v[172:175], v[212:215], v[116:119]
	v_mfma_f32_16x16x32_bf16 v[112:115], v[204:207], v[212:215], v[112:115]
	v_mfma_f32_16x16x32_bf16 v[100:103], v[172:175], v[220:223], v[100:103]
	v_mfma_f32_16x16x32_bf16 v[96:99], v[204:207], v[220:223], v[96:99]
	v_mfma_f32_16x16x32_bf16 v[84:87], v[172:175], v[228:231], v[84:87]
	v_mfma_f32_16x16x32_bf16 v[80:83], v[204:207], v[228:231], v[80:83]
	v_mfma_f32_16x16x32_bf16 v[68:71], v[172:175], v[236:239], v[68:71]
	v_mfma_f32_16x16x32_bf16 v[64:67], v[204:207], v[236:239], v[64:67]
	s_barrier
	s_add_i32 s4, s74, s1
	v_lshl_add_u64 v[180:181], v[180:181], 0, s[26:27]
	s_mov_b32 m0, s4
	ds_read_b128 v[208:211], v155 offset:49152
	ds_read_b128 v[212:215], v155 offset:50176
	ds_read_b128 v[216:219], v155 offset:51200
	ds_read_b128 v[220:223], v155 offset:52224
	ds_read_b128 v[224:227], v155 offset:53248
	ds_read_b128 v[228:231], v155 offset:54272
	ds_read_b128 v[232:235], v155 offset:55296
	ds_read_b128 v[236:239], v155 offset:56320
	global_load_lds_dwordx4 v[180:181], off
	s_add_i32 m0, s4, 0x2000
	s_add_u32 s4, s34, 0x40080
	v_lshl_add_u64 v[180:181], v[202:203], 0, s[26:27]
	s_addc_u32 s5, s35, 0
	s_add_i32 s34, s75, s1
	global_load_lds_dwordx4 v[180:181], off
	s_mov_b32 m0, s34
	v_lshl_add_u64 v[180:181], s[4:5], 0, v[144:145]
	global_load_lds_dwordx4 v[180:181], off
	s_add_i32 m0, s34, 0x2000
	v_lshl_add_u64 v[180:181], s[4:5], 0, v[128:129]
	global_load_lds_dwordx4 v[180:181], off
	s_mov_b32 m0, s67
	v_lshl_add_u64 v[180:181], v[240:241], 0, s[26:27]
	global_load_lds_dwordx4 v[180:181], off
	s_mov_b32 m0, s68
	v_lshl_add_u64 v[180:181], v[242:243], 0, s[26:27]
	global_load_lds_dwordx4 v[180:181], off
	s_add_i32 s73, s73, 2
	s_add_u32 s2, s2, 0x100
	s_addc_u32 s3, s3, 0
	s_add_u32 s71, s71, 0x100
	s_addc_u32 s72, s72, 0
	s_cmp_gt_u32 s73, 13
	s_waitcnt vmcnt(8)
	s_waitcnt lgkmcnt(0)
	s_barrier
	v_mfma_f32_16x16x32_bf16 v[60:63], v[138:141], v[208:211], v[60:63]
	v_mfma_f32_16x16x32_bf16 v[56:59], v[160:163], v[208:211], v[56:59]
	v_mfma_f32_16x16x32_bf16 v[44:47], v[138:141], v[216:219], v[44:47]
	v_mfma_f32_16x16x32_bf16 v[40:43], v[160:163], v[216:219], v[40:43]
	v_mfma_f32_16x16x32_bf16 v[28:31], v[138:141], v[224:227], v[28:31]
	v_mfma_f32_16x16x32_bf16 v[24:27], v[160:163], v[224:227], v[24:27]
	v_mfma_f32_16x16x32_bf16 v[12:15], v[138:141], v[232:235], v[12:15]
	v_mfma_f32_16x16x32_bf16 v[8:11], v[160:163], v[232:235], v[8:11]
	v_mfma_f32_16x16x32_bf16 v[60:63], v[156:159], v[212:215], v[60:63]
	v_mfma_f32_16x16x32_bf16 v[56:59], v[164:167], v[212:215], v[56:59]
	v_mfma_f32_16x16x32_bf16 v[44:47], v[156:159], v[220:223], v[44:47]
	v_mfma_f32_16x16x32_bf16 v[40:43], v[164:167], v[220:223], v[40:43]
	v_mfma_f32_16x16x32_bf16 v[28:31], v[156:159], v[228:231], v[28:31]
	v_mfma_f32_16x16x32_bf16 v[24:27], v[164:167], v[228:231], v[24:27]
	v_mfma_f32_16x16x32_bf16 v[12:15], v[156:159], v[236:239], v[12:15]
	v_mfma_f32_16x16x32_bf16 v[8:11], v[164:167], v[236:239], v[8:11]
	v_mfma_f32_16x16x32_bf16 v[52:55], v[168:171], v[208:211], v[52:55]
	v_mfma_f32_16x16x32_bf16 v[48:51], v[176:179], v[208:211], v[48:51]
	v_mfma_f32_16x16x32_bf16 v[36:39], v[168:171], v[216:219], v[36:39]
	v_mfma_f32_16x16x32_bf16 v[32:35], v[176:179], v[216:219], v[32:35]
	v_mfma_f32_16x16x32_bf16 v[20:23], v[168:171], v[224:227], v[20:23]
	v_mfma_f32_16x16x32_bf16 v[16:19], v[176:179], v[224:227], v[16:19]
	v_mfma_f32_16x16x32_bf16 v[4:7], v[168:171], v[232:235], v[4:7]
	v_mfma_f32_16x16x32_bf16 v[0:3], v[176:179], v[232:235], v[0:3]
	v_mfma_f32_16x16x32_bf16 v[52:55], v[172:175], v[212:215], v[52:55]
	v_mfma_f32_16x16x32_bf16 v[48:51], v[204:207], v[212:215], v[48:51]
	v_mfma_f32_16x16x32_bf16 v[36:39], v[172:175], v[220:223], v[36:39]
	v_mfma_f32_16x16x32_bf16 v[32:35], v[204:207], v[220:223], v[32:35]
	v_mfma_f32_16x16x32_bf16 v[20:23], v[172:175], v[228:231], v[20:23]
	v_mfma_f32_16x16x32_bf16 v[16:19], v[204:207], v[228:231], v[16:19]
	v_mfma_f32_16x16x32_bf16 v[4:7], v[172:175], v[236:239], v[4:7]
	v_mfma_f32_16x16x32_bf16 v[0:3], v[204:207], v[236:239], v[0:3]
	s_barrier
	s_cbranch_scc0 .LBB0_1305
	v_lshl_add_u32 v140, s58, 8, v142
	v_ashrrev_i32_e32 v141, 31, v140
	v_lshl_add_u64 v[156:157], v[140:141], 4, s[44:45]
	global_load_dwordx4 v[208:211], v[156:157], off
	global_load_dwordx4 v[212:215], v[156:157], off offset:256
	global_load_dwordx4 v[216:219], v[156:157], off offset:512
	global_load_dwordx4 v[220:223], v[156:157], off offset:768
	global_load_dwordx4 v[224:227], v[156:157], off offset:2048
	global_load_dwordx4 v[228:231], v[156:157], off offset:2304
	global_load_dwordx4 v[232:235], v[156:157], off offset:2560
	global_load_dwordx4 v[236:239], v[156:157], off offset:2816
	s_and_b64 vcc, exec, s[46:47]
	s_cbranch_vccz .LBB0_1308
	s_barrier

.LBB0_1399:
	v_add_u32_e32 v142, 0x10000, v160
	ds_read_b128 v[138:141], v142
	ds_read_b128 v[154:157], v142 offset:1024
	ds_read_b128 v[172:175], v142 offset:2048
	ds_read_b128 v[176:179], v142 offset:3072
	v_add_u32_e32 v142, 0x14000, v160
	ds_read_b128 v[204:207], v142
	ds_read_b128 v[208:211], v142 offset:1024
	ds_read_b128 v[212:215], v142 offset:2048
	ds_read_b128 v[216:219], v142 offset:3072
	ds_read_b128 v[220:223], v170
	ds_read_b128 v[224:227], v170 offset:1024
	ds_read_b128 v[228:231], v170 offset:2048
	ds_read_b128 v[232:235], v170 offset:3072
	ds_read_b128 v[236:239], v170 offset:4096
	ds_read_b128 v[240:243], v170 offset:5120
	ds_read_b128 v[244:247], v170 offset:6144
	ds_read_b128 v[248:251], v170 offset:7168
	s_add_u32 s58, s54, 0x100
	s_addc_u32 s59, s55, 0
	s_add_i32 s4, 0, 0x10000
	s_cmp_eq_u32 s29, 40
	s_cselect_b32 s61, s45, s59
	s_cselect_b32 s60, s44, s58
	s_cselect_b32 s35, s53, s28
	s_cselect_b32 s34, s52, s3
	s_add_i32 s47, 0, 0x14000
	s_add_i32 m0, s65, 0xc000
	v_lshl_add_u64 v[142:143], s[54:55], 0, v[134:135]
	global_load_lds_dwordx4 v[142:143], off
	s_add_i32 m0, s65, 0xe000
	v_lshl_add_u64 v[142:143], s[54:55], 0, v[136:137]
	global_load_lds_dwordx4 v[142:143], off
	s_waitcnt vmcnt(8)
	s_waitcnt lgkmcnt(0)
	s_barrier
	v_mfma_f32_16x16x32_bf16 v[124:127], v[138:141], v[220:223], v[124:127]
	v_mfma_f32_16x16x32_bf16 v[120:123], v[172:175], v[220:223], v[120:123]
	v_mfma_f32_16x16x32_bf16 v[108:111], v[138:141], v[228:231], v[108:111]
	v_mfma_f32_16x16x32_bf16 v[104:107], v[172:175], v[228:231], v[104:107]
	v_mfma_f32_16x16x32_bf16 v[92:95], v[138:141], v[236:239], v[92:95]
	v_mfma_f32_16x16x32_bf16 v[88:91], v[172:175], v[236:239], v[88:91]
	v_mfma_f32_16x16x32_bf16 v[76:79], v[138:141], v[244:247], v[76:79]
	v_mfma_f32_16x16x32_bf16 v[72:75], v[172:175], v[244:247], v[72:75]
	v_mfma_f32_16x16x32_bf16 v[124:127], v[154:157], v[224:227], v[124:127]
	v_mfma_f32_16x16x32_bf16 v[120:123], v[176:179], v[224:227], v[120:123]
	v_mfma_f32_16x16x32_bf16 v[108:111], v[154:157], v[232:235], v[108:111]
	v_mfma_f32_16x16x32_bf16 v[104:107], v[176:179], v[232:235], v[104:107]
	v_mfma_f32_16x16x32_bf16 v[92:95], v[154:157], v[240:243], v[92:95]
	v_mfma_f32_16x16x32_bf16 v[88:91], v[176:179], v[240:243], v[88:91]
	v_mfma_f32_16x16x32_bf16 v[76:79], v[154:157], v[248:251], v[76:79]
	v_mfma_f32_16x16x32_bf16 v[72:75], v[176:179], v[248:251], v[72:75]
	v_mfma_f32_16x16x32_bf16 v[116:119], v[204:207], v[220:223], v[116:119]
	v_mfma_f32_16x16x32_bf16 v[112:115], v[212:215], v[220:223], v[112:115]
	v_mfma_f32_16x16x32_bf16 v[100:103], v[204:207], v[228:231], v[100:103]
	v_mfma_f32_16x16x32_bf16 v[96:99], v[212:215], v[228:231], v[96:99]
	v_mfma_f32_16x16x32_bf16 v[84:87], v[204:207], v[236:239], v[84:87]
	v_mfma_f32_16x16x32_bf16 v[80:83], v[212:215], v[236:239], v[80:83]
	v_mfma_f32_16x16x32_bf16 v[68:71], v[204:207], v[244:247], v[68:71]
	v_mfma_f32_16x16x32_bf16 v[64:67], v[212:215], v[244:247], v[64:67]
	v_mfma_f32_16x16x32_bf16 v[116:119], v[208:211], v[224:227], v[116:119]
	v_mfma_f32_16x16x32_bf16 v[112:115], v[216:219], v[224:227], v[112:115]
	v_mfma_f32_16x16x32_bf16 v[100:103], v[208:211], v[232:235], v[100:103]
	v_mfma_f32_16x16x32_bf16 v[96:99], v[216:219], v[232:235], v[96:99]
	v_mfma_f32_16x16x32_bf16 v[84:87], v[208:211], v[240:243], v[84:87]
	v_mfma_f32_16x16x32_bf16 v[80:83], v[216:219], v[240:243], v[80:83]
	v_mfma_f32_16x16x32_bf16 v[68:71], v[208:211], v[248:251], v[68:71]
	v_mfma_f32_16x16x32_bf16 v[64:67], v[216:219], v[248:251], v[64:67]
	s_barrier
	s_add_i32 s4, s4, s33
	v_lshl_add_u64 v[142:143], s[34:35], 0, v[128:129]
	s_mov_b32 m0, s4
	ds_read_b128 v[220:223], v170 offset:16384
	ds_read_b128 v[224:227], v170 offset:17408
	ds_read_b128 v[228:231], v170 offset:18432
	ds_read_b128 v[232:235], v170 offset:19456
	ds_read_b128 v[236:239], v170 offset:20480
	ds_read_b128 v[240:243], v170 offset:21504
	ds_read_b128 v[244:247], v170 offset:22528
	ds_read_b128 v[248:251], v170 offset:23552
	global_load_lds_dwordx4 v[142:143], off
	s_add_i32 m0, s4, 0x2000
	s_add_u32 s4, s34, 0xb0000
	v_lshl_add_u64 v[158:159], s[34:35], 0, v[130:131]
	s_addc_u32 s5, s35, 0
	s_add_i32 s47, s47, s33
	global_load_lds_dwordx4 v[158:159], off
	v_lshl_add_u64 v[180:181], s[4:5], 0, v[128:129]
	s_mov_b32 m0, s47
	v_lshl_add_u64 v[202:203], s[60:61], 0, v[130:131]
	global_load_lds_dwordx4 v[180:181], off
	s_add_i32 m0, s47, 0x2000
	v_lshl_add_u64 v[180:181], s[4:5], 0, v[130:131]
	global_load_lds_dwordx4 v[180:181], off
	s_mov_b32 m0, s65
	v_lshl_add_u64 v[180:181], s[60:61], 0, v[128:129]
	global_load_lds_dwordx4 v[180:181], off
	s_mov_b32 m0, s66
	s_nop 0
	global_load_lds_dwordx4 v[202:203], off
	s_waitcnt vmcnt(8)
	s_waitcnt lgkmcnt(0)
	s_barrier
	v_mfma_f32_16x16x32_bf16 v[60:63], v[138:141], v[220:223], v[60:63]
	v_mfma_f32_16x16x32_bf16 v[56:59], v[172:175], v[220:223], v[56:59]
	v_mfma_f32_16x16x32_bf16 v[44:47], v[138:141], v[228:231], v[44:47]
	v_mfma_f32_16x16x32_bf16 v[40:43], v[172:175], v[228:231], v[40:43]
	v_mfma_f32_16x16x32_bf16 v[28:31], v[138:141], v[236:239], v[28:31]
	v_mfma_f32_16x16x32_bf16 v[24:27], v[172:175], v[236:239], v[24:27]
	v_mfma_f32_16x16x32_bf16 v[12:15], v[138:141], v[244:247], v[12:15]
	v_mfma_f32_16x16x32_bf16 v[8:11], v[172:175], v[244:247], v[8:11]
	v_mfma_f32_16x16x32_bf16 v[60:63], v[154:157], v[224:227], v[60:63]
	v_mfma_f32_16x16x32_bf16 v[56:59], v[176:179], v[224:227], v[56:59]
	v_mfma_f32_16x16x32_bf16 v[44:47], v[154:157], v[232:235], v[44:47]
	v_mfma_f32_16x16x32_bf16 v[40:43], v[176:179], v[232:235], v[40:43]
	v_mfma_f32_16x16x32_bf16 v[28:31], v[154:157], v[240:243], v[28:31]
	v_mfma_f32_16x16x32_bf16 v[24:27], v[176:179], v[240:243], v[24:27]
	v_mfma_f32_16x16x32_bf16 v[12:15], v[154:157], v[248:251], v[12:15]
	v_mfma_f32_16x16x32_bf16 v[8:11], v[176:179], v[248:251], v[8:11]
	v_mfma_f32_16x16x32_bf16 v[52:55], v[204:207], v[220:223], v[52:55]
	v_mfma_f32_16x16x32_bf16 v[48:51], v[212:215], v[220:223], v[48:51]
	v_mfma_f32_16x16x32_bf16 v[36:39], v[204:207], v[228:231], v[36:39]
	v_mfma_f32_16x16x32_bf16 v[32:35], v[212:215], v[228:231], v[32:35]
	v_mfma_f32_16x16x32_bf16 v[20:23], v[204:207], v[236:239], v[20:23]
	v_mfma_f32_16x16x32_bf16 v[16:19], v[212:215], v[236:239], v[16:19]
	v_mfma_f32_16x16x32_bf16 v[4:7], v[204:207], v[244:247], v[4:7]
	v_mfma_f32_16x16x32_bf16 v[0:3], v[212:215], v[244:247], v[0:3]
	v_mfma_f32_16x16x32_bf16 v[52:55], v[208:211], v[224:227], v[52:55]
	v_mfma_f32_16x16x32_bf16 v[48:51], v[216:219], v[224:227], v[48:51]
	v_mfma_f32_16x16x32_bf16 v[36:39], v[208:211], v[232:235], v[36:39]
	v_mfma_f32_16x16x32_bf16 v[32:35], v[216:219], v[232:235], v[32:35]
	v_mfma_f32_16x16x32_bf16 v[20:23], v[208:211], v[240:243], v[20:23]
	v_mfma_f32_16x16x32_bf16 v[16:19], v[216:219], v[240:243], v[16:19]
	v_mfma_f32_16x16x32_bf16 v[4:7], v[208:211], v[248:251], v[4:7]
	v_mfma_f32_16x16x32_bf16 v[0:3], v[216:219], v[248:251], v[0:3]
	s_barrier
	v_add_u32_e32 v144, 0x18000, v160
	ds_read_b128 v[138:141], v144
	ds_read_b128 v[154:157], v144 offset:1024
	ds_read_b128 v[172:175], v144 offset:2048
	ds_read_b128 v[176:179], v144 offset:3072
	v_add_u32_e32 v144, 0x1c000, v160
	ds_read_b128 v[204:207], v144
	ds_read_b128 v[208:211], v144 offset:1024
	ds_read_b128 v[212:215], v144 offset:2048
	ds_read_b128 v[216:219], v144 offset:3072
	ds_read_b128 v[220:223], v170 offset:32768
	ds_read_b128 v[224:227], v170 offset:33792
	ds_read_b128 v[228:231], v170 offset:34816
	ds_read_b128 v[232:235], v170 offset:35840
	ds_read_b128 v[236:239], v170 offset:36864
	ds_read_b128 v[240:243], v170 offset:37888
	ds_read_b128 v[244:247], v170 offset:38912
	ds_read_b128 v[248:251], v170 offset:39936
	s_add_i32 s47, 0, 0x18000
	s_add_i32 s54, 0, 0x1c000
	s_add_u32 s4, s60, 0xb0000
	s_addc_u32 s5, s61, 0
	s_mov_b32 m0, s67
	v_lshl_add_u64 v[252:253], s[4:5], 0, v[128:129]
	global_load_lds_dwordx4 v[252:253], off
	s_mov_b32 m0, s68
	v_lshl_add_u64 v[252:253], s[4:5], 0, v[130:131]
	global_load_lds_dwordx4 v[252:253], off
	s_waitcnt vmcnt(8)
	s_waitcnt lgkmcnt(0)
	s_barrier
	v_mfma_f32_16x16x32_bf16 v[124:127], v[138:141], v[220:223], v[124:127]
	v_mfma_f32_16x16x32_bf16 v[120:123], v[172:175], v[220:223], v[120:123]
	v_mfma_f32_16x16x32_bf16 v[108:111], v[138:141], v[228:231], v[108:111]
	v_mfma_f32_16x16x32_bf16 v[104:107], v[172:175], v[228:231], v[104:107]
	v_mfma_f32_16x16x32_bf16 v[92:95], v[138:141], v[236:239], v[92:95]
	v_mfma_f32_16x16x32_bf16 v[88:91], v[172:175], v[236:239], v[88:91]
	v_mfma_f32_16x16x32_bf16 v[76:79], v[138:141], v[244:247], v[76:79]
	v_mfma_f32_16x16x32_bf16 v[72:75], v[172:175], v[244:247], v[72:75]
	v_mfma_f32_16x16x32_bf16 v[124:127], v[154:157], v[224:227], v[124:127]
	v_mfma_f32_16x16x32_bf16 v[120:123], v[176:179], v[224:227], v[120:123]
	v_mfma_f32_16x16x32_bf16 v[108:111], v[154:157], v[232:235], v[108:111]
	v_mfma_f32_16x16x32_bf16 v[104:107], v[176:179], v[232:235], v[104:107]
	v_mfma_f32_16x16x32_bf16 v[92:95], v[154:157], v[240:243], v[92:95]
	v_mfma_f32_16x16x32_bf16 v[88:91], v[176:179], v[240:243], v[88:91]
	v_mfma_f32_16x16x32_bf16 v[76:79], v[154:157], v[248:251], v[76:79]
	v_mfma_f32_16x16x32_bf16 v[72:75], v[176:179], v[248:251], v[72:75]
	v_mfma_f32_16x16x32_bf16 v[116:119], v[204:207], v[220:223], v[116:119]
	v_mfma_f32_16x16x32_bf16 v[112:115], v[212:215], v[220:223], v[112:115]
	v_mfma_f32_16x16x32_bf16 v[100:103], v[204:207], v[228:231], v[100:103]
	v_mfma_f32_16x16x32_bf16 v[96:99], v[212:215], v[228:231], v[96:99]
	v_mfma_f32_16x16x32_bf16 v[84:87], v[204:207], v[236:239], v[84:87]
	v_mfma_f32_16x16x32_bf16 v[80:83], v[212:215], v[236:239], v[80:83]
	v_mfma_f32_16x16x32_bf16 v[68:71], v[204:207], v[244:247], v[68:71]
	v_mfma_f32_16x16x32_bf16 v[64:67], v[212:215], v[244:247], v[64:67]
	v_mfma_f32_16x16x32_bf16 v[116:119], v[208:211], v[224:227], v[116:119]
	v_mfma_f32_16x16x32_bf16 v[112:115], v[216:219], v[224:227], v[112:115]
	v_mfma_f32_16x16x32_bf16 v[100:103], v[208:211], v[232:235], v[100:103]
	v_mfma_f32_16x16x32_bf16 v[96:99], v[216:219], v[232:235], v[96:99]
	v_mfma_f32_16x16x32_bf16 v[84:87], v[208:211], v[240:243], v[84:87]
	v_mfma_f32_16x16x32_bf16 v[80:83], v[216:219], v[240:243], v[80:83]
	v_mfma_f32_16x16x32_bf16 v[68:71], v[208:211], v[248:251], v[68:71]
	v_mfma_f32_16x16x32_bf16 v[64:67], v[216:219], v[248:251], v[64:67]
	s_barrier
	s_add_i32 s4, s47, s33
	v_lshl_add_u64 v[142:143], v[142:143], 0, s[26:27]
	s_mov_b32 m0, s4
	ds_read_b128 v[220:223], v170 offset:49152
	ds_read_b128 v[224:227], v170 offset:50176
	ds_read_b128 v[228:231], v170 offset:51200
	ds_read_b128 v[232:235], v170 offset:52224
	ds_read_b128 v[236:239], v170 offset:53248
	ds_read_b128 v[240:243], v170 offset:54272
	ds_read_b128 v[244:247], v170 offset:55296
	ds_read_b128 v[248:251], v170 offset:56320
	global_load_lds_dwordx4 v[142:143], off
	s_add_i32 m0, s4, 0x2000
	s_add_u32 s4, s34, 0xb0080
	v_lshl_add_u64 v[142:143], v[158:159], 0, s[26:27]
	s_addc_u32 s5, s35, 0
	s_add_i32 s34, s54, s33
	global_load_lds_dwordx4 v[142:143], off
	s_mov_b32 m0, s34
	v_lshl_add_u64 v[142:143], s[4:5], 0, v[128:129]
	global_load_lds_dwordx4 v[142:143], off
	s_add_i32 m0, s34, 0x2000
	v_lshl_add_u64 v[142:143], s[4:5], 0, v[130:131]
	global_load_lds_dwordx4 v[142:143], off
	s_mov_b32 m0, s69
	v_lshl_add_u64 v[142:143], v[180:181], 0, s[26:27]
	global_load_lds_dwordx4 v[142:143], off
	s_mov_b32 m0, s70
	v_lshl_add_u64 v[142:143], v[202:203], 0, s[26:27]
	global_load_lds_dwordx4 v[142:143], off
	s_add_i32 s29, s29, 2
	s_add_u32 s3, s3, 0x100
	s_addc_u32 s28, s28, 0
	s_cmp_gt_u32 s29, 41
	s_mov_b64 s[54:55], s[58:59]
	s_waitcnt vmcnt(8)
	s_waitcnt lgkmcnt(0)
	s_barrier
	v_mfma_f32_16x16x32_bf16 v[60:63], v[138:141], v[220:223], v[60:63]
	v_mfma_f32_16x16x32_bf16 v[56:59], v[172:175], v[220:223], v[56:59]
	v_mfma_f32_16x16x32_bf16 v[44:47], v[138:141], v[228:231], v[44:47]
	v_mfma_f32_16x16x32_bf16 v[40:43], v[172:175], v[228:231], v[40:43]
	v_mfma_f32_16x16x32_bf16 v[28:31], v[138:141], v[236:239], v[28:31]
	v_mfma_f32_16x16x32_bf16 v[24:27], v[172:175], v[236:239], v[24:27]
	v_mfma_f32_16x16x32_bf16 v[12:15], v[138:141], v[244:247], v[12:15]
	v_mfma_f32_16x16x32_bf16 v[8:11], v[172:175], v[244:247], v[8:11]
	v_mfma_f32_16x16x32_bf16 v[60:63], v[154:157], v[224:227], v[60:63]
	v_mfma_f32_16x16x32_bf16 v[56:59], v[176:179], v[224:227], v[56:59]
	v_mfma_f32_16x16x32_bf16 v[44:47], v[154:157], v[232:235], v[44:47]
	v_mfma_f32_16x16x32_bf16 v[40:43], v[176:179], v[232:235], v[40:43]
	v_mfma_f32_16x16x32_bf16 v[28:31], v[154:157], v[240:243], v[28:31]
	v_mfma_f32_16x16x32_bf16 v[24:27], v[176:179], v[240:243], v[24:27]
	v_mfma_f32_16x16x32_bf16 v[12:15], v[154:157], v[248:251], v[12:15]
	v_mfma_f32_16x16x32_bf16 v[8:11], v[176:179], v[248:251], v[8:11]
	v_mfma_f32_16x16x32_bf16 v[52:55], v[204:207], v[220:223], v[52:55]
	v_mfma_f32_16x16x32_bf16 v[48:51], v[212:215], v[220:223], v[48:51]
	v_mfma_f32_16x16x32_bf16 v[36:39], v[204:207], v[228:231], v[36:39]
	v_mfma_f32_16x16x32_bf16 v[32:35], v[212:215], v[228:231], v[32:35]
	v_mfma_f32_16x16x32_bf16 v[20:23], v[204:207], v[236:239], v[20:23]
	v_mfma_f32_16x16x32_bf16 v[16:19], v[212:215], v[236:239], v[16:19]
	v_mfma_f32_16x16x32_bf16 v[4:7], v[204:207], v[244:247], v[4:7]
	v_mfma_f32_16x16x32_bf16 v[0:3], v[212:215], v[244:247], v[0:3]
	v_mfma_f32_16x16x32_bf16 v[52:55], v[208:211], v[224:227], v[52:55]
	v_mfma_f32_16x16x32_bf16 v[48:51], v[216:219], v[224:227], v[48:51]
	v_mfma_f32_16x16x32_bf16 v[36:39], v[208:211], v[232:235], v[36:39]
	v_mfma_f32_16x16x32_bf16 v[32:35], v[216:219], v[232:235], v[32:35]
	v_mfma_f32_16x16x32_bf16 v[20:23], v[208:211], v[240:243], v[20:23]
	v_mfma_f32_16x16x32_bf16 v[16:19], v[216:219], v[240:243], v[16:19]
	v_mfma_f32_16x16x32_bf16 v[4:7], v[208:211], v[248:251], v[4:7]
	v_mfma_f32_16x16x32_bf16 v[0:3], v[216:219], v[248:251], v[0:3]
	s_barrier
	s_cbranch_scc0 .LBB0_1399
	s_and_b64 vcc, exec, s[50:51]
	s_cbranch_vccz .LBB0_1402
	s_barrier
